# static s_setprio 1 for waves 4-7 set once at kernel entry; all per-phase setprio flips in the GEMM loops deleted
# speedup vs baseline: 1.0110x; 1.0110x over previous
; #define LAS __attribute__((address_space(3)))
; __global__ void __launch_bounds__(512, 2) fwd_megakernel(Args a) {
;     ...
;     XcdBarrier bar = xcd_barrier_post((unsigned*)(a.ws + WS_CTL), (volatile LAS unsigned*)(lds + LDS_CTL_OFF));
;     for (int step = a.ph_lo; step < a.ph_hi; ++step) {
;         unsigned long long lz = 0; asm volatile("" : "+s"(lz));
;         unsigned char* ws = a.ws + lz; float* ss = (float*)(ws + WS_SS); bf16* XB = (bf16*)(ws + WS_XB); bf16* W_RIN = (bf16*)(ws + WS_W_RIN);
;         int kind = K_PRO, layer = 0, mode = 0, ldo = 0, cset = 0; bool sync_after = true;
;         pg8::Gemm gm{nullptr, nullptr, 0, 0, 0};
;         bf16* obf = nullptr; const float* bias = nullptr; const float* rbase = a.out;
;         switch (step) {
;             case 0: kind = K_PRO; break;
;             case 1: kind = K_GSCALE; gm = pg8::Gemm{XB, W_RIN, SEQ, 6144, DM}; obf = (bf16*)(ws + WS_PROJ); ldo = 6144; sync_after = false; break;
;             case 2: kind = K_GSCALET; gm = pg8::Gemm{W_RIN + (size_t)6144 * DM, XB, 6144, SEQ, DM}; obf = (bf16*)(ws + WS_KVT); ldo = KVT_LD; break;
;             case 3: kind = K_RSCAN; break;
;             case 4: kind = K_ROUT; break;
;             case 5: kind = K_GRESIDK; gm = pg8::Gemm{(bf16*)(ws + WS_Y), (bf16*)(ws + WS_W_ROUT), SEQ, DM, 4096}; break;
;             case 6: kind = K_GCONV; gm = pg8::Gemm{XB - 2 * DM, (bf16*)(ws + WS_W_UP), 33 * 256, FF2, DM, 254}; layer = 0; cset = 1; break;
;             case 7: kind = K_NONE; break;
;             case 8: kind = K_GRESID; gm = pg8::Gemm{(bf16*)(ws + WS_HM), (bf16*)(ws + WS_W_DN), SEQ, DM, FF}; break;
;             case 9: kind = K_GSCALE; gm = pg8::Gemm{XB, (bf16*)(ws + WS_W_QKV), SEQ, AIN, DM}; obf = (bf16*)(ws + WS_QKV); ldo = AIN; mode = 2; bias = a.in[5]; cset = 2; break;
;             case 10: kind = K_ATTN; break;
;             case 11: kind = K_GRESID; gm = pg8::Gemm{(bf16*)(ws + WS_AO), (bf16*)(ws + WS_W_AOUT), SEQ, DM, DM}; break;
;             case 12: kind = K_GCONV; gm = pg8::Gemm{XB - 2 * DM, (bf16*)(ws + WS_W_UP) + (size_t)FF2 * DM, 33 * 256, FF2, DM, 254}; layer = 1; cset = 3; break;
;             case 13: kind = K_NONE; break;
;             case 14: kind = K_GRESIDF; gm = pg8::Gemm{(bf16*)(ws + WS_HM), (bf16*)(ws + WS_W_DN) + (size_t)DM * FF, SEQ, DM, FF}; sync_after = false; break;
;             default: kind = K_NONE; sync_after = false; break;
.LBB0_5:
	s_or_b64 exec, exec, s[4:5]
	s_cmp_ge_i32 s50, s51
	s_cbranch_scc1 .LBB0_677
	v_readlane_b32 s4, v250, 0
	s_lshl_b32 s6, s4, 3
	s_lshl_b32 s8, s90, 3
	s_cmpk_lt_i32 s4, 0x100
	s_cselect_b64 s[12:13], -1, 0
	v_writelane_b32 v250, s12, 5
	s_cmpk_lt_i32 s4, 0x200
	s_load_dwordx16 s[72:87], s[0:1], 0x0
	v_writelane_b32 v250, s13, 6
	s_cselect_b64 s[12:13], -1, 0
	v_writelane_b32 v250, s12, 7
	s_ashr_i32 s1, s4, 31
	s_mul_i32 s0, s91, s90
	v_writelane_b32 v250, s13, 8
	v_writelane_b32 v250, s1, 9
	s_lshr_b32 s1, s1, 29
	s_add_i32 s1, s4, s1
	s_ashr_i32 s5, s1, 3
	s_and_b32 s1, s1, -8
	v_writelane_b32 v250, s5, 10
	s_sub_i32 s1, s4, s1
	v_writelane_b32 v250, s1, 11
	s_ashr_i32 s1, s90, 31
	s_add_u32 s12, s70, 0x7e00000
	v_writelane_b32 v250, s1, 12
	s_addc_u32 s13, s71, 0
	v_writelane_b32 v250, s12, 13
	s_mul_i32 s0, s0, s10
	v_lshrrev_b32_e32 v1, 20, v0
	v_writelane_b32 v250, s13, 14
	s_add_u32 s12, s70, 0xbe80000
	s_addc_u32 s13, s71, 0
	v_writelane_b32 v250, s12, 15
	v_lshrrev_b32_e32 v0, 10, v0
	v_or_b32_e32 v0, v0, v1
	v_writelane_b32 v250, s13, 16
	s_add_u32 s12, s58, 0x5600000
	s_addc_u32 s13, s59, 0
	v_writelane_b32 v250, s12, 17
	s_mov_b32 s36, s50
	v_mbcnt_lo_u32_b32 v2, -1, 0
	v_writelane_b32 v250, s13, 18
	s_add_u32 s12, s56, 0x2000
	s_addc_u32 s13, s57, 0
	v_writelane_b32 v250, s12, 19
	v_mbcnt_hi_u32_b32 v213, -1, v2
	v_and_b32_e32 v2, 64, v213
	v_writelane_b32 v250, s13, 20
	s_add_u32 s12, s64, 0x2b00000
	s_addc_u32 s13, s65, 0
	s_add_u32 s52, s70, 0x5300000
	v_writelane_b32 v250, s12, 21
	s_addc_u32 s53, s71, 0
	v_mov_b32_e32 v210, 0x358637bd
	v_writelane_b32 v250, s13, 22
	s_add_u32 s12, s70, 0x4100000
	s_addc_u32 s13, s71, 0
	v_writelane_b32 v250, s12, 23
	v_mov_b32_e32 v211, 0x260
	v_mov_b32_e32 v182, 1
	v_writelane_b32 v250, s13, 24
	s_add_u32 s12, s70, 0x3100000
	s_addc_u32 s13, s71, 0
	v_writelane_b32 v250, s12, 25
	v_add_u32_e32 v214, 64, v2
	v_xor_b32_e32 v219, 16, v213
	v_writelane_b32 v250, s13, 26
	s_add_u32 s12, s70, 0x100000
	s_addc_u32 s13, s71, 0
	v_writelane_b32 v250, s12, 27
	v_xor_b32_e32 v220, 32, v213
	v_mov_b32_e32 v221, 0x42800000
	v_writelane_b32 v250, s13, 28
	s_waitcnt lgkmcnt(0)
	s_add_u32 s12, s74, 0x2000
	s_addc_u32 s13, s75, 0
	v_writelane_b32 v250, s12, 29
	s_lshl_b32 s1, s4, 9
	s_lshl_b32 s18, s90, 9
	v_writelane_b32 v250, s13, 30
	v_writelane_b32 v250, s1, 31
	s_cmp_lt_i32 s51, 17
	v_writelane_b32 v250, s0, 32
	s_cselect_b64 s[0:1], -1, 0
	v_writelane_b32 v250, s0, 33
	v_mov_b32_e32 v222, 0xff800000
	v_mov_b32_e32 v212, 0x800
	v_writelane_b32 v250, s1, 34
	s_add_u32 s0, s70, 0x80200
	s_addc_u32 s1, s71, 0
	v_writelane_b32 v250, s0, 35
	v_mov_b32_e32 v215, 0xa900000
	v_mov_b32_e32 v223, 0x4b00000
	v_writelane_b32 v250, s1, 36
	s_add_u32 s0, s70, 0x80400
	s_addc_u32 s1, s71, 0
	v_writelane_b32 v250, s0, 37
	v_mov_b32_e32 v218, 0x80
	s_movk_i32 s37, 0x2000
	v_writelane_b32 v250, s1, 38
	s_add_u32 s0, s70, 0x80500
	s_addc_u32 s1, s71, 0
	v_writelane_b32 v250, s0, 39
	s_mov_b64 s[24:25], 0x80
	s_mov_b32 s21, 0
	v_writelane_b32 v250, s1, 40
	s_add_u32 s0, s70, 0x80600
	s_addc_u32 s1, s71, 0
	v_writelane_b32 v250, s0, 41
	s_nop 1
	v_writelane_b32 v250, s1, 42
	s_add_u32 s0, s70, 0x80700
	s_addc_u32 s1, s71, 0
	v_writelane_b32 v250, s0, 43
	s_nop 1
	v_writelane_b32 v250, s1, 44
	s_add_u32 s0, s70, 0x80800
	s_addc_u32 s1, s71, 0
	v_writelane_b32 v250, s0, 45
	s_nop 1
	v_writelane_b32 v250, s1, 46
	s_add_u32 s0, s70, 0x80900
	s_addc_u32 s1, s71, 0
	v_writelane_b32 v250, s0, 47
	s_nop 1
	v_writelane_b32 v250, s1, 48
	s_add_u32 s0, s70, 0x80a00
	s_addc_u32 s1, s71, 0
	v_writelane_b32 v250, s0, 49
	s_nop 1
	v_writelane_b32 v250, s1, 50
	s_add_u32 s0, s70, 0x80b00
	s_addc_u32 s1, s71, 0
	v_writelane_b32 v250, s0, 51
	s_nop 1
	v_writelane_b32 v250, s1, 52
	s_add_u32 s0, s70, 0x80c00
	s_addc_u32 s1, s71, 0
	v_writelane_b32 v250, s0, 53
	s_nop 1
	v_writelane_b32 v250, s1, 54
	s_add_u32 s0, s70, 0x80d00
	s_addc_u32 s1, s71, 0
	v_writelane_b32 v250, s0, 55
	s_nop 1
	v_writelane_b32 v250, s1, 56
	s_add_u32 s0, s70, 0x80e00
	s_addc_u32 s1, s71, 0
	v_writelane_b32 v250, s0, 57
	s_nop 1
	v_writelane_b32 v250, s1, 58
	s_add_u32 s0, s70, 0x80f00
	s_addc_u32 s1, s71, 0
	v_writelane_b32 v250, s0, 59
	s_nop 1
	v_writelane_b32 v250, s1, 60
	s_add_u32 s0, s70, 0x81000
	s_addc_u32 s1, s71, 0
	v_writelane_b32 v250, s0, 61
	s_nop 1
	v_writelane_b32 v250, s1, 62
	s_add_u32 s0, s70, 0x81100
	s_addc_u32 s1, s71, 0
	v_writelane_b32 v250, s0, 63
	s_nop 1
	v_writelane_b32 v251, s1, 0
	s_add_u32 s0, s70, 0x81200
	s_addc_u32 s1, s71, 0
	v_writelane_b32 v251, s0, 1
	s_nop 1
	v_writelane_b32 v251, s1, 2
	s_add_u32 s0, s70, 0x81300
	s_addc_u32 s1, s71, 0
	v_writelane_b32 v251, s0, 3
	s_cmp_eq_u32 s9, 15
	s_nop 0
	v_writelane_b32 v251, s1, 4
	s_cselect_b64 s[0:1], -1, 0
	v_writelane_b32 v251, s0, 5
	s_cmp_eq_u32 s9, 14
	s_nop 0
	v_writelane_b32 v251, s1, 6
	s_cselect_b64 s[0:1], -1, 0
	v_writelane_b32 v251, s0, 7
	s_cmp_eq_u32 s9, 13
	s_nop 0
	v_writelane_b32 v251, s1, 8
	s_cselect_b64 s[0:1], -1, 0
	v_writelane_b32 v251, s0, 9
	s_cmp_eq_u32 s9, 12
	s_nop 0
	v_writelane_b32 v251, s1, 10
	s_cselect_b64 s[0:1], -1, 0
	v_writelane_b32 v251, s0, 11
	s_cmp_eq_u32 s9, 11
	s_nop 0
	v_writelane_b32 v251, s1, 12
; __device__ __forceinline__ void xcd_barrier_complete(unsigned* bar, unsigned x, unsigned& nloc, unsigned& nx) {
;     const unsigned G = gridDim.x * gridDim.y * gridDim.z;
;     unsigned sum, cnt, mine, sp = 0u;
;     for (;;) {
;         sum = 0u; cnt = 0u; mine = 0u;
; #pragma unroll
;         for (unsigned j = 0; j < 16; ++j) { const unsigned c = xb_ld(&bar[XB_XCNT(j)]); sum += c; cnt += (c > 0u) ? 1u : 0u; mine = (j == x) ? c : mine; }
;         if (sum == G) break;
;         __builtin_amdgcn_s_sleep(1);
;         if ((++sp & 255u) == 0u) { if (xb_ld(&bar[XB_TMO])) break; if (sp > XB_SPIN_CAP) { atomicAdd(&bar[XB_TMO], 1u); break; } }
;     }
;     nloc = mine > 0u ? mine : 1u; nx = cnt > 0u ? cnt : 1u;
; }
; __device__ __forceinline__ void xcd_barrier(const XcdBarrier& b) {
;     asm volatile("s_waitcnt vmcnt(0)" ::: "memory");
;     __syncthreads();
;     if (threadIdx.x == 0) {
;         unsigned* bar = b.bar;
;         __builtin_amdgcn_s_waitcnt(0);
;         unsigned nloc = b.st[0], nx = b.st[1];
;         if (nloc == 0u) { xcd_barrier_complete(bar, b.x, nloc, nx); b.st[0] = nloc; b.st[1] = nx; }
;         const unsigned old = xb_add(&bar[XB_XSUB(b.x)], 1u);
;         const unsigned gen = old / nloc;
;         if (old + 1u == (gen + 1u) * nloc) {
;             __builtin_amdgcn_fence(__ATOMIC_RELEASE, "agent");
;             asm volatile("s_waitcnt vmcnt(0)" ::: "memory");
;             const unsigned og = xb_add(&bar[XB_TOP], 1u);
;             const unsigned tg = og / nx;
;             if (og + 1u == (tg + 1u) * nx) xb_add(&bar[XB_TOPGEN], 1u);
;             else XB_SPIN(xb_ld(&bar[XB_TOPGEN]) == tg, bar);
;             __builtin_amdgcn_fence(__ATOMIC_ACQUIRE, "agent");
;             xb_add(&bar[XB_XGEN(b.x)], 1u);
;             asm volatile("s_waitcnt vmcnt(0)" ::: "memory");
;         } else {
;             XB_SPIN(xb_ld(&bar[XB_XGEN(b.x)]) == gen, bar);
;             __builtin_amdgcn_fence(__ATOMIC_ACQUIRE, "agent");
; __global__ void __launch_bounds__(512, 2) fwd_megakernel(Args a) {
;     ...
;     for (int step = a.ph_lo; step < a.ph_hi; ++step) {
;         unsigned long long lz = 0; asm volatile("" : "+s"(lz));
;         unsigned char* ws = a.ws + lz; float* ss = (float*)(ws + WS_SS); bf16* XB = (bf16*)(ws + WS_XB); bf16* W_RIN = (bf16*)(ws + WS_W_RIN);
;         int kind = K_PRO, layer = 0, mode = 0, ldo = 0, cset = 0; bool sync_after = true;
	s_cselect_b64 s[0:1], -1, 0
	v_writelane_b32 v251, s0, 13
	s_cmp_eq_u32 s9, 10
	s_nop 0
	v_writelane_b32 v251, s1, 14
	s_cselect_b64 s[0:1], -1, 0
	v_writelane_b32 v251, s0, 15
	s_cmp_eq_u32 s9, 9
	s_nop 0
	v_writelane_b32 v251, s1, 16
	s_cselect_b64 s[0:1], -1, 0
	v_writelane_b32 v251, s0, 17
	s_cmp_eq_u32 s9, 8
	s_nop 0
	v_writelane_b32 v251, s1, 18
	s_cselect_b64 s[0:1], -1, 0
	v_writelane_b32 v251, s0, 19
	s_cmp_eq_u32 s9, 7
	s_nop 0
	v_writelane_b32 v251, s1, 20
	s_cselect_b64 s[0:1], -1, 0
	v_writelane_b32 v251, s0, 21
	s_cmp_eq_u32 s9, 6
	s_nop 0
	v_writelane_b32 v251, s1, 22
	s_cselect_b64 s[0:1], -1, 0
	v_writelane_b32 v251, s0, 23
	s_cmp_eq_u32 s9, 5
	s_nop 0
	v_writelane_b32 v251, s1, 24
	s_cselect_b64 s[0:1], -1, 0
	v_writelane_b32 v251, s0, 25
	s_cmp_eq_u32 s9, 4
	s_nop 0
	v_writelane_b32 v251, s1, 26
	s_cselect_b64 s[0:1], -1, 0
	v_writelane_b32 v251, s0, 27
	s_cmp_eq_u32 s9, 3
	s_nop 0
	v_writelane_b32 v251, s1, 28
	s_cselect_b64 s[0:1], -1, 0
	v_writelane_b32 v251, s0, 29
	s_cmp_eq_u32 s9, 2
	s_nop 0
	v_writelane_b32 v251, s1, 30
	s_cselect_b64 s[0:1], -1, 0
	v_writelane_b32 v251, s0, 31
	s_cmp_eq_u32 s9, 1
	s_nop 0
	v_writelane_b32 v251, s1, 32
	s_cselect_b64 s[0:1], -1, 0
	v_writelane_b32 v251, s0, 33
	s_cmp_eq_u32 s9, 0
	s_nop 0
	v_writelane_b32 v251, s1, 34
	s_cselect_b64 s[0:1], -1, 0
	v_writelane_b32 v251, s0, 35
	s_nop 1
	v_writelane_b32 v251, s1, 36
	s_lshl_b32 s0, s9, 8
	s_add_u32 s0, s2, s0
	s_addc_u32 s1, s3, 0
	s_add_u32 s2, s0, 0x1400
	s_addc_u32 s3, s1, 0
	v_writelane_b32 v251, s2, 37
	s_add_u32 s0, s0, 0x2400
	s_addc_u32 s1, s1, 0
	v_writelane_b32 v251, s3, 38
	v_writelane_b32 v251, s0, 39
	s_nop 1
	v_writelane_b32 v251, s1, 40
	s_movk_i32 s0, 0x3ff
	v_and_or_b32 v0, v0, s0, v183
	s_add_u32 s0, s70, 0x83400
	s_addc_u32 s1, s71, 0
	v_writelane_b32 v251, s0, 41
	s_nop 1
	v_writelane_b32 v251, s1, 42
	s_add_u32 s0, s70, 0x83500
	s_addc_u32 s1, s71, 0
	v_writelane_b32 v251, s0, 43
	s_nop 1
	v_writelane_b32 v251, s1, 44
	s_abs_i32 s0, s90
	v_cvt_f32_u32_e32 v1, s0
	v_writelane_b32 v251, s0, 45
	s_sub_i32 s0, 0, s0
	v_rcp_iflag_f32_e32 v1, v1
	s_nop 0
	v_mul_f32_e32 v1, 0x4f7ffffe, v1
	v_cvt_u32_f32_e32 v1, v1
	s_nop 0
	v_readfirstlane_b32 s1, v1
	s_mul_i32 s0, s0, s1
	s_mul_hi_u32 s0, s1, s0
	s_add_i32 s0, s1, s0
	v_writelane_b32 v251, s0, 46
	s_add_u32 s0, s68, 0x1000
	s_addc_u32 s1, s69, 0
	v_writelane_b32 v251, s0, 47
	s_ashr_i32 s7, s6, 31
	s_ashr_i32 s9, s8, 31
	v_writelane_b32 v251, s1, 48
	v_writelane_b32 v251, s6, 49
	s_lshl_b64 s[0:1], s[8:9], 13
	s_add_u32 s2, s70, 0x11d00000
	v_writelane_b32 v251, s7, 50
	v_writelane_b32 v251, s2, 51
	s_addc_u32 s2, s71, 0
	v_writelane_b32 v251, s2, 52
	s_lshl_b32 s2, s4, 5
	v_writelane_b32 v251, s2, 53
	s_lshl_b32 s2, s90, 5
	v_writelane_b32 v251, s2, 54
	s_add_u32 s2, s70, 0x1b7c0000
	v_writelane_b32 v251, s2, 55
	s_addc_u32 s2, s71, 0
	v_writelane_b32 v251, s2, 56
	s_add_u32 s2, s70, 0xd400000
	s_addc_u32 s3, s71, 0
	s_ashr_i32 s19, s18, 31
	v_writelane_b32 v251, s2, 57
	s_lshl_b64 s[14:15], s[18:19], 4
	v_mov_b32_e32 v1, 0
	v_writelane_b32 v251, s3, 58
	s_add_u32 s2, s70, 0xf402000
	s_addc_u32 s3, s71, 0
	v_writelane_b32 v251, s2, 59
	v_mov_b32_e32 v4, v1
	v_mov_b32_e32 v5, v1
	v_writelane_b32 v251, s3, 60
	s_lshl_b64 s[2:3], s[8:9], 5
	v_writelane_b32 v251, s2, 61
	v_mov_b32_e32 v6, v1
	v_mov_b32_e32 v7, v1
	v_writelane_b32 v251, s3, 62
	s_add_u32 s2, s72, 0x1000
	v_writelane_b32 v252, s72, 0
	v_writelane_b32 v251, s2, 63
	s_addc_u32 s2, s73, 0
	v_writelane_b32 v252, s73, 1
	v_writelane_b32 v252, s74, 2
	v_writelane_b32 v252, s75, 3
	v_writelane_b32 v252, s76, 4
	v_writelane_b32 v252, s77, 5
	v_writelane_b32 v252, s78, 6
	v_writelane_b32 v252, s79, 7
	v_writelane_b32 v252, s80, 8
	v_writelane_b32 v252, s81, 9
	v_writelane_b32 v252, s82, 10
	v_writelane_b32 v252, s83, 11
	v_writelane_b32 v252, s84, 12
	v_writelane_b32 v252, s85, 13
	v_writelane_b32 v252, s86, 14
	v_writelane_b32 v252, s87, 15
	v_writelane_b32 v252, s2, 16
	s_add_u32 s2, s70, 0xd402800
	v_writelane_b32 v252, s2, 17
	s_addc_u32 s2, s71, 0
	v_writelane_b32 v252, s2, 18
	s_add_i32 s2, 0, 0x10c00
	v_writelane_b32 v252, s2, 19
	s_add_i32 s2, 0, 0x20000
	v_writelane_b32 v252, s2, 20
	s_add_i32 s2, 0, 0x22400
	v_writelane_b32 v252, s2, 21
	s_add_i32 s2, 0, 0x12400
	v_writelane_b32 v252, s2, 22
	s_add_i32 s2, 0, 0x22800
	v_writelane_b32 v252, s2, 23
	s_add_i32 s2, 0, 0x25fc0
	v_writelane_b32 v252, s2, 24
	s_add_i32 s2, 0, 0x25fc4
	v_writelane_b32 v252, s2, 25
	v_cmp_eq_u32_e64 s[2:3], 0, v0
	s_add_i32 s19, 0, 0x10000
	s_add_i32 s91, 0, 0x18000
	v_writelane_b32 v252, s2, 26
	s_nop 1
	v_writelane_b32 v252, s3, 27
	s_lshl_b64 s[2:3], s[8:9], 12
	v_writelane_b32 v252, s2, 28
	s_nop 1
	v_writelane_b32 v252, s3, 29
	v_writelane_b32 v252, s50, 30
	s_nop 1
	v_writelane_b32 v252, s51, 31
	v_writelane_b32 v252, s52, 32
	s_nop 1
	v_writelane_b32 v252, s53, 33
	v_writelane_b32 v252, s0, 34
	s_nop 1
	v_writelane_b32 v252, s1, 35
	v_readfirstlane_b32 s98, v183
	s_nop 3
	s_cmpk_lt_u32 s98, 0x100
	s_cbranch_scc1 .Lmy_prio
	s_setprio 1
.Lmy_prio:
	s_branch .LBB0_8
.LBB0_7:
	s_cmp_ge_i32 s9, s51
	s_mov_b32 s36, s9
	v_readlane_b32 s0, v252, 34
	v_readlane_b32 s1, v252, 35
	s_cbranch_scc1 .LBB0_677

; #define PG8_STAGE(bufoff, gbase, voff) do { _Pragma("unroll") for (int _i = 0; _i < 2; ++_i) \
;         __builtin_amdgcn_global_load_lds((const unsigned*)((const char*)(gbase) + (voff)[_i]), (PG8_LAS unsigned*)(lds + (bufoff) + ldsw + _i * 8192), 16, 0, 0); } while (0)
; #define PG8_LDA(dst, b, h) do { _Pragma("unroll") for (int m = 0; m < 4; ++m) _Pragma("unroll") for (int k = 0; k < 2; ++k) dst[m][k] = *(const PG8_LAS bf16x8*)(lds + PG8_SA(b, h) + aoff + m * 2048 + k * 1024); } while (0)
; #define PG8_LDB(dst, b, h) do { _Pragma("unroll") for (int n = 0; n < 2; ++n) _Pragma("unroll") for (int k = 0; k < 2; ++k) dst[n][k] = *(const PG8_LAS bf16x8*)(lds + PG8_SB(b, h) + boff + n * 2048 + k * 1024); } while (0)
; #define PG8_MMA(ai, bj, At, Bt) do { __builtin_amdgcn_s_setprio(1); _Pragma("unroll") for (int m = 0; m < 4; ++m) _Pragma("unroll") for (int n = 0; n < 2; ++n) _Pragma("unroll") for (int k = 0; k < 2; ++k) \
;         acc[ai][bj][m][n] = __builtin_amdgcn_mfma_f32_16x16x32_bf16(Bt[n][k], At[m][k], acc[ai][bj][m][n], 0, 0, 0); __builtin_amdgcn_s_setprio(0); } while (0)
; #define PG8_WAIT_V(n) asm volatile("s_waitcnt vmcnt(" #n ")" ::: "memory")
; #define PG8_WAIT_L(n) asm volatile("s_waitcnt lgkmcnt(" #n ")" ::: "memory")
; template <class Epi, class Sched, bool ALIGN_EPI = false, bool SP2 = false>
; __device__ __forceinline__ void gemm_phase(PG8_LAS unsigned char* lds, const Gemm g, const Sched& S, const Epi& E) {
;     ...
;             const bool last = (t == nt - 2);
;             const char* a1 = cA + (size_t)(t + 1) * kstep;
;             const char* a2 = last ? nA : cA + (size_t)(t + 2) * kstep; const char* b2 = last ? nB : cB + (size_t)(t + 2) * kstep;
;             const char* a3 = a2 + kstep; const char* b3 = b2 + kstep;
;             if (last && has_next) S.a_ready(nxt);
;             if constexpr (SP2) {
;             PG8_LDB(B0, 0, 0); PG8_LDB(B1, 0, 1); PG8_SCHED; PG8_LDA(At, 0, 0); PG8_STAGE(PG8_SA(1, 1), a1 + hstep, voffA);
;             PG8_WAIT_V(8); PG8_WAIT_L(0); PG8_BAR; PG8_MMA(0, 0, At, B0); PG8_MMA(0, 1, At, B1); PG8_BAR; PG8_SCHED;
;             PG8_LDA(At, 0, 1); PG8_STAGE(PG8_SB(0, 0), b2, voffB); PG8_STAGE(PG8_SB(0, 1), b2 + hstep, voffB); PG8_STAGE(PG8_SA(0, 0), a2, voffA);
;             PG8_WAIT_V(8); PG8_WAIT_L(0); PG8_BAR; PG8_MMA(1, 0, At, B0); PG8_MMA(1, 1, At, B1); PG8_BAR; PG8_SCHED;
.LBB0_202:
	s_add_i32 s78, s38, 2
	s_add_u32 s79, s22, 0x80
	s_addc_u32 s39, s23, 0
	s_cmp_eq_u32 s33, s38
	s_cselect_b32 s39, s7, s39
	s_cselect_b32 s38, s6, s79
	v_add_u32_e32 v0, s19, v150
	s_cselect_b32 s81, s17, s77
	s_cselect_b32 s80, s16, s76
	s_add_i32 s79, 0, 0x14000
	ds_read_b128 v[152:155], v0
	ds_read_b128 v[156:159], v0 offset:1024
	ds_read_b128 v[160:163], v0 offset:2048
	ds_read_b128 v[164:167], v0 offset:3072
	v_add_u32_e32 v0, s79, v150
	ds_read_b128 v[168:171], v0
	ds_read_b128 v[172:175], v0 offset:1024
	ds_read_b128 v[176:179], v0 offset:2048
	ds_read_b128 v[184:187], v0 offset:3072
	v_lshl_add_u64 v[2:3], s[22:23], 0, v[144:145]
	s_add_i32 m0, s42, 0xc000
	ds_read_b128 v[188:191], v151
	ds_read_b128 v[192:195], v151 offset:1024
	ds_read_b128 v[196:199], v151 offset:2048
	ds_read_b128 v[200:203], v151 offset:3072
	ds_read_b128 v[204:207], v151 offset:4096
	ds_read_b128 v[230:233], v151 offset:5120
	ds_read_b128 v[234:237], v151 offset:6144
	ds_read_b128 v[238:241], v151 offset:7168
	global_load_lds_dwordx4 v[2:3], off
	v_lshl_add_u64 v[2:3], s[22:23], 0, v[146:147]
	s_add_i32 m0, s42, 0xe000
	s_nop 0
	global_load_lds_dwordx4 v[2:3], off
	s_waitcnt vmcnt(8)
	s_waitcnt lgkmcnt(0)
	s_barrier
	s_waitcnt lgkmcnt(0)
	v_mfma_f32_16x16x32_bf16 v[132:135], v[152:155], v[188:191], v[132:135]
	v_mfma_f32_16x16x32_bf16 v[132:135], v[156:159], v[192:195], v[132:135]
	v_mfma_f32_16x16x32_bf16 v[116:119], v[152:155], v[196:199], v[116:119]
	v_mfma_f32_16x16x32_bf16 v[116:119], v[156:159], v[200:203], v[116:119]
	v_mfma_f32_16x16x32_bf16 v[100:103], v[152:155], v[204:207], v[100:103]
	v_mfma_f32_16x16x32_bf16 v[100:103], v[156:159], v[230:233], v[100:103]
	v_mfma_f32_16x16x32_bf16 v[84:87], v[152:155], v[234:237], v[84:87]
	v_mfma_f32_16x16x32_bf16 v[84:87], v[156:159], v[238:241], v[84:87]
	v_mfma_f32_16x16x32_bf16 v[80:83], v[160:163], v[234:237], v[80:83]
	v_mfma_f32_16x16x32_bf16 v[80:83], v[164:167], v[238:241], v[80:83]
	v_mfma_f32_16x16x32_bf16 v[96:99], v[160:163], v[204:207], v[96:99]
	v_mfma_f32_16x16x32_bf16 v[96:99], v[164:167], v[230:233], v[96:99]
	v_mfma_f32_16x16x32_bf16 v[112:115], v[160:163], v[196:199], v[112:115]
	v_mfma_f32_16x16x32_bf16 v[112:115], v[164:167], v[200:203], v[112:115]
	v_mfma_f32_16x16x32_bf16 v[128:131], v[160:163], v[188:191], v[128:131]
	v_mfma_f32_16x16x32_bf16 v[128:131], v[164:167], v[192:195], v[128:131]
	v_mfma_f32_16x16x32_bf16 v[124:127], v[168:171], v[188:191], v[124:127]
	v_mfma_f32_16x16x32_bf16 v[124:127], v[172:175], v[192:195], v[124:127]
	v_mfma_f32_16x16x32_bf16 v[108:111], v[168:171], v[196:199], v[108:111]
	v_mfma_f32_16x16x32_bf16 v[108:111], v[172:175], v[200:203], v[108:111]
	v_mfma_f32_16x16x32_bf16 v[92:95], v[168:171], v[204:207], v[92:95]
	v_mfma_f32_16x16x32_bf16 v[92:95], v[172:175], v[230:233], v[92:95]
	v_mfma_f32_16x16x32_bf16 v[76:79], v[168:171], v[234:237], v[76:79]
	v_mfma_f32_16x16x32_bf16 v[76:79], v[172:175], v[238:241], v[76:79]
	v_mfma_f32_16x16x32_bf16 v[72:75], v[176:179], v[234:237], v[72:75]
	v_mfma_f32_16x16x32_bf16 v[72:75], v[184:187], v[238:241], v[72:75]
	v_mfma_f32_16x16x32_bf16 v[88:91], v[176:179], v[204:207], v[88:91]
	v_mfma_f32_16x16x32_bf16 v[88:91], v[184:187], v[230:233], v[88:91]
	v_mfma_f32_16x16x32_bf16 v[104:107], v[176:179], v[196:199], v[104:107]
	v_mfma_f32_16x16x32_bf16 v[104:107], v[184:187], v[200:203], v[104:107]
	v_mfma_f32_16x16x32_bf16 v[120:123], v[176:179], v[188:191], v[120:123]
	v_mfma_f32_16x16x32_bf16 v[120:123], v[184:187], v[192:195], v[120:123]
	s_barrier
	s_add_i32 s82, s19, s20
	v_lshl_add_u64 v[2:3], s[80:81], 0, v[140:141]
	s_mov_b32 m0, s82
	ds_read_b128 v[188:191], v151 offset:16384
	ds_read_b128 v[192:195], v151 offset:17408
	ds_read_b128 v[196:199], v151 offset:18432
	ds_read_b128 v[200:203], v151 offset:19456
	ds_read_b128 v[204:207], v151 offset:20480
	ds_read_b128 v[230:233], v151 offset:21504
	ds_read_b128 v[234:237], v151 offset:22528
	ds_read_b128 v[238:241], v151 offset:23552
	global_load_lds_dwordx4 v[2:3], off
	s_add_i32 m0, s82, 0x2000
	v_lshl_add_u64 v[180:181], s[80:81], 0, v[136:137]
	s_add_u32 s80, s80, s48
	s_addc_u32 s81, s81, s49
	s_add_i32 s79, s79, s20
	global_load_lds_dwordx4 v[180:181], off
	v_lshl_add_u64 v[208:209], s[80:81], 0, v[140:141]
	s_mov_b32 m0, s79
	v_lshl_add_u64 v[216:217], s[80:81], 0, v[136:137]
	global_load_lds_dwordx4 v[208:209], off
	s_add_i32 m0, s79, 0x2000
	v_lshl_add_u64 v[224:225], s[38:39], 0, v[142:143]
	global_load_lds_dwordx4 v[216:217], off
	s_mov_b32 m0, s42
	v_lshl_add_u64 v[226:227], s[38:39], 0, v[138:139]
	global_load_lds_dwordx4 v[224:225], off
	s_mov_b32 m0, s45
	s_nop 0
	global_load_lds_dwordx4 v[226:227], off
	s_waitcnt vmcnt(8)
	s_waitcnt lgkmcnt(0)
	s_barrier
; #define PG8_STAGE(bufoff, gbase, voff) do { _Pragma("unroll") for (int _i = 0; _i < 2; ++_i) \
;         __builtin_amdgcn_global_load_lds((const unsigned*)((const char*)(gbase) + (voff)[_i]), (PG8_LAS unsigned*)(lds + (bufoff) + ldsw + _i * 8192), 16, 0, 0); } while (0)
; #define PG8_LDA(dst, b, h) do { _Pragma("unroll") for (int m = 0; m < 4; ++m) _Pragma("unroll") for (int k = 0; k < 2; ++k) dst[m][k] = *(const PG8_LAS bf16x8*)(lds + PG8_SA(b, h) + aoff + m * 2048 + k * 1024); } while (0)
; #define PG8_LDB(dst, b, h) do { _Pragma("unroll") for (int n = 0; n < 2; ++n) _Pragma("unroll") for (int k = 0; k < 2; ++k) dst[n][k] = *(const PG8_LAS bf16x8*)(lds + PG8_SB(b, h) + boff + n * 2048 + k * 1024); } while (0)
; #define PG8_MMA(ai, bj, At, Bt) do { __builtin_amdgcn_s_setprio(1); _Pragma("unroll") for (int m = 0; m < 4; ++m) _Pragma("unroll") for (int n = 0; n < 2; ++n) _Pragma("unroll") for (int k = 0; k < 2; ++k) \
;         acc[ai][bj][m][n] = __builtin_amdgcn_mfma_f32_16x16x32_bf16(Bt[n][k], At[m][k], acc[ai][bj][m][n], 0, 0, 0); __builtin_amdgcn_s_setprio(0); } while (0)
; #define PG8_WAIT_V(n) asm volatile("s_waitcnt vmcnt(" #n ")" ::: "memory")
; #define PG8_WAIT_L(n) asm volatile("s_waitcnt lgkmcnt(" #n ")" ::: "memory")
; #define PG8_BAR __builtin_amdgcn_s_barrier()
; #define PG8_SCHED __builtin_amdgcn_sched_barrier(0)
; template <class Epi, class Sched, bool ALIGN_EPI = false, bool SP2 = false>
; __device__ __forceinline__ void gemm_phase(PG8_LAS unsigned char* lds, const Gemm g, const Sched& S, const Epi& E) {
;     ...
;             PG8_WAIT_V(8); PG8_WAIT_L(0); PG8_BAR; PG8_MMA(1, 0, At, B0); PG8_MMA(1, 1, At, B1); PG8_BAR; PG8_SCHED;
;             PG8_LDB(B0, 1, 0); PG8_LDB(B1, 1, 1); PG8_SCHED; PG8_LDA(At, 1, 0); PG8_STAGE(PG8_SA(0, 1), a2 + hstep, voffA);
;             PG8_WAIT_V(8); PG8_WAIT_L(0); PG8_BAR; PG8_MMA(0, 0, At, B0); PG8_MMA(0, 1, At, B1); PG8_BAR; PG8_SCHED;
	s_waitcnt lgkmcnt(0)
	v_mfma_f32_16x16x32_bf16 v[68:71], v[152:155], v[188:191], v[68:71]
	v_mfma_f32_16x16x32_bf16 v[68:71], v[156:159], v[192:195], v[68:71]
	v_mfma_f32_16x16x32_bf16 v[52:55], v[152:155], v[196:199], v[52:55]
	v_mfma_f32_16x16x32_bf16 v[52:55], v[156:159], v[200:203], v[52:55]
	v_mfma_f32_16x16x32_bf16 v[36:39], v[152:155], v[204:207], v[36:39]
	v_mfma_f32_16x16x32_bf16 v[36:39], v[156:159], v[230:233], v[36:39]
	v_mfma_f32_16x16x32_bf16 v[20:23], v[152:155], v[234:237], v[20:23]
	v_mfma_f32_16x16x32_bf16 v[20:23], v[156:159], v[238:241], v[20:23]
	v_mfma_f32_16x16x32_bf16 v[16:19], v[160:163], v[234:237], v[16:19]
	v_mfma_f32_16x16x32_bf16 v[16:19], v[164:167], v[238:241], v[16:19]
	v_mfma_f32_16x16x32_bf16 v[32:35], v[160:163], v[204:207], v[32:35]
	v_mfma_f32_16x16x32_bf16 v[32:35], v[164:167], v[230:233], v[32:35]
	v_mfma_f32_16x16x32_bf16 v[48:51], v[160:163], v[196:199], v[48:51]
	v_mfma_f32_16x16x32_bf16 v[48:51], v[164:167], v[200:203], v[48:51]
	v_mfma_f32_16x16x32_bf16 v[64:67], v[160:163], v[188:191], v[64:67]
	v_mfma_f32_16x16x32_bf16 v[64:67], v[164:167], v[192:195], v[64:67]
	v_mfma_f32_16x16x32_bf16 v[60:63], v[168:171], v[188:191], v[60:63]
	v_mfma_f32_16x16x32_bf16 v[60:63], v[172:175], v[192:195], v[60:63]
	v_mfma_f32_16x16x32_bf16 v[44:47], v[168:171], v[196:199], v[44:47]
	v_mfma_f32_16x16x32_bf16 v[44:47], v[172:175], v[200:203], v[44:47]
	v_mfma_f32_16x16x32_bf16 v[28:31], v[168:171], v[204:207], v[28:31]
	v_mfma_f32_16x16x32_bf16 v[28:31], v[172:175], v[230:233], v[28:31]
	v_mfma_f32_16x16x32_bf16 v[12:15], v[168:171], v[234:237], v[12:15]
	v_mfma_f32_16x16x32_bf16 v[12:15], v[172:175], v[238:241], v[12:15]
	v_mfma_f32_16x16x32_bf16 v[8:11], v[176:179], v[234:237], v[8:11]
	v_mfma_f32_16x16x32_bf16 v[8:11], v[184:187], v[238:241], v[8:11]
	v_mfma_f32_16x16x32_bf16 v[24:27], v[176:179], v[204:207], v[24:27]
	v_mfma_f32_16x16x32_bf16 v[24:27], v[184:187], v[230:233], v[24:27]
	v_mfma_f32_16x16x32_bf16 v[40:43], v[176:179], v[196:199], v[40:43]
	v_mfma_f32_16x16x32_bf16 v[40:43], v[184:187], v[200:203], v[40:43]
	v_mfma_f32_16x16x32_bf16 v[56:59], v[176:179], v[188:191], v[56:59]
	v_mfma_f32_16x16x32_bf16 v[56:59], v[184:187], v[192:195], v[56:59]
	s_barrier
	v_add_u32_e32 v0, s91, v150
	s_add_i32 s79, 0, 0x1c000
	ds_read_b128 v[152:155], v0
	ds_read_b128 v[156:159], v0 offset:1024
	ds_read_b128 v[160:163], v0 offset:2048
	ds_read_b128 v[164:167], v0 offset:3072
	v_add_u32_e32 v0, s79, v150
	ds_read_b128 v[168:171], v0
	ds_read_b128 v[172:175], v0 offset:1024
	ds_read_b128 v[176:179], v0 offset:2048
	ds_read_b128 v[184:187], v0 offset:3072
	s_add_u32 s38, s38, s48
	s_addc_u32 s39, s39, s49
	s_mov_b32 m0, s46
	v_lshl_add_u64 v[228:229], s[38:39], 0, v[142:143]
	ds_read_b128 v[188:191], v151 offset:32768
	ds_read_b128 v[192:195], v151 offset:33792
	ds_read_b128 v[196:199], v151 offset:34816
	ds_read_b128 v[200:203], v151 offset:35840
	ds_read_b128 v[204:207], v151 offset:36864
	ds_read_b128 v[230:233], v151 offset:37888
	ds_read_b128 v[234:237], v151 offset:38912
	ds_read_b128 v[238:241], v151 offset:39936
	global_load_lds_dwordx4 v[228:229], off
	v_lshl_add_u64 v[228:229], s[38:39], 0, v[138:139]
	s_mov_b32 m0, s47
	s_nop 0
	global_load_lds_dwordx4 v[228:229], off
	s_waitcnt vmcnt(8)
	s_waitcnt lgkmcnt(0)
	s_barrier
	s_waitcnt lgkmcnt(0)
	v_mfma_f32_16x16x32_bf16 v[132:135], v[152:155], v[188:191], v[132:135]
	v_mfma_f32_16x16x32_bf16 v[132:135], v[156:159], v[192:195], v[132:135]
	v_mfma_f32_16x16x32_bf16 v[116:119], v[152:155], v[196:199], v[116:119]
	v_mfma_f32_16x16x32_bf16 v[116:119], v[156:159], v[200:203], v[116:119]
	v_mfma_f32_16x16x32_bf16 v[100:103], v[152:155], v[204:207], v[100:103]
	v_mfma_f32_16x16x32_bf16 v[100:103], v[156:159], v[230:233], v[100:103]
	v_mfma_f32_16x16x32_bf16 v[84:87], v[152:155], v[234:237], v[84:87]
	v_mfma_f32_16x16x32_bf16 v[84:87], v[156:159], v[238:241], v[84:87]
	v_mfma_f32_16x16x32_bf16 v[80:83], v[160:163], v[234:237], v[80:83]
	v_mfma_f32_16x16x32_bf16 v[80:83], v[164:167], v[238:241], v[80:83]
	v_mfma_f32_16x16x32_bf16 v[96:99], v[160:163], v[204:207], v[96:99]
	v_mfma_f32_16x16x32_bf16 v[96:99], v[164:167], v[230:233], v[96:99]
	v_mfma_f32_16x16x32_bf16 v[112:115], v[160:163], v[196:199], v[112:115]
	v_mfma_f32_16x16x32_bf16 v[112:115], v[164:167], v[200:203], v[112:115]
	v_mfma_f32_16x16x32_bf16 v[128:131], v[160:163], v[188:191], v[128:131]
	v_mfma_f32_16x16x32_bf16 v[128:131], v[164:167], v[192:195], v[128:131]
	v_mfma_f32_16x16x32_bf16 v[124:127], v[168:171], v[188:191], v[124:127]
	v_mfma_f32_16x16x32_bf16 v[124:127], v[172:175], v[192:195], v[124:127]
	v_mfma_f32_16x16x32_bf16 v[108:111], v[168:171], v[196:199], v[108:111]
	v_mfma_f32_16x16x32_bf16 v[108:111], v[172:175], v[200:203], v[108:111]
	v_mfma_f32_16x16x32_bf16 v[92:95], v[168:171], v[204:207], v[92:95]
	v_mfma_f32_16x16x32_bf16 v[92:95], v[172:175], v[230:233], v[92:95]
	v_mfma_f32_16x16x32_bf16 v[76:79], v[168:171], v[234:237], v[76:79]
	v_mfma_f32_16x16x32_bf16 v[76:79], v[172:175], v[238:241], v[76:79]
	v_mfma_f32_16x16x32_bf16 v[72:75], v[176:179], v[234:237], v[72:75]
	v_mfma_f32_16x16x32_bf16 v[72:75], v[184:187], v[238:241], v[72:75]
	v_mfma_f32_16x16x32_bf16 v[88:91], v[176:179], v[204:207], v[88:91]
	v_mfma_f32_16x16x32_bf16 v[88:91], v[184:187], v[230:233], v[88:91]
	v_mfma_f32_16x16x32_bf16 v[104:107], v[176:179], v[196:199], v[104:107]
	v_mfma_f32_16x16x32_bf16 v[104:107], v[184:187], v[200:203], v[104:107]
	v_mfma_f32_16x16x32_bf16 v[120:123], v[176:179], v[188:191], v[120:123]
	v_mfma_f32_16x16x32_bf16 v[120:123], v[184:187], v[192:195], v[120:123]
	s_barrier
; #define PG8_STAGE(bufoff, gbase, voff) do { _Pragma("unroll") for (int _i = 0; _i < 2; ++_i) \
;         __builtin_amdgcn_global_load_lds((const unsigned*)((const char*)(gbase) + (voff)[_i]), (PG8_LAS unsigned*)(lds + (bufoff) + ldsw + _i * 8192), 16, 0, 0); } while (0)
; #define PG8_LDA(dst, b, h) do { _Pragma("unroll") for (int m = 0; m < 4; ++m) _Pragma("unroll") for (int k = 0; k < 2; ++k) dst[m][k] = *(const PG8_LAS bf16x8*)(lds + PG8_SA(b, h) + aoff + m * 2048 + k * 1024); } while (0)
; #define PG8_MMA(ai, bj, At, Bt) do { __builtin_amdgcn_s_setprio(1); _Pragma("unroll") for (int m = 0; m < 4; ++m) _Pragma("unroll") for (int n = 0; n < 2; ++n) _Pragma("unroll") for (int k = 0; k < 2; ++k) \
;         acc[ai][bj][m][n] = __builtin_amdgcn_mfma_f32_16x16x32_bf16(Bt[n][k], At[m][k], acc[ai][bj][m][n], 0, 0, 0); __builtin_amdgcn_s_setprio(0); } while (0)
; #define PG8_WAIT_V(n) asm volatile("s_waitcnt vmcnt(" #n ")" ::: "memory")
; #define PG8_WAIT_L(n) asm volatile("s_waitcnt lgkmcnt(" #n ")" ::: "memory")
; #define PG8_BAR __builtin_amdgcn_s_barrier()
; #define PG8_SCHED __builtin_amdgcn_sched_barrier(0)
; template <class Epi, class Sched, bool ALIGN_EPI = false, bool SP2 = false>
; __device__ __forceinline__ void gemm_phase(PG8_LAS unsigned char* lds, const Gemm g, const Sched& S, const Epi& E) {
;     ...
;             PG8_LDA(At, 1, 1); PG8_STAGE(PG8_SB(1, 0), b3, voffB); PG8_STAGE(PG8_SB(1, 1), b3 + hstep, voffB); PG8_STAGE(PG8_SA(1, 0), a3, voffA);
;             PG8_WAIT_V(8); PG8_WAIT_L(0); PG8_BAR; PG8_MMA(1, 0, At, B0); PG8_MMA(1, 1, At, B1); PG8_BAR; PG8_SCHED;
	s_add_i32 s38, s91, s20
	v_lshl_add_u64 v[2:3], v[2:3], 0, s[24:25]
	s_mov_b32 m0, s38
	ds_read_b128 v[188:191], v151 offset:49152
	ds_read_b128 v[192:195], v151 offset:50176
	ds_read_b128 v[196:199], v151 offset:51200
	ds_read_b128 v[200:203], v151 offset:52224
	ds_read_b128 v[204:207], v151 offset:53248
	ds_read_b128 v[230:233], v151 offset:54272
	ds_read_b128 v[234:237], v151 offset:55296
	ds_read_b128 v[238:241], v151 offset:56320
	global_load_lds_dwordx4 v[2:3], off
	v_lshl_add_u64 v[2:3], v[180:181], 0, s[24:25]
	s_add_i32 m0, s38, 0x2000
	s_add_i32 s38, s79, s20
	global_load_lds_dwordx4 v[2:3], off
	v_lshl_add_u64 v[2:3], v[208:209], 0, s[24:25]
	s_mov_b32 m0, s38
	s_nop 0
	global_load_lds_dwordx4 v[2:3], off
	v_lshl_add_u64 v[2:3], v[216:217], 0, s[24:25]
	s_add_i32 m0, s38, 0x2000
	s_nop 0
	global_load_lds_dwordx4 v[2:3], off
	v_lshl_add_u64 v[2:3], v[224:225], 0, s[24:25]
	s_mov_b32 m0, s52
	s_nop 0
	global_load_lds_dwordx4 v[2:3], off
	v_lshl_add_u64 v[2:3], v[226:227], 0, s[24:25]
	s_mov_b32 m0, s53
	s_nop 0
	global_load_lds_dwordx4 v[2:3], off
	s_waitcnt vmcnt(8)
	s_waitcnt lgkmcnt(0)
	s_barrier
	s_waitcnt lgkmcnt(0)
	v_mfma_f32_16x16x32_bf16 v[68:71], v[152:155], v[188:191], v[68:71]
	v_mfma_f32_16x16x32_bf16 v[68:71], v[156:159], v[192:195], v[68:71]
	v_mfma_f32_16x16x32_bf16 v[52:55], v[152:155], v[196:199], v[52:55]
	v_mfma_f32_16x16x32_bf16 v[52:55], v[156:159], v[200:203], v[52:55]
	v_mfma_f32_16x16x32_bf16 v[36:39], v[152:155], v[204:207], v[36:39]
	v_mfma_f32_16x16x32_bf16 v[36:39], v[156:159], v[230:233], v[36:39]
	v_mfma_f32_16x16x32_bf16 v[20:23], v[152:155], v[234:237], v[20:23]
	v_mfma_f32_16x16x32_bf16 v[20:23], v[156:159], v[238:241], v[20:23]
	v_mfma_f32_16x16x32_bf16 v[16:19], v[160:163], v[234:237], v[16:19]
	v_mfma_f32_16x16x32_bf16 v[16:19], v[164:167], v[238:241], v[16:19]
	v_mfma_f32_16x16x32_bf16 v[32:35], v[160:163], v[204:207], v[32:35]
	v_mfma_f32_16x16x32_bf16 v[32:35], v[164:167], v[230:233], v[32:35]
	v_mfma_f32_16x16x32_bf16 v[48:51], v[160:163], v[196:199], v[48:51]
	v_mfma_f32_16x16x32_bf16 v[48:51], v[164:167], v[200:203], v[48:51]
	v_mfma_f32_16x16x32_bf16 v[64:67], v[160:163], v[188:191], v[64:67]
	v_mfma_f32_16x16x32_bf16 v[64:67], v[164:167], v[192:195], v[64:67]
	v_mfma_f32_16x16x32_bf16 v[60:63], v[168:171], v[188:191], v[60:63]
	v_mfma_f32_16x16x32_bf16 v[60:63], v[172:175], v[192:195], v[60:63]
	v_mfma_f32_16x16x32_bf16 v[44:47], v[168:171], v[196:199], v[44:47]
	v_mfma_f32_16x16x32_bf16 v[44:47], v[172:175], v[200:203], v[44:47]
	v_mfma_f32_16x16x32_bf16 v[28:31], v[168:171], v[204:207], v[28:31]
	v_mfma_f32_16x16x32_bf16 v[28:31], v[172:175], v[230:233], v[28:31]
	v_mfma_f32_16x16x32_bf16 v[12:15], v[168:171], v[234:237], v[12:15]
	v_mfma_f32_16x16x32_bf16 v[12:15], v[172:175], v[238:241], v[12:15]
	v_mfma_f32_16x16x32_bf16 v[8:11], v[176:179], v[234:237], v[8:11]
	v_mfma_f32_16x16x32_bf16 v[8:11], v[184:187], v[238:241], v[8:11]
	v_mfma_f32_16x16x32_bf16 v[24:27], v[176:179], v[204:207], v[24:27]
	v_mfma_f32_16x16x32_bf16 v[24:27], v[184:187], v[230:233], v[24:27]
	v_mfma_f32_16x16x32_bf16 v[40:43], v[176:179], v[196:199], v[40:43]
	v_mfma_f32_16x16x32_bf16 v[40:43], v[184:187], v[200:203], v[40:43]
	v_mfma_f32_16x16x32_bf16 v[56:59], v[176:179], v[188:191], v[56:59]
	v_mfma_f32_16x16x32_bf16 v[56:59], v[184:187], v[192:195], v[56:59]
	s_barrier
	s_add_u32 s22, s22, 0x100
	s_addc_u32 s23, s23, 0
	s_add_u32 s76, s76, 0x100
	s_addc_u32 s77, s77, 0
	s_cmp_ge_u32 s78, s9
	s_mov_b32 s38, s78
	s_cbranch_scc0 .LBB0_202

; #define PG8_STAGE(bufoff, gbase, voff) do { _Pragma("unroll") for (int _i = 0; _i < 2; ++_i) \
;         __builtin_amdgcn_global_load_lds((const unsigned*)((const char*)(gbase) + (voff)[_i]), (PG8_LAS unsigned*)(lds + (bufoff) + ldsw + _i * 8192), 16, 0, 0); } while (0)
; #define PG8_LDA(dst, b, h) do { _Pragma("unroll") for (int m = 0; m < 4; ++m) _Pragma("unroll") for (int k = 0; k < 2; ++k) dst[m][k] = *(const PG8_LAS bf16x8*)(lds + PG8_SA(b, h) + aoff + m * 2048 + k * 1024); } while (0)
; #define PG8_LDB(dst, b, h) do { _Pragma("unroll") for (int n = 0; n < 2; ++n) _Pragma("unroll") for (int k = 0; k < 2; ++k) dst[n][k] = *(const PG8_LAS bf16x8*)(lds + PG8_SB(b, h) + boff + n * 2048 + k * 1024); } while (0)
; #define PG8_MMA(ai, bj, At, Bt) do { __builtin_amdgcn_s_setprio(1); _Pragma("unroll") for (int m = 0; m < 4; ++m) _Pragma("unroll") for (int n = 0; n < 2; ++n) _Pragma("unroll") for (int k = 0; k < 2; ++k) \
;         acc[ai][bj][m][n] = __builtin_amdgcn_mfma_f32_16x16x32_bf16(Bt[n][k], At[m][k], acc[ai][bj][m][n], 0, 0, 0); __builtin_amdgcn_s_setprio(0); } while (0)
; #define PG8_WAIT_V(n) asm volatile("s_waitcnt vmcnt(" #n ")" ::: "memory")
; template <class Epi, class Sched, bool ALIGN_EPI = false, bool SP2 = false>
; __device__ __forceinline__ void gemm_phase(PG8_LAS unsigned char* lds, const Gemm g, const Sched& S, const Epi& E) {
;     ...
;             if constexpr (Epi::KHOOK) { if ((t & 7) == 0 && t != 0) E.khook(acc, t >> 3, wr, fr, lds); }
;             const bool last = (t == nt - 2);
;             const char* a1 = cA + (size_t)(t + 1) * kstep;
;             const char* a2 = last ? nA : cA + (size_t)(t + 2) * kstep; const char* b2 = last ? nB : cB + (size_t)(t + 2) * kstep;
;             const char* a3 = a2 + kstep; const char* b3 = b2 + kstep;
;             if (last && has_next) S.a_ready(nxt);
;             if constexpr (SP2) {
;             PG8_LDB(B0, 0, 0); PG8_LDB(B1, 0, 1); PG8_SCHED; PG8_LDA(At, 0, 0); PG8_STAGE(PG8_SA(1, 1), a1 + hstep, voffA);
;             PG8_WAIT_V(8); PG8_WAIT_L(0); PG8_BAR; PG8_MMA(0, 0, At, B0); PG8_MMA(0, 1, At, B1); PG8_BAR; PG8_SCHED;
;             PG8_LDA(At, 0, 1); PG8_STAGE(PG8_SB(0, 0), b2, voffB); PG8_STAGE(PG8_SB(0, 1), b2 + hstep, voffB); PG8_STAGE(PG8_SA(0, 0), a2, voffA);
;             PG8_WAIT_V(8); PG8_WAIT_L(0); PG8_BAR; PG8_MMA(1, 0, At, B0); PG8_MMA(1, 1, At, B1); PG8_BAR; PG8_SCHED;
.LBB0_245:
	v_readlane_b32 s22, v252, 59
	v_readlane_b32 s23, v252, 60
	s_andn2_b64 vcc, exec, s[22:23]
	s_cbranch_vccnz .LBB0_252
	s_add_u32 s40, s6, s48
	s_addc_u32 s41, s7, s49
	s_add_u32 s37, s6, 0x100
	s_addc_u32 s80, s7, 0
	s_and_b64 s[22:23], s[12:13], exec
	s_cselect_b32 s23, s5, s80
	s_cselect_b32 s22, s4, s37
	s_add_u32 s37, s10, 0x100
	s_addc_u32 s82, s11, 0
	s_and_b64 s[80:81], s[12:13], exec
	s_cselect_b32 s85, s17, s82
	s_cselect_b32 s84, s16, s37
	s_add_i32 s83, 0, 0x14000
	v_add_u32_e32 v150, s19, v147
	v_add_u32_e32 v151, s83, v147
	ds_read_b128 v[152:155], v150
	ds_read_b128 v[156:159], v150 offset:1024
	ds_read_b128 v[160:163], v150 offset:2048
	ds_read_b128 v[164:167], v150 offset:3072
	ds_read_b128 v[168:171], v151
	ds_read_b128 v[172:175], v151 offset:1024
	ds_read_b128 v[176:179], v151 offset:2048
	ds_read_b128 v[184:187], v151 offset:3072
	v_lshl_add_u64 v[180:181], s[40:41], 0, v[2:3]
	s_add_i32 s37, s47, 0xc000
	v_lshl_add_u64 v[180:181], v[180:181], 0, s[24:25]
	s_mov_b32 m0, s37
	ds_read_b128 v[188:191], v149
	ds_read_b128 v[192:195], v149 offset:1024
	ds_read_b128 v[196:199], v149 offset:2048
	ds_read_b128 v[200:203], v149 offset:3072
	ds_read_b128 v[204:207], v149 offset:4096
	ds_read_b128 v[230:233], v149 offset:5120
	ds_read_b128 v[234:237], v149 offset:6144
	ds_read_b128 v[238:241], v149 offset:7168
	global_load_lds_dwordx4 v[180:181], off
	v_lshl_add_u64 v[180:181], s[40:41], 0, v[136:137]
	s_add_i32 s80, s47, 0xe000
	v_lshl_add_u64 v[180:181], v[180:181], 0, s[24:25]
	s_mov_b32 m0, s80
	s_nop 0
	global_load_lds_dwordx4 v[180:181], off
	s_waitcnt vmcnt(8)
	s_waitcnt lgkmcnt(0)
	s_barrier
	s_waitcnt lgkmcnt(0)
	v_mfma_f32_16x16x32_bf16 v[132:135], v[152:155], v[188:191], v[132:135]
	v_mfma_f32_16x16x32_bf16 v[132:135], v[156:159], v[192:195], v[132:135]
	v_mfma_f32_16x16x32_bf16 v[116:119], v[152:155], v[196:199], v[116:119]
	v_mfma_f32_16x16x32_bf16 v[116:119], v[156:159], v[200:203], v[116:119]
	v_mfma_f32_16x16x32_bf16 v[100:103], v[152:155], v[204:207], v[100:103]
	v_mfma_f32_16x16x32_bf16 v[100:103], v[156:159], v[230:233], v[100:103]
	v_mfma_f32_16x16x32_bf16 v[84:87], v[152:155], v[234:237], v[84:87]
	v_mfma_f32_16x16x32_bf16 v[84:87], v[156:159], v[238:241], v[84:87]
	v_mfma_f32_16x16x32_bf16 v[80:83], v[160:163], v[234:237], v[80:83]
	v_mfma_f32_16x16x32_bf16 v[80:83], v[164:167], v[238:241], v[80:83]
	v_mfma_f32_16x16x32_bf16 v[96:99], v[160:163], v[204:207], v[96:99]
	v_mfma_f32_16x16x32_bf16 v[96:99], v[164:167], v[230:233], v[96:99]
	v_mfma_f32_16x16x32_bf16 v[112:115], v[160:163], v[196:199], v[112:115]
	v_mfma_f32_16x16x32_bf16 v[112:115], v[164:167], v[200:203], v[112:115]
	v_mfma_f32_16x16x32_bf16 v[128:131], v[160:163], v[188:191], v[128:131]
	v_mfma_f32_16x16x32_bf16 v[128:131], v[164:167], v[192:195], v[128:131]
	v_mfma_f32_16x16x32_bf16 v[124:127], v[168:171], v[188:191], v[124:127]
	v_mfma_f32_16x16x32_bf16 v[124:127], v[172:175], v[192:195], v[124:127]
	v_mfma_f32_16x16x32_bf16 v[108:111], v[168:171], v[196:199], v[108:111]
	v_mfma_f32_16x16x32_bf16 v[108:111], v[172:175], v[200:203], v[108:111]
	v_mfma_f32_16x16x32_bf16 v[92:95], v[168:171], v[204:207], v[92:95]
	v_mfma_f32_16x16x32_bf16 v[92:95], v[172:175], v[230:233], v[92:95]
	v_mfma_f32_16x16x32_bf16 v[76:79], v[168:171], v[234:237], v[76:79]
	v_mfma_f32_16x16x32_bf16 v[76:79], v[172:175], v[238:241], v[76:79]
	v_mfma_f32_16x16x32_bf16 v[72:75], v[176:179], v[234:237], v[72:75]
	v_mfma_f32_16x16x32_bf16 v[72:75], v[184:187], v[238:241], v[72:75]
	v_mfma_f32_16x16x32_bf16 v[88:91], v[176:179], v[204:207], v[88:91]
	v_mfma_f32_16x16x32_bf16 v[88:91], v[184:187], v[230:233], v[88:91]
	v_mfma_f32_16x16x32_bf16 v[104:107], v[176:179], v[196:199], v[104:107]
	v_mfma_f32_16x16x32_bf16 v[104:107], v[184:187], v[200:203], v[104:107]
	v_mfma_f32_16x16x32_bf16 v[120:123], v[176:179], v[188:191], v[120:123]
	v_mfma_f32_16x16x32_bf16 v[120:123], v[184:187], v[192:195], v[120:123]
	s_barrier
	s_add_i32 s81, s19, s46
	s_add_i32 s82, s81, 0x2000
	v_lshl_add_u64 v[208:209], s[84:85], 0, v[0:1]
	s_mov_b32 m0, s81
	s_add_u32 s40, s84, s48
	ds_read_b128 v[188:191], v149 offset:16384
	ds_read_b128 v[192:195], v149 offset:17408
	ds_read_b128 v[196:199], v149 offset:18432
	ds_read_b128 v[200:203], v149 offset:19456
	ds_read_b128 v[204:207], v149 offset:20480
	ds_read_b128 v[230:233], v149 offset:21504
	ds_read_b128 v[234:237], v149 offset:22528
	ds_read_b128 v[238:241], v149 offset:23552
	global_load_lds_dwordx4 v[208:209], off
	v_lshl_add_u64 v[216:217], s[84:85], 0, v[138:139]
	s_mov_b32 m0, s82
	s_addc_u32 s41, s85, s49
	s_add_i32 s83, s83, s46
	global_load_lds_dwordx4 v[216:217], off
	v_lshl_add_u64 v[224:225], s[40:41], 0, v[0:1]
	s_mov_b32 m0, s83
	s_add_i32 s84, s83, 0x2000
	global_load_lds_dwordx4 v[224:225], off
	v_lshl_add_u64 v[226:227], s[40:41], 0, v[138:139]
	s_mov_b32 m0, s84
	v_lshl_add_u64 v[228:229], s[22:23], 0, v[2:3]
	global_load_lds_dwordx4 v[226:227], off
	s_mov_b32 m0, s47
	v_lshl_add_u64 v[242:243], s[22:23], 0, v[136:137]
	global_load_lds_dwordx4 v[228:229], off
	s_mov_b32 m0, s52
	s_nop 0
	global_load_lds_dwordx4 v[242:243], off
	s_waitcnt vmcnt(8)
	s_waitcnt lgkmcnt(0)
	s_barrier
; #define PG8_STAGE(bufoff, gbase, voff) do { _Pragma("unroll") for (int _i = 0; _i < 2; ++_i) \
;         __builtin_amdgcn_global_load_lds((const unsigned*)((const char*)(gbase) + (voff)[_i]), (PG8_LAS unsigned*)(lds + (bufoff) + ldsw + _i * 8192), 16, 0, 0); } while (0)
; #define PG8_LDA(dst, b, h) do { _Pragma("unroll") for (int m = 0; m < 4; ++m) _Pragma("unroll") for (int k = 0; k < 2; ++k) dst[m][k] = *(const PG8_LAS bf16x8*)(lds + PG8_SA(b, h) + aoff + m * 2048 + k * 1024); } while (0)
; #define PG8_LDB(dst, b, h) do { _Pragma("unroll") for (int n = 0; n < 2; ++n) _Pragma("unroll") for (int k = 0; k < 2; ++k) dst[n][k] = *(const PG8_LAS bf16x8*)(lds + PG8_SB(b, h) + boff + n * 2048 + k * 1024); } while (0)
; #define PG8_MMA(ai, bj, At, Bt) do { __builtin_amdgcn_s_setprio(1); _Pragma("unroll") for (int m = 0; m < 4; ++m) _Pragma("unroll") for (int n = 0; n < 2; ++n) _Pragma("unroll") for (int k = 0; k < 2; ++k) \
;         acc[ai][bj][m][n] = __builtin_amdgcn_mfma_f32_16x16x32_bf16(Bt[n][k], At[m][k], acc[ai][bj][m][n], 0, 0, 0); __builtin_amdgcn_s_setprio(0); } while (0)
; #define PG8_WAIT_V(n) asm volatile("s_waitcnt vmcnt(" #n ")" ::: "memory")
; #define PG8_WAIT_L(n) asm volatile("s_waitcnt lgkmcnt(" #n ")" ::: "memory")
; #define PG8_BAR __builtin_amdgcn_s_barrier()
; #define PG8_SCHED __builtin_amdgcn_sched_barrier(0)
; template <class Epi, class Sched, bool ALIGN_EPI = false, bool SP2 = false>
; __device__ __forceinline__ void gemm_phase(PG8_LAS unsigned char* lds, const Gemm g, const Sched& S, const Epi& E) {
;     ...
;             PG8_WAIT_V(8); PG8_WAIT_L(0); PG8_BAR; PG8_MMA(1, 0, At, B0); PG8_MMA(1, 1, At, B1); PG8_BAR; PG8_SCHED;
;             PG8_LDB(B0, 1, 0); PG8_LDB(B1, 1, 1); PG8_SCHED; PG8_LDA(At, 1, 0); PG8_STAGE(PG8_SA(0, 1), a2 + hstep, voffA);
;             PG8_WAIT_V(8); PG8_WAIT_L(0); PG8_BAR; PG8_MMA(0, 0, At, B0); PG8_MMA(0, 1, At, B1); PG8_BAR; PG8_SCHED;
	s_waitcnt lgkmcnt(0)
	v_mfma_f32_16x16x32_bf16 v[68:71], v[152:155], v[188:191], v[68:71]
	v_mfma_f32_16x16x32_bf16 v[68:71], v[156:159], v[192:195], v[68:71]
	v_mfma_f32_16x16x32_bf16 v[52:55], v[152:155], v[196:199], v[52:55]
	v_mfma_f32_16x16x32_bf16 v[52:55], v[156:159], v[200:203], v[52:55]
	v_mfma_f32_16x16x32_bf16 v[36:39], v[152:155], v[204:207], v[36:39]
	v_mfma_f32_16x16x32_bf16 v[36:39], v[156:159], v[230:233], v[36:39]
	v_mfma_f32_16x16x32_bf16 v[20:23], v[152:155], v[234:237], v[20:23]
	v_mfma_f32_16x16x32_bf16 v[20:23], v[156:159], v[238:241], v[20:23]
	v_mfma_f32_16x16x32_bf16 v[16:19], v[160:163], v[234:237], v[16:19]
	v_mfma_f32_16x16x32_bf16 v[16:19], v[164:167], v[238:241], v[16:19]
	v_mfma_f32_16x16x32_bf16 v[32:35], v[160:163], v[204:207], v[32:35]
	v_mfma_f32_16x16x32_bf16 v[32:35], v[164:167], v[230:233], v[32:35]
	v_mfma_f32_16x16x32_bf16 v[48:51], v[160:163], v[196:199], v[48:51]
	v_mfma_f32_16x16x32_bf16 v[48:51], v[164:167], v[200:203], v[48:51]
	v_mfma_f32_16x16x32_bf16 v[64:67], v[160:163], v[188:191], v[64:67]
	v_mfma_f32_16x16x32_bf16 v[64:67], v[164:167], v[192:195], v[64:67]
	v_mfma_f32_16x16x32_bf16 v[60:63], v[168:171], v[188:191], v[60:63]
	v_mfma_f32_16x16x32_bf16 v[60:63], v[172:175], v[192:195], v[60:63]
	v_mfma_f32_16x16x32_bf16 v[44:47], v[168:171], v[196:199], v[44:47]
	v_mfma_f32_16x16x32_bf16 v[44:47], v[172:175], v[200:203], v[44:47]
	v_mfma_f32_16x16x32_bf16 v[28:31], v[168:171], v[204:207], v[28:31]
	v_mfma_f32_16x16x32_bf16 v[28:31], v[172:175], v[230:233], v[28:31]
	v_mfma_f32_16x16x32_bf16 v[12:15], v[168:171], v[234:237], v[12:15]
	v_mfma_f32_16x16x32_bf16 v[12:15], v[172:175], v[238:241], v[12:15]
	v_mfma_f32_16x16x32_bf16 v[8:11], v[176:179], v[234:237], v[8:11]
	v_mfma_f32_16x16x32_bf16 v[8:11], v[184:187], v[238:241], v[8:11]
	v_mfma_f32_16x16x32_bf16 v[24:27], v[176:179], v[204:207], v[24:27]
	v_mfma_f32_16x16x32_bf16 v[24:27], v[184:187], v[230:233], v[24:27]
	v_mfma_f32_16x16x32_bf16 v[40:43], v[176:179], v[196:199], v[40:43]
	v_mfma_f32_16x16x32_bf16 v[40:43], v[184:187], v[200:203], v[40:43]
	v_mfma_f32_16x16x32_bf16 v[56:59], v[176:179], v[188:191], v[56:59]
	v_mfma_f32_16x16x32_bf16 v[56:59], v[184:187], v[192:195], v[56:59]
	s_barrier
	s_add_i32 s87, 0, 0x1c000
	v_add_u32_e32 v152, s91, v147
	v_add_u32_e32 v153, s87, v147
	ds_read_b128 v[154:157], v152
	ds_read_b128 v[158:161], v152 offset:1024
	ds_read_b128 v[162:165], v152 offset:2048
	ds_read_b128 v[166:169], v152 offset:3072
	ds_read_b128 v[170:173], v153
	ds_read_b128 v[174:177], v153 offset:1024
	ds_read_b128 v[178:181], v153 offset:2048
	ds_read_b128 v[184:187], v153 offset:3072
	s_add_u32 s22, s22, s48
	s_addc_u32 s23, s23, s49
	s_mov_b32 m0, s53
	v_lshl_add_u64 v[244:245], s[22:23], 0, v[2:3]
	ds_read_b128 v[188:191], v149 offset:32768
	ds_read_b128 v[192:195], v149 offset:33792
	ds_read_b128 v[196:199], v149 offset:34816
	ds_read_b128 v[200:203], v149 offset:35840
	ds_read_b128 v[204:207], v149 offset:36864
	ds_read_b128 v[230:233], v149 offset:37888
	ds_read_b128 v[234:237], v149 offset:38912
	ds_read_b128 v[238:241], v149 offset:39936
	global_load_lds_dwordx4 v[244:245], off
	v_lshl_add_u64 v[244:245], s[22:23], 0, v[136:137]
	s_mov_b32 m0, s72
	s_nop 0
	global_load_lds_dwordx4 v[244:245], off
	s_waitcnt vmcnt(8)
	s_waitcnt lgkmcnt(0)
	s_barrier
	s_waitcnt lgkmcnt(0)
	v_mfma_f32_16x16x32_bf16 v[132:135], v[154:157], v[188:191], v[132:135]
	v_mfma_f32_16x16x32_bf16 v[132:135], v[158:161], v[192:195], v[132:135]
	v_mfma_f32_16x16x32_bf16 v[116:119], v[154:157], v[196:199], v[116:119]
	v_mfma_f32_16x16x32_bf16 v[116:119], v[158:161], v[200:203], v[116:119]
	v_mfma_f32_16x16x32_bf16 v[100:103], v[154:157], v[204:207], v[100:103]
	v_mfma_f32_16x16x32_bf16 v[100:103], v[158:161], v[230:233], v[100:103]
	v_mfma_f32_16x16x32_bf16 v[84:87], v[154:157], v[234:237], v[84:87]
	v_mfma_f32_16x16x32_bf16 v[84:87], v[158:161], v[238:241], v[84:87]
	v_mfma_f32_16x16x32_bf16 v[80:83], v[162:165], v[234:237], v[80:83]
	v_mfma_f32_16x16x32_bf16 v[80:83], v[166:169], v[238:241], v[80:83]
	v_mfma_f32_16x16x32_bf16 v[96:99], v[162:165], v[204:207], v[96:99]
	v_mfma_f32_16x16x32_bf16 v[96:99], v[166:169], v[230:233], v[96:99]
	v_mfma_f32_16x16x32_bf16 v[112:115], v[162:165], v[196:199], v[112:115]
	v_mfma_f32_16x16x32_bf16 v[112:115], v[166:169], v[200:203], v[112:115]
	v_mfma_f32_16x16x32_bf16 v[128:131], v[162:165], v[188:191], v[128:131]
	v_mfma_f32_16x16x32_bf16 v[128:131], v[166:169], v[192:195], v[128:131]
	v_mfma_f32_16x16x32_bf16 v[124:127], v[170:173], v[188:191], v[124:127]
	v_mfma_f32_16x16x32_bf16 v[124:127], v[174:177], v[192:195], v[124:127]
	v_mfma_f32_16x16x32_bf16 v[108:111], v[170:173], v[196:199], v[108:111]
	v_mfma_f32_16x16x32_bf16 v[108:111], v[174:177], v[200:203], v[108:111]
	v_mfma_f32_16x16x32_bf16 v[92:95], v[170:173], v[204:207], v[92:95]
	v_mfma_f32_16x16x32_bf16 v[92:95], v[174:177], v[230:233], v[92:95]
	v_mfma_f32_16x16x32_bf16 v[76:79], v[170:173], v[234:237], v[76:79]
	v_mfma_f32_16x16x32_bf16 v[76:79], v[174:177], v[238:241], v[76:79]
	v_mfma_f32_16x16x32_bf16 v[72:75], v[178:181], v[234:237], v[72:75]
	v_mfma_f32_16x16x32_bf16 v[72:75], v[184:187], v[238:241], v[72:75]
	v_mfma_f32_16x16x32_bf16 v[88:91], v[178:181], v[204:207], v[88:91]
	v_mfma_f32_16x16x32_bf16 v[88:91], v[184:187], v[230:233], v[88:91]
	v_mfma_f32_16x16x32_bf16 v[104:107], v[178:181], v[196:199], v[104:107]
	v_mfma_f32_16x16x32_bf16 v[104:107], v[184:187], v[200:203], v[104:107]
	v_mfma_f32_16x16x32_bf16 v[120:123], v[178:181], v[188:191], v[120:123]
	v_mfma_f32_16x16x32_bf16 v[120:123], v[184:187], v[192:195], v[120:123]
	s_barrier
; #define PG8_STAGE(bufoff, gbase, voff) do { _Pragma("unroll") for (int _i = 0; _i < 2; ++_i) \
;         __builtin_amdgcn_global_load_lds((const unsigned*)((const char*)(gbase) + (voff)[_i]), (PG8_LAS unsigned*)(lds + (bufoff) + ldsw + _i * 8192), 16, 0, 0); } while (0)
; #define PG8_LDA(dst, b, h) do { _Pragma("unroll") for (int m = 0; m < 4; ++m) _Pragma("unroll") for (int k = 0; k < 2; ++k) dst[m][k] = *(const PG8_LAS bf16x8*)(lds + PG8_SA(b, h) + aoff + m * 2048 + k * 1024); } while (0)
; #define PG8_MMA(ai, bj, At, Bt) do { __builtin_amdgcn_s_setprio(1); _Pragma("unroll") for (int m = 0; m < 4; ++m) _Pragma("unroll") for (int n = 0; n < 2; ++n) _Pragma("unroll") for (int k = 0; k < 2; ++k) \
;         acc[ai][bj][m][n] = __builtin_amdgcn_mfma_f32_16x16x32_bf16(Bt[n][k], At[m][k], acc[ai][bj][m][n], 0, 0, 0); __builtin_amdgcn_s_setprio(0); } while (0)
; #define PG8_WAIT_V(n) asm volatile("s_waitcnt vmcnt(" #n ")" ::: "memory")
; #define PG8_WAIT_L(n) asm volatile("s_waitcnt lgkmcnt(" #n ")" ::: "memory")
; #define PG8_BAR __builtin_amdgcn_s_barrier()
; #define PG8_SCHED __builtin_amdgcn_sched_barrier(0)
; template <class Epi, class Sched, bool ALIGN_EPI = false, bool SP2 = false>
; __device__ __forceinline__ void gemm_phase(PG8_LAS unsigned char* lds, const Gemm g, const Sched& S, const Epi& E) {
;     ...
;             PG8_LDA(At, 1, 1); PG8_STAGE(PG8_SB(1, 0), b3, voffB); PG8_STAGE(PG8_SB(1, 1), b3 + hstep, voffB); PG8_STAGE(PG8_SA(1, 0), a3, voffA);
;             PG8_WAIT_V(8); PG8_WAIT_L(0); PG8_BAR; PG8_MMA(1, 0, At, B0); PG8_MMA(1, 1, At, B1); PG8_BAR; PG8_SCHED;
	s_add_i32 s85, s91, s46
	v_lshl_add_u64 v[208:209], v[208:209], 0, s[24:25]
	s_mov_b32 m0, s85
	s_add_i32 s86, s85, 0x2000
	ds_read_b128 v[188:191], v149 offset:49152
	ds_read_b128 v[192:195], v149 offset:50176
	ds_read_b128 v[196:199], v149 offset:51200
	ds_read_b128 v[200:203], v149 offset:52224
	ds_read_b128 v[204:207], v149 offset:53248
	ds_read_b128 v[230:233], v149 offset:54272
	ds_read_b128 v[234:237], v149 offset:55296
	ds_read_b128 v[238:241], v149 offset:56320
	global_load_lds_dwordx4 v[208:209], off
	v_lshl_add_u64 v[208:209], v[216:217], 0, s[24:25]
	s_mov_b32 m0, s86
	s_add_i32 s87, s87, s46
	global_load_lds_dwordx4 v[208:209], off
	v_lshl_add_u64 v[208:209], v[224:225], 0, s[24:25]
	s_mov_b32 m0, s87
	s_add_i32 s88, s87, 0x2000
	global_load_lds_dwordx4 v[208:209], off
	v_lshl_add_u64 v[208:209], v[226:227], 0, s[24:25]
	s_mov_b32 m0, s88
	s_nop 0
	global_load_lds_dwordx4 v[208:209], off
	v_lshl_add_u64 v[208:209], v[228:229], 0, s[24:25]
	s_mov_b32 m0, s75
	s_nop 0
	global_load_lds_dwordx4 v[208:209], off
	v_lshl_add_u64 v[208:209], v[242:243], 0, s[24:25]
	s_mov_b32 m0, s76
	s_nop 0
	global_load_lds_dwordx4 v[208:209], off
	s_waitcnt vmcnt(8)
	s_waitcnt lgkmcnt(0)
	s_barrier
	s_waitcnt lgkmcnt(0)
	v_mfma_f32_16x16x32_bf16 v[68:71], v[154:157], v[188:191], v[68:71]
	v_mfma_f32_16x16x32_bf16 v[68:71], v[158:161], v[192:195], v[68:71]
	v_mfma_f32_16x16x32_bf16 v[52:55], v[154:157], v[196:199], v[52:55]
	v_mfma_f32_16x16x32_bf16 v[52:55], v[158:161], v[200:203], v[52:55]
	v_mfma_f32_16x16x32_bf16 v[36:39], v[154:157], v[204:207], v[36:39]
	v_mfma_f32_16x16x32_bf16 v[36:39], v[158:161], v[230:233], v[36:39]
	v_mfma_f32_16x16x32_bf16 v[20:23], v[154:157], v[234:237], v[20:23]
	v_mfma_f32_16x16x32_bf16 v[20:23], v[158:161], v[238:241], v[20:23]
	v_mfma_f32_16x16x32_bf16 v[16:19], v[162:165], v[234:237], v[16:19]
	v_mfma_f32_16x16x32_bf16 v[16:19], v[166:169], v[238:241], v[16:19]
	v_mfma_f32_16x16x32_bf16 v[32:35], v[162:165], v[204:207], v[32:35]
	v_mfma_f32_16x16x32_bf16 v[32:35], v[166:169], v[230:233], v[32:35]
	v_mfma_f32_16x16x32_bf16 v[48:51], v[162:165], v[196:199], v[48:51]
	v_mfma_f32_16x16x32_bf16 v[48:51], v[166:169], v[200:203], v[48:51]
	v_mfma_f32_16x16x32_bf16 v[64:67], v[162:165], v[188:191], v[64:67]
	v_mfma_f32_16x16x32_bf16 v[64:67], v[166:169], v[192:195], v[64:67]
	v_mfma_f32_16x16x32_bf16 v[60:63], v[170:173], v[188:191], v[60:63]
	v_mfma_f32_16x16x32_bf16 v[60:63], v[174:177], v[192:195], v[60:63]
	v_mfma_f32_16x16x32_bf16 v[44:47], v[170:173], v[196:199], v[44:47]
	v_mfma_f32_16x16x32_bf16 v[44:47], v[174:177], v[200:203], v[44:47]
	v_mfma_f32_16x16x32_bf16 v[28:31], v[170:173], v[204:207], v[28:31]
	v_mfma_f32_16x16x32_bf16 v[28:31], v[174:177], v[230:233], v[28:31]
	v_mfma_f32_16x16x32_bf16 v[12:15], v[170:173], v[234:237], v[12:15]
	v_mfma_f32_16x16x32_bf16 v[12:15], v[174:177], v[238:241], v[12:15]
	v_mfma_f32_16x16x32_bf16 v[8:11], v[178:181], v[234:237], v[8:11]
	v_mfma_f32_16x16x32_bf16 v[8:11], v[184:187], v[238:241], v[8:11]
	v_mfma_f32_16x16x32_bf16 v[24:27], v[178:181], v[204:207], v[24:27]
	v_mfma_f32_16x16x32_bf16 v[24:27], v[184:187], v[230:233], v[24:27]
	v_mfma_f32_16x16x32_bf16 v[40:43], v[178:181], v[196:199], v[40:43]
	v_mfma_f32_16x16x32_bf16 v[40:43], v[184:187], v[200:203], v[40:43]
	v_mfma_f32_16x16x32_bf16 v[56:59], v[178:181], v[188:191], v[56:59]
	v_mfma_f32_16x16x32_bf16 v[56:59], v[184:187], v[192:195], v[56:59]
	s_barrier
	v_readlane_b32 s22, v252, 42
	v_readlane_b32 s23, v252, 43
	s_andn2_b64 vcc, exec, s[22:23]
	s_cbranch_vccnz .LBB0_251
	s_add_u32 s22, s6, 0x180
	s_addc_u32 s23, s7, 0
	s_add_u32 s89, s10, 0x200
	s_addc_u32 s92, s11, 0
	s_mov_b32 s93, 4
	v_mov_b32_e32 v154, v148
	s_add_i32 s40, s93, -2
	s_and_b32 s40, s40, 6
	s_cmp_lg_u32 s40, 0
	s_cbranch_scc1 .LBB0_250
	s_branch .LBB0_249

; #define PG8_STAGE(bufoff, gbase, voff) do { _Pragma("unroll") for (int _i = 0; _i < 2; ++_i) \
;         __builtin_amdgcn_global_load_lds((const unsigned*)((const char*)(gbase) + (voff)[_i]), (PG8_LAS unsigned*)(lds + (bufoff) + ldsw + _i * 8192), 16, 0, 0); } while (0)
; #define PG8_LDA(dst, b, h) do { _Pragma("unroll") for (int m = 0; m < 4; ++m) _Pragma("unroll") for (int k = 0; k < 2; ++k) dst[m][k] = *(const PG8_LAS bf16x8*)(lds + PG8_SA(b, h) + aoff + m * 2048 + k * 1024); } while (0)
; #define PG8_LDB(dst, b, h) do { _Pragma("unroll") for (int n = 0; n < 2; ++n) _Pragma("unroll") for (int k = 0; k < 2; ++k) dst[n][k] = *(const PG8_LAS bf16x8*)(lds + PG8_SB(b, h) + boff + n * 2048 + k * 1024); } while (0)
; #define PG8_MMA(ai, bj, At, Bt) do { __builtin_amdgcn_s_setprio(1); _Pragma("unroll") for (int m = 0; m < 4; ++m) _Pragma("unroll") for (int n = 0; n < 2; ++n) _Pragma("unroll") for (int k = 0; k < 2; ++k) \
;         acc[ai][bj][m][n] = __builtin_amdgcn_mfma_f32_16x16x32_bf16(Bt[n][k], At[m][k], acc[ai][bj][m][n], 0, 0, 0); __builtin_amdgcn_s_setprio(0); } while (0)
; #define PG8_WAIT_V(n) asm volatile("s_waitcnt vmcnt(" #n ")" ::: "memory")
; #define PG8_WAIT_L(n) asm volatile("s_waitcnt lgkmcnt(" #n ")" ::: "memory")
; template <class Epi, class Sched, bool ALIGN_EPI = false, bool SP2 = false>
; __device__ __forceinline__ void gemm_phase(PG8_LAS unsigned char* lds, const Gemm g, const Sched& S, const Epi& E) {
;     ...
;             const bool last = (t == nt - 2);
;             const char* a1 = cA + (size_t)(t + 1) * kstep;
;             const char* a2 = last ? nA : cA + (size_t)(t + 2) * kstep; const char* b2 = last ? nB : cB + (size_t)(t + 2) * kstep;
;             const char* a3 = a2 + kstep; const char* b3 = b2 + kstep;
;             if (last && has_next) S.a_ready(nxt);
;             if constexpr (SP2) {
;             PG8_LDB(B0, 0, 0); PG8_LDB(B1, 0, 1); PG8_SCHED; PG8_LDA(At, 0, 0); PG8_STAGE(PG8_SA(1, 1), a1 + hstep, voffA);
;             PG8_WAIT_V(8); PG8_WAIT_L(0); PG8_BAR; PG8_MMA(0, 0, At, B0); PG8_MMA(0, 1, At, B1); PG8_BAR; PG8_SCHED;
;             PG8_LDA(At, 0, 1); PG8_STAGE(PG8_SB(0, 0), b2, voffB); PG8_STAGE(PG8_SB(0, 1), b2 + hstep, voffB); PG8_STAGE(PG8_SA(0, 0), a2, voffA);
;             PG8_WAIT_V(8); PG8_WAIT_L(0); PG8_BAR; PG8_MMA(1, 0, At, B0); PG8_MMA(1, 1, At, B1); PG8_BAR; PG8_SCHED;
.LBB0_250:
	ds_read_b128 v[156:159], v150
	ds_read_b128 v[160:163], v150 offset:1024
	ds_read_b128 v[164:167], v150 offset:2048
	ds_read_b128 v[168:171], v150 offset:3072
	ds_read_b128 v[172:175], v151
	ds_read_b128 v[176:179], v151 offset:1024
	ds_read_b128 v[184:187], v151 offset:2048
	ds_read_b128 v[188:191], v151 offset:3072
	s_add_u32 s40, s22, 0x80
	s_addc_u32 s41, s23, 0
	s_cmp_eq_u32 s9, s93
	s_cselect_b32 s40, s4, s40
	s_cselect_b32 s41, s5, s41
	s_cselect_b32 s95, s17, s92
	s_cselect_b32 s94, s16, s89
	s_mov_b32 m0, s37
	v_lshl_add_u64 v[180:181], s[22:23], 0, v[140:141]
	ds_read_b128 v[192:195], v149
	ds_read_b128 v[196:199], v149 offset:1024
	ds_read_b128 v[200:203], v149 offset:2048
	ds_read_b128 v[204:207], v149 offset:3072
	ds_read_b128 v[230:233], v149 offset:4096
	ds_read_b128 v[234:237], v149 offset:5120
	ds_read_b128 v[238:241], v149 offset:6144
	ds_read_b128 v[242:245], v149 offset:7168
	global_load_lds_dwordx4 v[180:181], off
	v_lshl_add_u64 v[180:181], s[22:23], 0, v[142:143]
	s_mov_b32 m0, s80
	s_nop 0
	global_load_lds_dwordx4 v[180:181], off
	s_waitcnt vmcnt(8)
	s_waitcnt lgkmcnt(0)
	s_barrier
	s_waitcnt lgkmcnt(0)
	v_mfma_f32_16x16x32_bf16 v[132:135], v[156:159], v[192:195], v[132:135]
	v_mfma_f32_16x16x32_bf16 v[132:135], v[160:163], v[196:199], v[132:135]
	v_mfma_f32_16x16x32_bf16 v[116:119], v[156:159], v[200:203], v[116:119]
	v_mfma_f32_16x16x32_bf16 v[116:119], v[160:163], v[204:207], v[116:119]
	v_mfma_f32_16x16x32_bf16 v[100:103], v[156:159], v[230:233], v[100:103]
	v_mfma_f32_16x16x32_bf16 v[100:103], v[160:163], v[234:237], v[100:103]
	v_mfma_f32_16x16x32_bf16 v[84:87], v[156:159], v[238:241], v[84:87]
	v_mfma_f32_16x16x32_bf16 v[84:87], v[160:163], v[242:245], v[84:87]
	v_mfma_f32_16x16x32_bf16 v[80:83], v[164:167], v[238:241], v[80:83]
	v_mfma_f32_16x16x32_bf16 v[80:83], v[168:171], v[242:245], v[80:83]
	v_mfma_f32_16x16x32_bf16 v[96:99], v[164:167], v[230:233], v[96:99]
	v_mfma_f32_16x16x32_bf16 v[96:99], v[168:171], v[234:237], v[96:99]
	v_mfma_f32_16x16x32_bf16 v[112:115], v[164:167], v[200:203], v[112:115]
	v_mfma_f32_16x16x32_bf16 v[112:115], v[168:171], v[204:207], v[112:115]
	v_mfma_f32_16x16x32_bf16 v[128:131], v[164:167], v[192:195], v[128:131]
	v_mfma_f32_16x16x32_bf16 v[128:131], v[168:171], v[196:199], v[128:131]
	v_mfma_f32_16x16x32_bf16 v[124:127], v[172:175], v[192:195], v[124:127]
	v_mfma_f32_16x16x32_bf16 v[124:127], v[176:179], v[196:199], v[124:127]
	v_mfma_f32_16x16x32_bf16 v[108:111], v[172:175], v[200:203], v[108:111]
	v_mfma_f32_16x16x32_bf16 v[108:111], v[176:179], v[204:207], v[108:111]
	v_mfma_f32_16x16x32_bf16 v[92:95], v[172:175], v[230:233], v[92:95]
	v_mfma_f32_16x16x32_bf16 v[92:95], v[176:179], v[234:237], v[92:95]
	v_mfma_f32_16x16x32_bf16 v[76:79], v[172:175], v[238:241], v[76:79]
	v_mfma_f32_16x16x32_bf16 v[76:79], v[176:179], v[242:245], v[76:79]
	v_mfma_f32_16x16x32_bf16 v[72:75], v[184:187], v[238:241], v[72:75]
	v_mfma_f32_16x16x32_bf16 v[72:75], v[188:191], v[242:245], v[72:75]
	v_mfma_f32_16x16x32_bf16 v[88:91], v[184:187], v[230:233], v[88:91]
	v_mfma_f32_16x16x32_bf16 v[88:91], v[188:191], v[234:237], v[88:91]
	v_mfma_f32_16x16x32_bf16 v[104:107], v[184:187], v[200:203], v[104:107]
	v_mfma_f32_16x16x32_bf16 v[104:107], v[188:191], v[204:207], v[104:107]
	v_mfma_f32_16x16x32_bf16 v[120:123], v[184:187], v[192:195], v[120:123]
	v_mfma_f32_16x16x32_bf16 v[120:123], v[188:191], v[196:199], v[120:123]
	s_barrier
	s_mov_b32 m0, s81
	v_lshl_add_u64 v[180:181], s[94:95], 0, v[0:1]
	v_lshl_add_u64 v[208:209], s[94:95], 0, v[138:139]
	s_add_u32 s94, s94, s48
	ds_read_b128 v[192:195], v149 offset:16384
	ds_read_b128 v[196:199], v149 offset:17408
	ds_read_b128 v[200:203], v149 offset:18432
	ds_read_b128 v[204:207], v149 offset:19456
	ds_read_b128 v[230:233], v149 offset:20480
	ds_read_b128 v[234:237], v149 offset:21504
	ds_read_b128 v[238:241], v149 offset:22528
	ds_read_b128 v[242:245], v149 offset:23552
	global_load_lds_dwordx4 v[180:181], off
	s_mov_b32 m0, s82
	s_addc_u32 s95, s95, s49
	global_load_lds_dwordx4 v[208:209], off
	v_lshl_add_u64 v[216:217], s[94:95], 0, v[0:1]
	s_mov_b32 m0, s83
	v_lshl_add_u64 v[224:225], s[94:95], 0, v[138:139]
	global_load_lds_dwordx4 v[216:217], off
	s_mov_b32 m0, s84
	v_lshl_add_u64 v[226:227], s[40:41], 0, v[2:3]
	global_load_lds_dwordx4 v[224:225], off
	s_mov_b32 m0, s47
	v_lshl_add_u64 v[228:229], s[40:41], 0, v[136:137]
	global_load_lds_dwordx4 v[226:227], off
	s_mov_b32 m0, s52
	s_nop 0
	global_load_lds_dwordx4 v[228:229], off
	s_waitcnt vmcnt(8)
	s_waitcnt lgkmcnt(0)
	s_barrier
; #define PG8_STAGE(bufoff, gbase, voff) do { _Pragma("unroll") for (int _i = 0; _i < 2; ++_i) \
;         __builtin_amdgcn_global_load_lds((const unsigned*)((const char*)(gbase) + (voff)[_i]), (PG8_LAS unsigned*)(lds + (bufoff) + ldsw + _i * 8192), 16, 0, 0); } while (0)
; #define PG8_LDA(dst, b, h) do { _Pragma("unroll") for (int m = 0; m < 4; ++m) _Pragma("unroll") for (int k = 0; k < 2; ++k) dst[m][k] = *(const PG8_LAS bf16x8*)(lds + PG8_SA(b, h) + aoff + m * 2048 + k * 1024); } while (0)
; #define PG8_LDB(dst, b, h) do { _Pragma("unroll") for (int n = 0; n < 2; ++n) _Pragma("unroll") for (int k = 0; k < 2; ++k) dst[n][k] = *(const PG8_LAS bf16x8*)(lds + PG8_SB(b, h) + boff + n * 2048 + k * 1024); } while (0)
; #define PG8_MMA(ai, bj, At, Bt) do { __builtin_amdgcn_s_setprio(1); _Pragma("unroll") for (int m = 0; m < 4; ++m) _Pragma("unroll") for (int n = 0; n < 2; ++n) _Pragma("unroll") for (int k = 0; k < 2; ++k) \
;         acc[ai][bj][m][n] = __builtin_amdgcn_mfma_f32_16x16x32_bf16(Bt[n][k], At[m][k], acc[ai][bj][m][n], 0, 0, 0); __builtin_amdgcn_s_setprio(0); } while (0)
; #define PG8_WAIT_V(n) asm volatile("s_waitcnt vmcnt(" #n ")" ::: "memory")
; #define PG8_WAIT_L(n) asm volatile("s_waitcnt lgkmcnt(" #n ")" ::: "memory")
; #define PG8_BAR __builtin_amdgcn_s_barrier()
; #define PG8_SCHED __builtin_amdgcn_sched_barrier(0)
; template <class Epi, class Sched, bool ALIGN_EPI = false, bool SP2 = false>
; __device__ __forceinline__ void gemm_phase(PG8_LAS unsigned char* lds, const Gemm g, const Sched& S, const Epi& E) {
;     ...
;             PG8_WAIT_V(8); PG8_WAIT_L(0); PG8_BAR; PG8_MMA(1, 0, At, B0); PG8_MMA(1, 1, At, B1); PG8_BAR; PG8_SCHED;
;             PG8_LDB(B0, 1, 0); PG8_LDB(B1, 1, 1); PG8_SCHED; PG8_LDA(At, 1, 0); PG8_STAGE(PG8_SA(0, 1), a2 + hstep, voffA);
;             PG8_WAIT_V(8); PG8_WAIT_L(0); PG8_BAR; PG8_MMA(0, 0, At, B0); PG8_MMA(0, 1, At, B1); PG8_BAR; PG8_SCHED;
	s_waitcnt lgkmcnt(0)
	v_mfma_f32_16x16x32_bf16 v[68:71], v[156:159], v[192:195], v[68:71]
	v_mfma_f32_16x16x32_bf16 v[68:71], v[160:163], v[196:199], v[68:71]
	v_mfma_f32_16x16x32_bf16 v[52:55], v[156:159], v[200:203], v[52:55]
	v_mfma_f32_16x16x32_bf16 v[52:55], v[160:163], v[204:207], v[52:55]
	v_mfma_f32_16x16x32_bf16 v[36:39], v[156:159], v[230:233], v[36:39]
	v_mfma_f32_16x16x32_bf16 v[36:39], v[160:163], v[234:237], v[36:39]
	v_mfma_f32_16x16x32_bf16 v[20:23], v[156:159], v[238:241], v[20:23]
	v_mfma_f32_16x16x32_bf16 v[20:23], v[160:163], v[242:245], v[20:23]
	v_mfma_f32_16x16x32_bf16 v[16:19], v[164:167], v[238:241], v[16:19]
	v_mfma_f32_16x16x32_bf16 v[16:19], v[168:171], v[242:245], v[16:19]
	v_mfma_f32_16x16x32_bf16 v[32:35], v[164:167], v[230:233], v[32:35]
	v_mfma_f32_16x16x32_bf16 v[32:35], v[168:171], v[234:237], v[32:35]
	v_mfma_f32_16x16x32_bf16 v[48:51], v[164:167], v[200:203], v[48:51]
	v_mfma_f32_16x16x32_bf16 v[48:51], v[168:171], v[204:207], v[48:51]
	v_mfma_f32_16x16x32_bf16 v[64:67], v[164:167], v[192:195], v[64:67]
	v_mfma_f32_16x16x32_bf16 v[64:67], v[168:171], v[196:199], v[64:67]
	v_mfma_f32_16x16x32_bf16 v[60:63], v[172:175], v[192:195], v[60:63]
	v_mfma_f32_16x16x32_bf16 v[60:63], v[176:179], v[196:199], v[60:63]
	v_mfma_f32_16x16x32_bf16 v[44:47], v[172:175], v[200:203], v[44:47]
	v_mfma_f32_16x16x32_bf16 v[44:47], v[176:179], v[204:207], v[44:47]
	v_mfma_f32_16x16x32_bf16 v[28:31], v[172:175], v[230:233], v[28:31]
	v_mfma_f32_16x16x32_bf16 v[28:31], v[176:179], v[234:237], v[28:31]
	v_mfma_f32_16x16x32_bf16 v[12:15], v[172:175], v[238:241], v[12:15]
	v_mfma_f32_16x16x32_bf16 v[12:15], v[176:179], v[242:245], v[12:15]
	v_mfma_f32_16x16x32_bf16 v[8:11], v[184:187], v[238:241], v[8:11]
	v_mfma_f32_16x16x32_bf16 v[8:11], v[188:191], v[242:245], v[8:11]
	v_mfma_f32_16x16x32_bf16 v[24:27], v[184:187], v[230:233], v[24:27]
	v_mfma_f32_16x16x32_bf16 v[24:27], v[188:191], v[234:237], v[24:27]
	v_mfma_f32_16x16x32_bf16 v[40:43], v[184:187], v[200:203], v[40:43]
	v_mfma_f32_16x16x32_bf16 v[40:43], v[188:191], v[204:207], v[40:43]
	v_mfma_f32_16x16x32_bf16 v[56:59], v[184:187], v[192:195], v[56:59]
	v_mfma_f32_16x16x32_bf16 v[56:59], v[188:191], v[196:199], v[56:59]
	s_barrier
	ds_read_b128 v[156:159], v152
	ds_read_b128 v[160:163], v152 offset:1024
	ds_read_b128 v[164:167], v152 offset:2048
	ds_read_b128 v[168:171], v152 offset:3072
	ds_read_b128 v[172:175], v153
	ds_read_b128 v[176:179], v153 offset:1024
	ds_read_b128 v[184:187], v153 offset:2048
	ds_read_b128 v[188:191], v153 offset:3072
	s_add_u32 s40, s40, s48
	s_addc_u32 s41, s41, s49
	s_mov_b32 m0, s53
	v_lshl_add_u64 v[246:247], s[40:41], 0, v[2:3]
	ds_read_b128 v[192:195], v149 offset:32768
	ds_read_b128 v[196:199], v149 offset:33792
	ds_read_b128 v[200:203], v149 offset:34816
	ds_read_b128 v[204:207], v149 offset:35840
	ds_read_b128 v[230:233], v149 offset:36864
	ds_read_b128 v[234:237], v149 offset:37888
	ds_read_b128 v[238:241], v149 offset:38912
	ds_read_b128 v[242:245], v149 offset:39936
	global_load_lds_dwordx4 v[246:247], off
	v_lshl_add_u64 v[246:247], s[40:41], 0, v[136:137]
	s_mov_b32 m0, s72
	s_nop 0
	global_load_lds_dwordx4 v[246:247], off
	s_waitcnt vmcnt(8)
	s_waitcnt lgkmcnt(0)
	s_barrier
	s_waitcnt lgkmcnt(0)
	v_mfma_f32_16x16x32_bf16 v[132:135], v[156:159], v[192:195], v[132:135]
	v_mfma_f32_16x16x32_bf16 v[132:135], v[160:163], v[196:199], v[132:135]
	v_mfma_f32_16x16x32_bf16 v[116:119], v[156:159], v[200:203], v[116:119]
	v_mfma_f32_16x16x32_bf16 v[116:119], v[160:163], v[204:207], v[116:119]
	v_mfma_f32_16x16x32_bf16 v[100:103], v[156:159], v[230:233], v[100:103]
	v_mfma_f32_16x16x32_bf16 v[100:103], v[160:163], v[234:237], v[100:103]
	v_mfma_f32_16x16x32_bf16 v[84:87], v[156:159], v[238:241], v[84:87]
	v_mfma_f32_16x16x32_bf16 v[84:87], v[160:163], v[242:245], v[84:87]
	v_mfma_f32_16x16x32_bf16 v[80:83], v[164:167], v[238:241], v[80:83]
	v_mfma_f32_16x16x32_bf16 v[80:83], v[168:171], v[242:245], v[80:83]
	v_mfma_f32_16x16x32_bf16 v[96:99], v[164:167], v[230:233], v[96:99]
	v_mfma_f32_16x16x32_bf16 v[96:99], v[168:171], v[234:237], v[96:99]
	v_mfma_f32_16x16x32_bf16 v[112:115], v[164:167], v[200:203], v[112:115]
	v_mfma_f32_16x16x32_bf16 v[112:115], v[168:171], v[204:207], v[112:115]
	v_mfma_f32_16x16x32_bf16 v[128:131], v[164:167], v[192:195], v[128:131]
	v_mfma_f32_16x16x32_bf16 v[128:131], v[168:171], v[196:199], v[128:131]
	v_mfma_f32_16x16x32_bf16 v[124:127], v[172:175], v[192:195], v[124:127]
	v_mfma_f32_16x16x32_bf16 v[124:127], v[176:179], v[196:199], v[124:127]
	v_mfma_f32_16x16x32_bf16 v[108:111], v[172:175], v[200:203], v[108:111]
	v_mfma_f32_16x16x32_bf16 v[108:111], v[176:179], v[204:207], v[108:111]
	v_mfma_f32_16x16x32_bf16 v[92:95], v[172:175], v[230:233], v[92:95]
	v_mfma_f32_16x16x32_bf16 v[92:95], v[176:179], v[234:237], v[92:95]
	v_mfma_f32_16x16x32_bf16 v[76:79], v[172:175], v[238:241], v[76:79]
	v_mfma_f32_16x16x32_bf16 v[76:79], v[176:179], v[242:245], v[76:79]
	v_mfma_f32_16x16x32_bf16 v[72:75], v[184:187], v[238:241], v[72:75]
	v_mfma_f32_16x16x32_bf16 v[72:75], v[188:191], v[242:245], v[72:75]
	v_mfma_f32_16x16x32_bf16 v[88:91], v[184:187], v[230:233], v[88:91]
	v_mfma_f32_16x16x32_bf16 v[88:91], v[188:191], v[234:237], v[88:91]
	v_mfma_f32_16x16x32_bf16 v[104:107], v[184:187], v[200:203], v[104:107]
	v_mfma_f32_16x16x32_bf16 v[104:107], v[188:191], v[204:207], v[104:107]
	v_mfma_f32_16x16x32_bf16 v[120:123], v[184:187], v[192:195], v[120:123]
	v_mfma_f32_16x16x32_bf16 v[120:123], v[188:191], v[196:199], v[120:123]
	s_barrier
; #define PG8_STAGE(bufoff, gbase, voff) do { _Pragma("unroll") for (int _i = 0; _i < 2; ++_i) \
;         __builtin_amdgcn_global_load_lds((const unsigned*)((const char*)(gbase) + (voff)[_i]), (PG8_LAS unsigned*)(lds + (bufoff) + ldsw + _i * 8192), 16, 0, 0); } while (0)
; #define PG8_LDA(dst, b, h) do { _Pragma("unroll") for (int m = 0; m < 4; ++m) _Pragma("unroll") for (int k = 0; k < 2; ++k) dst[m][k] = *(const PG8_LAS bf16x8*)(lds + PG8_SA(b, h) + aoff + m * 2048 + k * 1024); } while (0)
; #define PG8_MMA(ai, bj, At, Bt) do { __builtin_amdgcn_s_setprio(1); _Pragma("unroll") for (int m = 0; m < 4; ++m) _Pragma("unroll") for (int n = 0; n < 2; ++n) _Pragma("unroll") for (int k = 0; k < 2; ++k) \
;         acc[ai][bj][m][n] = __builtin_amdgcn_mfma_f32_16x16x32_bf16(Bt[n][k], At[m][k], acc[ai][bj][m][n], 0, 0, 0); __builtin_amdgcn_s_setprio(0); } while (0)
; #define PG8_WAIT_V(n) asm volatile("s_waitcnt vmcnt(" #n ")" ::: "memory")
; #define PG8_WAIT_L(n) asm volatile("s_waitcnt lgkmcnt(" #n ")" ::: "memory")
; #define PG8_BAR __builtin_amdgcn_s_barrier()
; #define PG8_SCHED __builtin_amdgcn_sched_barrier(0)
; template <class Epi, class Sched, bool ALIGN_EPI = false, bool SP2 = false>
; __device__ __forceinline__ void gemm_phase(PG8_LAS unsigned char* lds, const Gemm g, const Sched& S, const Epi& E) {
;     ...
;         for (int t = 0; t < nt; t += 2) {
;             if constexpr (Epi::KHOOK) { if ((t & 7) == 0 && t != 0) E.khook(acc, t >> 3, wr, fr, lds); }
;             const bool last = (t == nt - 2);
;             const char* a1 = cA + (size_t)(t + 1) * kstep;
;             const char* a2 = last ? nA : cA + (size_t)(t + 2) * kstep; const char* b2 = last ? nB : cB + (size_t)(t + 2) * kstep;
;     ...
;             PG8_LDA(At, 1, 1); PG8_STAGE(PG8_SB(1, 0), b3, voffB); PG8_STAGE(PG8_SB(1, 1), b3 + hstep, voffB); PG8_STAGE(PG8_SA(1, 0), a3, voffA);
;             PG8_WAIT_V(8); PG8_WAIT_L(0); PG8_BAR; PG8_MMA(1, 0, At, B0); PG8_MMA(1, 1, At, B1); PG8_BAR; PG8_SCHED;
	s_mov_b32 m0, s85
	v_lshl_add_u64 v[180:181], v[180:181], 0, s[24:25]
	ds_read_b128 v[192:195], v149 offset:49152
	ds_read_b128 v[196:199], v149 offset:50176
	ds_read_b128 v[200:203], v149 offset:51200
	ds_read_b128 v[204:207], v149 offset:52224
	ds_read_b128 v[230:233], v149 offset:53248
	ds_read_b128 v[234:237], v149 offset:54272
	ds_read_b128 v[238:241], v149 offset:55296
	ds_read_b128 v[242:245], v149 offset:56320
	global_load_lds_dwordx4 v[180:181], off
	v_lshl_add_u64 v[180:181], v[208:209], 0, s[24:25]
	s_mov_b32 m0, s86
	s_nop 0
	global_load_lds_dwordx4 v[180:181], off
	v_lshl_add_u64 v[180:181], v[216:217], 0, s[24:25]
	s_mov_b32 m0, s87
	s_nop 0
	global_load_lds_dwordx4 v[180:181], off
	v_lshl_add_u64 v[180:181], v[224:225], 0, s[24:25]
	s_mov_b32 m0, s88
	s_nop 0
	global_load_lds_dwordx4 v[180:181], off
	v_lshl_add_u64 v[180:181], v[226:227], 0, s[24:25]
	s_mov_b32 m0, s75
	s_nop 0
	global_load_lds_dwordx4 v[180:181], off
	v_lshl_add_u64 v[180:181], v[228:229], 0, s[24:25]
	s_mov_b32 m0, s76
	s_nop 0
	global_load_lds_dwordx4 v[180:181], off
	s_waitcnt vmcnt(8)
	s_waitcnt lgkmcnt(0)
	s_barrier
	s_waitcnt lgkmcnt(0)
	v_mfma_f32_16x16x32_bf16 v[68:71], v[156:159], v[192:195], v[68:71]
	v_mfma_f32_16x16x32_bf16 v[68:71], v[160:163], v[196:199], v[68:71]
	v_mfma_f32_16x16x32_bf16 v[52:55], v[156:159], v[200:203], v[52:55]
	v_mfma_f32_16x16x32_bf16 v[52:55], v[160:163], v[204:207], v[52:55]
	v_mfma_f32_16x16x32_bf16 v[36:39], v[156:159], v[230:233], v[36:39]
	v_mfma_f32_16x16x32_bf16 v[36:39], v[160:163], v[234:237], v[36:39]
	v_mfma_f32_16x16x32_bf16 v[20:23], v[156:159], v[238:241], v[20:23]
	v_mfma_f32_16x16x32_bf16 v[20:23], v[160:163], v[242:245], v[20:23]
	v_mfma_f32_16x16x32_bf16 v[16:19], v[164:167], v[238:241], v[16:19]
	v_mfma_f32_16x16x32_bf16 v[16:19], v[168:171], v[242:245], v[16:19]
	v_mfma_f32_16x16x32_bf16 v[32:35], v[164:167], v[230:233], v[32:35]
	v_mfma_f32_16x16x32_bf16 v[32:35], v[168:171], v[234:237], v[32:35]
	v_mfma_f32_16x16x32_bf16 v[48:51], v[164:167], v[200:203], v[48:51]
	v_mfma_f32_16x16x32_bf16 v[48:51], v[168:171], v[204:207], v[48:51]
	v_mfma_f32_16x16x32_bf16 v[64:67], v[164:167], v[192:195], v[64:67]
	v_mfma_f32_16x16x32_bf16 v[64:67], v[168:171], v[196:199], v[64:67]
	v_mfma_f32_16x16x32_bf16 v[60:63], v[172:175], v[192:195], v[60:63]
	v_mfma_f32_16x16x32_bf16 v[60:63], v[176:179], v[196:199], v[60:63]
	v_mfma_f32_16x16x32_bf16 v[44:47], v[172:175], v[200:203], v[44:47]
	v_mfma_f32_16x16x32_bf16 v[44:47], v[176:179], v[204:207], v[44:47]
	v_mfma_f32_16x16x32_bf16 v[28:31], v[172:175], v[230:233], v[28:31]
	v_mfma_f32_16x16x32_bf16 v[28:31], v[176:179], v[234:237], v[28:31]
	v_mfma_f32_16x16x32_bf16 v[12:15], v[172:175], v[238:241], v[12:15]
	v_mfma_f32_16x16x32_bf16 v[12:15], v[176:179], v[242:245], v[12:15]
	v_mfma_f32_16x16x32_bf16 v[8:11], v[184:187], v[238:241], v[8:11]
	v_mfma_f32_16x16x32_bf16 v[8:11], v[188:191], v[242:245], v[8:11]
	v_mfma_f32_16x16x32_bf16 v[24:27], v[184:187], v[230:233], v[24:27]
	v_mfma_f32_16x16x32_bf16 v[24:27], v[188:191], v[234:237], v[24:27]
	v_mfma_f32_16x16x32_bf16 v[40:43], v[184:187], v[200:203], v[40:43]
	v_mfma_f32_16x16x32_bf16 v[40:43], v[188:191], v[204:207], v[40:43]
	v_mfma_f32_16x16x32_bf16 v[56:59], v[184:187], v[192:195], v[56:59]
	v_mfma_f32_16x16x32_bf16 v[56:59], v[188:191], v[196:199], v[56:59]
	s_barrier
	s_add_i32 s40, s93, 2
	s_add_u32 s22, s22, 0x100
	s_addc_u32 s23, s23, 0
	s_add_u32 s89, s89, 0x100
	s_addc_u32 s92, s92, 0
	s_cmp_ge_u32 s93, s9
	v_add_u32_e32 v154, 0x100, v154
	s_cbranch_scc0 .LBB0_248

; #define PG8_STAGE(bufoff, gbase, voff) do { _Pragma("unroll") for (int _i = 0; _i < 2; ++_i) \
;         __builtin_amdgcn_global_load_lds((const unsigned*)((const char*)(gbase) + (voff)[_i]), (PG8_LAS unsigned*)(lds + (bufoff) + ldsw + _i * 8192), 16, 0, 0); } while (0)
; #define PG8_LDA(dst, b, h) do { _Pragma("unroll") for (int m = 0; m < 4; ++m) _Pragma("unroll") for (int k = 0; k < 2; ++k) dst[m][k] = *(const PG8_LAS bf16x8*)(lds + PG8_SA(b, h) + aoff + m * 2048 + k * 1024); } while (0)
; #define PG8_LDB(dst, b, h) do { _Pragma("unroll") for (int n = 0; n < 2; ++n) _Pragma("unroll") for (int k = 0; k < 2; ++k) dst[n][k] = *(const PG8_LAS bf16x8*)(lds + PG8_SB(b, h) + boff + n * 2048 + k * 1024); } while (0)
; #define PG8_MMA(ai, bj, At, Bt) do { __builtin_amdgcn_s_setprio(1); _Pragma("unroll") for (int m = 0; m < 4; ++m) _Pragma("unroll") for (int n = 0; n < 2; ++n) _Pragma("unroll") for (int k = 0; k < 2; ++k) \
;         acc[ai][bj][m][n] = __builtin_amdgcn_mfma_f32_16x16x32_bf16(Bt[n][k], At[m][k], acc[ai][bj][m][n], 0, 0, 0); __builtin_amdgcn_s_setprio(0); } while (0)
; #define PG8_WAIT_V(n) asm volatile("s_waitcnt vmcnt(" #n ")" ::: "memory")
; #define PG8_WAIT_L(n) asm volatile("s_waitcnt lgkmcnt(" #n ")" ::: "memory")
; template <class Epi, class Sched, bool ALIGN_EPI = false, bool SP2 = false>
; __device__ __forceinline__ void gemm_phase(PG8_LAS unsigned char* lds, const Gemm g, const Sched& S, const Epi& E) {
;     ...
;             const bool last = (t == nt - 2);
;             const char* a1 = cA + (size_t)(t + 1) * kstep;
;             const char* a2 = last ? nA : cA + (size_t)(t + 2) * kstep; const char* b2 = last ? nB : cB + (size_t)(t + 2) * kstep;
;             const char* a3 = a2 + kstep; const char* b3 = b2 + kstep;
;             if (last && has_next) S.a_ready(nxt);
;             if constexpr (SP2) {
;             PG8_LDB(B0, 0, 0); PG8_LDB(B1, 0, 1); PG8_SCHED; PG8_LDA(At, 0, 0); PG8_STAGE(PG8_SA(1, 1), a1 + hstep, voffA);
;             PG8_WAIT_V(8); PG8_WAIT_L(0); PG8_BAR; PG8_MMA(0, 0, At, B0); PG8_MMA(0, 1, At, B1); PG8_BAR; PG8_SCHED;
;             PG8_LDA(At, 0, 1); PG8_STAGE(PG8_SB(0, 0), b2, voffB); PG8_STAGE(PG8_SB(0, 1), b2 + hstep, voffB); PG8_STAGE(PG8_SA(0, 0), a2, voffA);
;             PG8_WAIT_V(8); PG8_WAIT_L(0); PG8_BAR; PG8_MMA(1, 0, At, B0); PG8_MMA(1, 1, At, B1); PG8_BAR; PG8_SCHED;
.LBB0_294:
	s_add_i32 s81, s40, 2
	s_add_u32 s82, s38, 0x80
	s_addc_u32 s41, s39, 0
	s_cmp_eq_u32 s33, s40
	s_cselect_b32 s41, s7, s41
	s_cselect_b32 s40, s6, s82
	v_add_u32_e32 v0, s19, v151
	s_cselect_b32 s83, s23, s80
	s_cselect_b32 s82, s22, s79
	s_add_i32 s84, 0, 0x14000
	ds_read_b128 v[154:157], v0
	ds_read_b128 v[158:161], v0 offset:1024
	ds_read_b128 v[162:165], v0 offset:2048
	ds_read_b128 v[166:169], v0 offset:3072
	v_add_u32_e32 v0, s84, v151
	ds_read_b128 v[170:173], v0
	ds_read_b128 v[174:177], v0 offset:1024
	ds_read_b128 v[178:181], v0 offset:2048
	ds_read_b128 v[184:187], v0 offset:3072
	v_lshl_add_u64 v[2:3], s[38:39], 0, v[144:145]
	s_add_i32 m0, s46, 0xc000
	ds_read_b128 v[188:191], v152
	ds_read_b128 v[192:195], v152 offset:1024
	ds_read_b128 v[196:199], v152 offset:2048
	ds_read_b128 v[200:203], v152 offset:3072
	ds_read_b128 v[204:207], v152 offset:4096
	ds_read_b128 v[230:233], v152 offset:5120
	ds_read_b128 v[234:237], v152 offset:6144
	ds_read_b128 v[238:241], v152 offset:7168
	global_load_lds_dwordx4 v[2:3], off
	v_lshl_add_u64 v[2:3], s[38:39], 0, v[146:147]
	s_add_i32 m0, s46, 0xe000
	s_nop 0
	global_load_lds_dwordx4 v[2:3], off
	s_waitcnt vmcnt(8)
	s_waitcnt lgkmcnt(0)
	s_barrier
	s_waitcnt lgkmcnt(0)
	v_mfma_f32_16x16x32_bf16 v[8:11], v[154:157], v[188:191], v[8:11]
	v_mfma_f32_16x16x32_bf16 v[8:11], v[158:161], v[192:195], v[8:11]
	v_mfma_f32_16x16x32_bf16 v[48:51], v[154:157], v[196:199], v[48:51]
	v_mfma_f32_16x16x32_bf16 v[48:51], v[158:161], v[200:203], v[48:51]
	v_mfma_f32_16x16x32_bf16 v[96:99], v[154:157], v[204:207], v[96:99]
	v_mfma_f32_16x16x32_bf16 v[96:99], v[158:161], v[230:233], v[96:99]
	v_mfma_f32_16x16x32_bf16 v[120:123], v[154:157], v[234:237], v[120:123]
	v_mfma_f32_16x16x32_bf16 v[120:123], v[158:161], v[238:241], v[120:123]
	v_mfma_f32_16x16x32_bf16 v[124:127], v[162:165], v[234:237], v[124:127]
	v_mfma_f32_16x16x32_bf16 v[124:127], v[166:169], v[238:241], v[124:127]
	v_mfma_f32_16x16x32_bf16 v[100:103], v[162:165], v[204:207], v[100:103]
	v_mfma_f32_16x16x32_bf16 v[100:103], v[166:169], v[230:233], v[100:103]
	v_mfma_f32_16x16x32_bf16 v[52:55], v[162:165], v[196:199], v[52:55]
	v_mfma_f32_16x16x32_bf16 v[52:55], v[166:169], v[200:203], v[52:55]
	v_mfma_f32_16x16x32_bf16 v[12:15], v[162:165], v[188:191], v[12:15]
	v_mfma_f32_16x16x32_bf16 v[12:15], v[166:169], v[192:195], v[12:15]
	v_mfma_f32_16x16x32_bf16 v[24:27], v[170:173], v[188:191], v[24:27]
	v_mfma_f32_16x16x32_bf16 v[24:27], v[174:177], v[192:195], v[24:27]
	v_mfma_f32_16x16x32_bf16 v[72:75], v[170:173], v[196:199], v[72:75]
	v_mfma_f32_16x16x32_bf16 v[72:75], v[174:177], v[200:203], v[72:75]
	v_mfma_f32_16x16x32_bf16 v[112:115], v[170:173], v[204:207], v[112:115]
	v_mfma_f32_16x16x32_bf16 v[112:115], v[174:177], v[230:233], v[112:115]
	v_mfma_f32_16x16x32_bf16 v[128:131], v[170:173], v[234:237], v[128:131]
	v_mfma_f32_16x16x32_bf16 v[128:131], v[174:177], v[238:241], v[128:131]
	v_mfma_f32_16x16x32_bf16 v[132:135], v[178:181], v[234:237], v[132:135]
	v_mfma_f32_16x16x32_bf16 v[132:135], v[184:187], v[238:241], v[132:135]
	v_mfma_f32_16x16x32_bf16 v[116:119], v[178:181], v[204:207], v[116:119]
	v_mfma_f32_16x16x32_bf16 v[116:119], v[184:187], v[230:233], v[116:119]
	v_mfma_f32_16x16x32_bf16 v[76:79], v[178:181], v[196:199], v[76:79]
	v_mfma_f32_16x16x32_bf16 v[76:79], v[184:187], v[200:203], v[76:79]
	v_mfma_f32_16x16x32_bf16 v[28:31], v[178:181], v[188:191], v[28:31]
	v_mfma_f32_16x16x32_bf16 v[28:31], v[184:187], v[192:195], v[28:31]
	s_barrier
	s_add_i32 s85, s19, s37
	v_lshl_add_u64 v[2:3], s[82:83], 0, v[140:141]
	s_mov_b32 m0, s85
	ds_read_b128 v[188:191], v152 offset:16384
	ds_read_b128 v[192:195], v152 offset:17408
	ds_read_b128 v[196:199], v152 offset:18432
	ds_read_b128 v[200:203], v152 offset:19456
	ds_read_b128 v[204:207], v152 offset:20480
	ds_read_b128 v[230:233], v152 offset:21504
	ds_read_b128 v[234:237], v152 offset:22528
	ds_read_b128 v[238:241], v152 offset:23552
	global_load_lds_dwordx4 v[2:3], off
	s_add_i32 m0, s85, 0x2000
	v_lshl_add_u64 v[208:209], s[82:83], 0, v[136:137]
	s_add_u32 s82, s82, s48
	s_addc_u32 s83, s83, s49
	s_add_i32 s84, s84, s37
	global_load_lds_dwordx4 v[208:209], off
	v_lshl_add_u64 v[216:217], s[82:83], 0, v[140:141]
	s_mov_b32 m0, s84
	v_lshl_add_u64 v[224:225], s[82:83], 0, v[136:137]
	global_load_lds_dwordx4 v[216:217], off
	s_add_i32 m0, s84, 0x2000
	v_lshl_add_u64 v[226:227], s[40:41], 0, v[142:143]
	global_load_lds_dwordx4 v[224:225], off
	s_mov_b32 m0, s46
	v_lshl_add_u64 v[228:229], s[40:41], 0, v[138:139]
	global_load_lds_dwordx4 v[226:227], off
	s_mov_b32 m0, s47
	s_nop 0
	global_load_lds_dwordx4 v[228:229], off
	s_waitcnt vmcnt(8)
	s_waitcnt lgkmcnt(0)
	s_barrier
; #define PG8_STAGE(bufoff, gbase, voff) do { _Pragma("unroll") for (int _i = 0; _i < 2; ++_i) \
;         __builtin_amdgcn_global_load_lds((const unsigned*)((const char*)(gbase) + (voff)[_i]), (PG8_LAS unsigned*)(lds + (bufoff) + ldsw + _i * 8192), 16, 0, 0); } while (0)
; #define PG8_LDA(dst, b, h) do { _Pragma("unroll") for (int m = 0; m < 4; ++m) _Pragma("unroll") for (int k = 0; k < 2; ++k) dst[m][k] = *(const PG8_LAS bf16x8*)(lds + PG8_SA(b, h) + aoff + m * 2048 + k * 1024); } while (0)
; #define PG8_LDB(dst, b, h) do { _Pragma("unroll") for (int n = 0; n < 2; ++n) _Pragma("unroll") for (int k = 0; k < 2; ++k) dst[n][k] = *(const PG8_LAS bf16x8*)(lds + PG8_SB(b, h) + boff + n * 2048 + k * 1024); } while (0)
; #define PG8_MMA(ai, bj, At, Bt) do { __builtin_amdgcn_s_setprio(1); _Pragma("unroll") for (int m = 0; m < 4; ++m) _Pragma("unroll") for (int n = 0; n < 2; ++n) _Pragma("unroll") for (int k = 0; k < 2; ++k) \
;         acc[ai][bj][m][n] = __builtin_amdgcn_mfma_f32_16x16x32_bf16(Bt[n][k], At[m][k], acc[ai][bj][m][n], 0, 0, 0); __builtin_amdgcn_s_setprio(0); } while (0)
; #define PG8_WAIT_V(n) asm volatile("s_waitcnt vmcnt(" #n ")" ::: "memory")
; #define PG8_WAIT_L(n) asm volatile("s_waitcnt lgkmcnt(" #n ")" ::: "memory")
; #define PG8_BAR __builtin_amdgcn_s_barrier()
; #define PG8_SCHED __builtin_amdgcn_sched_barrier(0)
; template <class Epi, class Sched, bool ALIGN_EPI = false, bool SP2 = false>
; __device__ __forceinline__ void gemm_phase(PG8_LAS unsigned char* lds, const Gemm g, const Sched& S, const Epi& E) {
;     ...
;             PG8_WAIT_V(8); PG8_WAIT_L(0); PG8_BAR; PG8_MMA(1, 0, At, B0); PG8_MMA(1, 1, At, B1); PG8_BAR; PG8_SCHED;
;             PG8_LDB(B0, 1, 0); PG8_LDB(B1, 1, 1); PG8_SCHED; PG8_LDA(At, 1, 0); PG8_STAGE(PG8_SA(0, 1), a2 + hstep, voffA);
;             PG8_WAIT_V(8); PG8_WAIT_L(0); PG8_BAR; PG8_MMA(0, 0, At, B0); PG8_MMA(0, 1, At, B1); PG8_BAR; PG8_SCHED;
	s_waitcnt lgkmcnt(0)
	v_mfma_f32_16x16x32_bf16 v[16:19], v[154:157], v[188:191], v[16:19]
	v_mfma_f32_16x16x32_bf16 v[16:19], v[158:161], v[192:195], v[16:19]
	v_mfma_f32_16x16x32_bf16 v[56:59], v[154:157], v[196:199], v[56:59]
	v_mfma_f32_16x16x32_bf16 v[56:59], v[158:161], v[200:203], v[56:59]
	v_mfma_f32_16x16x32_bf16 v[104:107], v[154:157], v[204:207], v[104:107]
	v_mfma_f32_16x16x32_bf16 v[104:107], v[158:161], v[230:233], v[104:107]
	v_mfma_f32_16x16x32_bf16 v[68:71], v[154:157], v[234:237], v[68:71]
	v_mfma_f32_16x16x32_bf16 v[68:71], v[158:161], v[238:241], v[68:71]
	v_mfma_f32_16x16x32_bf16 v[64:67], v[162:165], v[234:237], v[64:67]
	v_mfma_f32_16x16x32_bf16 v[64:67], v[166:169], v[238:241], v[64:67]
	v_mfma_f32_16x16x32_bf16 v[108:111], v[162:165], v[204:207], v[108:111]
	v_mfma_f32_16x16x32_bf16 v[108:111], v[166:169], v[230:233], v[108:111]
	v_mfma_f32_16x16x32_bf16 v[60:63], v[162:165], v[196:199], v[60:63]
	v_mfma_f32_16x16x32_bf16 v[60:63], v[166:169], v[200:203], v[60:63]
	v_mfma_f32_16x16x32_bf16 v[20:23], v[162:165], v[188:191], v[20:23]
	v_mfma_f32_16x16x32_bf16 v[20:23], v[166:169], v[192:195], v[20:23]
	v_mfma_f32_16x16x32_bf16 v[40:43], v[170:173], v[188:191], v[40:43]
	v_mfma_f32_16x16x32_bf16 v[40:43], v[174:177], v[192:195], v[40:43]
	v_mfma_f32_16x16x32_bf16 v[88:91], v[170:173], v[196:199], v[88:91]
	v_mfma_f32_16x16x32_bf16 v[88:91], v[174:177], v[200:203], v[88:91]
	v_mfma_f32_16x16x32_bf16 v[84:87], v[170:173], v[204:207], v[84:87]
	v_mfma_f32_16x16x32_bf16 v[84:87], v[174:177], v[230:233], v[84:87]
	v_mfma_f32_16x16x32_bf16 v[36:39], v[170:173], v[234:237], v[36:39]
	v_mfma_f32_16x16x32_bf16 v[36:39], v[174:177], v[238:241], v[36:39]
	v_mfma_f32_16x16x32_bf16 v[32:35], v[178:181], v[234:237], v[32:35]
	v_mfma_f32_16x16x32_bf16 v[32:35], v[184:187], v[238:241], v[32:35]
	v_mfma_f32_16x16x32_bf16 v[80:83], v[178:181], v[204:207], v[80:83]
	v_mfma_f32_16x16x32_bf16 v[80:83], v[184:187], v[230:233], v[80:83]
	v_mfma_f32_16x16x32_bf16 v[92:95], v[178:181], v[196:199], v[92:95]
	v_mfma_f32_16x16x32_bf16 v[92:95], v[184:187], v[200:203], v[92:95]
	v_mfma_f32_16x16x32_bf16 v[44:47], v[178:181], v[188:191], v[44:47]
	v_mfma_f32_16x16x32_bf16 v[44:47], v[184:187], v[192:195], v[44:47]
	s_barrier
	v_add_u32_e32 v0, s91, v151
	s_add_i32 s82, 0, 0x1c000
	ds_read_b128 v[154:157], v0
	ds_read_b128 v[158:161], v0 offset:1024
	ds_read_b128 v[162:165], v0 offset:2048
	ds_read_b128 v[166:169], v0 offset:3072
	v_add_u32_e32 v0, s82, v151
	ds_read_b128 v[170:173], v0
	ds_read_b128 v[174:177], v0 offset:1024
	ds_read_b128 v[178:181], v0 offset:2048
	ds_read_b128 v[184:187], v0 offset:3072
	s_add_u32 s40, s40, s48
	s_addc_u32 s41, s41, s49
	s_mov_b32 m0, s52
	v_lshl_add_u64 v[242:243], s[40:41], 0, v[142:143]
	ds_read_b128 v[188:191], v152 offset:32768
	ds_read_b128 v[192:195], v152 offset:33792
	ds_read_b128 v[196:199], v152 offset:34816
	ds_read_b128 v[200:203], v152 offset:35840
	ds_read_b128 v[204:207], v152 offset:36864
	ds_read_b128 v[230:233], v152 offset:37888
	ds_read_b128 v[234:237], v152 offset:38912
	ds_read_b128 v[238:241], v152 offset:39936
	global_load_lds_dwordx4 v[242:243], off
	v_lshl_add_u64 v[242:243], s[40:41], 0, v[138:139]
	s_mov_b32 m0, s53
	s_nop 0
	global_load_lds_dwordx4 v[242:243], off
	s_waitcnt vmcnt(8)
	s_waitcnt lgkmcnt(0)
	s_barrier
	s_waitcnt lgkmcnt(0)
	v_mfma_f32_16x16x32_bf16 v[8:11], v[154:157], v[188:191], v[8:11]
	v_mfma_f32_16x16x32_bf16 v[8:11], v[158:161], v[192:195], v[8:11]
	v_mfma_f32_16x16x32_bf16 v[48:51], v[154:157], v[196:199], v[48:51]
	v_mfma_f32_16x16x32_bf16 v[48:51], v[158:161], v[200:203], v[48:51]
	v_mfma_f32_16x16x32_bf16 v[96:99], v[154:157], v[204:207], v[96:99]
	v_mfma_f32_16x16x32_bf16 v[96:99], v[158:161], v[230:233], v[96:99]
	v_mfma_f32_16x16x32_bf16 v[120:123], v[154:157], v[234:237], v[120:123]
	v_mfma_f32_16x16x32_bf16 v[120:123], v[158:161], v[238:241], v[120:123]
	v_mfma_f32_16x16x32_bf16 v[124:127], v[162:165], v[234:237], v[124:127]
	v_mfma_f32_16x16x32_bf16 v[124:127], v[166:169], v[238:241], v[124:127]
	v_mfma_f32_16x16x32_bf16 v[100:103], v[162:165], v[204:207], v[100:103]
	v_mfma_f32_16x16x32_bf16 v[100:103], v[166:169], v[230:233], v[100:103]
	v_mfma_f32_16x16x32_bf16 v[52:55], v[162:165], v[196:199], v[52:55]
	v_mfma_f32_16x16x32_bf16 v[52:55], v[166:169], v[200:203], v[52:55]
	v_mfma_f32_16x16x32_bf16 v[12:15], v[162:165], v[188:191], v[12:15]
	v_mfma_f32_16x16x32_bf16 v[12:15], v[166:169], v[192:195], v[12:15]
	v_mfma_f32_16x16x32_bf16 v[24:27], v[170:173], v[188:191], v[24:27]
	v_mfma_f32_16x16x32_bf16 v[24:27], v[174:177], v[192:195], v[24:27]
	v_mfma_f32_16x16x32_bf16 v[72:75], v[170:173], v[196:199], v[72:75]
	v_mfma_f32_16x16x32_bf16 v[72:75], v[174:177], v[200:203], v[72:75]
	v_mfma_f32_16x16x32_bf16 v[112:115], v[170:173], v[204:207], v[112:115]
	v_mfma_f32_16x16x32_bf16 v[112:115], v[174:177], v[230:233], v[112:115]
	v_mfma_f32_16x16x32_bf16 v[128:131], v[170:173], v[234:237], v[128:131]
	v_mfma_f32_16x16x32_bf16 v[128:131], v[174:177], v[238:241], v[128:131]
	v_mfma_f32_16x16x32_bf16 v[132:135], v[178:181], v[234:237], v[132:135]
	v_mfma_f32_16x16x32_bf16 v[132:135], v[184:187], v[238:241], v[132:135]
	v_mfma_f32_16x16x32_bf16 v[116:119], v[178:181], v[204:207], v[116:119]
	v_mfma_f32_16x16x32_bf16 v[116:119], v[184:187], v[230:233], v[116:119]
	v_mfma_f32_16x16x32_bf16 v[76:79], v[178:181], v[196:199], v[76:79]
	v_mfma_f32_16x16x32_bf16 v[76:79], v[184:187], v[200:203], v[76:79]
	v_mfma_f32_16x16x32_bf16 v[28:31], v[178:181], v[188:191], v[28:31]
	v_mfma_f32_16x16x32_bf16 v[28:31], v[184:187], v[192:195], v[28:31]
	s_barrier
; #define PG8_STAGE(bufoff, gbase, voff) do { _Pragma("unroll") for (int _i = 0; _i < 2; ++_i) \
;         __builtin_amdgcn_global_load_lds((const unsigned*)((const char*)(gbase) + (voff)[_i]), (PG8_LAS unsigned*)(lds + (bufoff) + ldsw + _i * 8192), 16, 0, 0); } while (0)
; #define PG8_LDA(dst, b, h) do { _Pragma("unroll") for (int m = 0; m < 4; ++m) _Pragma("unroll") for (int k = 0; k < 2; ++k) dst[m][k] = *(const PG8_LAS bf16x8*)(lds + PG8_SA(b, h) + aoff + m * 2048 + k * 1024); } while (0)
; #define PG8_MMA(ai, bj, At, Bt) do { __builtin_amdgcn_s_setprio(1); _Pragma("unroll") for (int m = 0; m < 4; ++m) _Pragma("unroll") for (int n = 0; n < 2; ++n) _Pragma("unroll") for (int k = 0; k < 2; ++k) \
;         acc[ai][bj][m][n] = __builtin_amdgcn_mfma_f32_16x16x32_bf16(Bt[n][k], At[m][k], acc[ai][bj][m][n], 0, 0, 0); __builtin_amdgcn_s_setprio(0); } while (0)
; #define PG8_WAIT_V(n) asm volatile("s_waitcnt vmcnt(" #n ")" ::: "memory")
; #define PG8_WAIT_L(n) asm volatile("s_waitcnt lgkmcnt(" #n ")" ::: "memory")
; #define PG8_BAR __builtin_amdgcn_s_barrier()
; #define PG8_SCHED __builtin_amdgcn_sched_barrier(0)
; template <class Epi, class Sched, bool ALIGN_EPI = false, bool SP2 = false>
; __device__ __forceinline__ void gemm_phase(PG8_LAS unsigned char* lds, const Gemm g, const Sched& S, const Epi& E) {
;     ...
;         for (int t = 0; t < nt; t += 2) {
;             if constexpr (Epi::KHOOK) { if ((t & 7) == 0 && t != 0) E.khook(acc, t >> 3, wr, fr, lds); }
;             const bool last = (t == nt - 2);
;             const char* a1 = cA + (size_t)(t + 1) * kstep;
;             const char* a2 = last ? nA : cA + (size_t)(t + 2) * kstep; const char* b2 = last ? nB : cB + (size_t)(t + 2) * kstep;
;     ...
;             PG8_LDA(At, 1, 1); PG8_STAGE(PG8_SB(1, 0), b3, voffB); PG8_STAGE(PG8_SB(1, 1), b3 + hstep, voffB); PG8_STAGE(PG8_SA(1, 0), a3, voffA);
;             PG8_WAIT_V(8); PG8_WAIT_L(0); PG8_BAR; PG8_MMA(1, 0, At, B0); PG8_MMA(1, 1, At, B1); PG8_BAR; PG8_SCHED;
	s_add_i32 s40, s91, s37
	v_lshl_add_u64 v[2:3], v[2:3], 0, s[24:25]
	s_mov_b32 m0, s40
	ds_read_b128 v[188:191], v152 offset:49152
	ds_read_b128 v[192:195], v152 offset:50176
	ds_read_b128 v[196:199], v152 offset:51200
	ds_read_b128 v[200:203], v152 offset:52224
	ds_read_b128 v[204:207], v152 offset:53248
	ds_read_b128 v[230:233], v152 offset:54272
	ds_read_b128 v[234:237], v152 offset:55296
	ds_read_b128 v[238:241], v152 offset:56320
	global_load_lds_dwordx4 v[2:3], off
	v_lshl_add_u64 v[2:3], v[208:209], 0, s[24:25]
	s_add_i32 m0, s40, 0x2000
	s_add_i32 s40, s82, s37
	global_load_lds_dwordx4 v[2:3], off
	v_lshl_add_u64 v[2:3], v[216:217], 0, s[24:25]
	s_mov_b32 m0, s40
	s_nop 0
	global_load_lds_dwordx4 v[2:3], off
	v_lshl_add_u64 v[2:3], v[224:225], 0, s[24:25]
	s_add_i32 m0, s40, 0x2000
	s_nop 0
	global_load_lds_dwordx4 v[2:3], off
	v_lshl_add_u64 v[2:3], v[226:227], 0, s[24:25]
	s_mov_b32 m0, s73
	s_nop 0
	global_load_lds_dwordx4 v[2:3], off
	v_lshl_add_u64 v[2:3], v[228:229], 0, s[24:25]
	s_mov_b32 m0, s74
	s_nop 0
	global_load_lds_dwordx4 v[2:3], off
	s_waitcnt vmcnt(8)
	s_waitcnt lgkmcnt(0)
	s_barrier
	s_waitcnt lgkmcnt(0)
	v_mfma_f32_16x16x32_bf16 v[16:19], v[154:157], v[188:191], v[16:19]
	v_mfma_f32_16x16x32_bf16 v[16:19], v[158:161], v[192:195], v[16:19]
	v_mfma_f32_16x16x32_bf16 v[56:59], v[154:157], v[196:199], v[56:59]
	v_mfma_f32_16x16x32_bf16 v[56:59], v[158:161], v[200:203], v[56:59]
	v_mfma_f32_16x16x32_bf16 v[104:107], v[154:157], v[204:207], v[104:107]
	v_mfma_f32_16x16x32_bf16 v[104:107], v[158:161], v[230:233], v[104:107]
	v_mfma_f32_16x16x32_bf16 v[68:71], v[154:157], v[234:237], v[68:71]
	v_mfma_f32_16x16x32_bf16 v[68:71], v[158:161], v[238:241], v[68:71]
	v_mfma_f32_16x16x32_bf16 v[64:67], v[162:165], v[234:237], v[64:67]
	v_mfma_f32_16x16x32_bf16 v[64:67], v[166:169], v[238:241], v[64:67]
	v_mfma_f32_16x16x32_bf16 v[108:111], v[162:165], v[204:207], v[108:111]
	v_mfma_f32_16x16x32_bf16 v[108:111], v[166:169], v[230:233], v[108:111]
	v_mfma_f32_16x16x32_bf16 v[60:63], v[162:165], v[196:199], v[60:63]
	v_mfma_f32_16x16x32_bf16 v[60:63], v[166:169], v[200:203], v[60:63]
	v_mfma_f32_16x16x32_bf16 v[20:23], v[162:165], v[188:191], v[20:23]
	v_mfma_f32_16x16x32_bf16 v[20:23], v[166:169], v[192:195], v[20:23]
	v_mfma_f32_16x16x32_bf16 v[40:43], v[170:173], v[188:191], v[40:43]
	v_mfma_f32_16x16x32_bf16 v[40:43], v[174:177], v[192:195], v[40:43]
	v_mfma_f32_16x16x32_bf16 v[88:91], v[170:173], v[196:199], v[88:91]
	v_mfma_f32_16x16x32_bf16 v[88:91], v[174:177], v[200:203], v[88:91]
	v_mfma_f32_16x16x32_bf16 v[84:87], v[170:173], v[204:207], v[84:87]
	v_mfma_f32_16x16x32_bf16 v[84:87], v[174:177], v[230:233], v[84:87]
	v_mfma_f32_16x16x32_bf16 v[36:39], v[170:173], v[234:237], v[36:39]
	v_mfma_f32_16x16x32_bf16 v[36:39], v[174:177], v[238:241], v[36:39]
	v_mfma_f32_16x16x32_bf16 v[32:35], v[178:181], v[234:237], v[32:35]
	v_mfma_f32_16x16x32_bf16 v[32:35], v[184:187], v[238:241], v[32:35]
	v_mfma_f32_16x16x32_bf16 v[80:83], v[178:181], v[204:207], v[80:83]
	v_mfma_f32_16x16x32_bf16 v[80:83], v[184:187], v[230:233], v[80:83]
	v_mfma_f32_16x16x32_bf16 v[92:95], v[178:181], v[196:199], v[92:95]
	v_mfma_f32_16x16x32_bf16 v[92:95], v[184:187], v[200:203], v[92:95]
	v_mfma_f32_16x16x32_bf16 v[44:47], v[178:181], v[188:191], v[44:47]
	v_mfma_f32_16x16x32_bf16 v[44:47], v[184:187], v[192:195], v[44:47]
	s_barrier
	s_add_u32 s38, s38, 0x100
	s_addc_u32 s39, s39, 0
	s_add_u32 s79, s79, 0x100
	s_addc_u32 s80, s80, 0
	s_cmp_ge_u32 s81, s9
	s_mov_b32 s40, s81
	s_cbranch_scc0 .LBB0_294

; #define PG8_STAGE(bufoff, gbase, voff) do { _Pragma("unroll") for (int _i = 0; _i < 2; ++_i) \
;         __builtin_amdgcn_global_load_lds((const unsigned*)((const char*)(gbase) + (voff)[_i]), (PG8_LAS unsigned*)(lds + (bufoff) + ldsw + _i * 8192), 16, 0, 0); } while (0)
; #define PG8_LDA(dst, b, h) do { _Pragma("unroll") for (int m = 0; m < 4; ++m) _Pragma("unroll") for (int k = 0; k < 2; ++k) dst[m][k] = *(const PG8_LAS bf16x8*)(lds + PG8_SA(b, h) + aoff + m * 2048 + k * 1024); } while (0)
; #define PG8_LDB(dst, b, h) do { _Pragma("unroll") for (int n = 0; n < 2; ++n) _Pragma("unroll") for (int k = 0; k < 2; ++k) dst[n][k] = *(const PG8_LAS bf16x8*)(lds + PG8_SB(b, h) + boff + n * 2048 + k * 1024); } while (0)
; #define PG8_MMA(ai, bj, At, Bt) do { __builtin_amdgcn_s_setprio(1); _Pragma("unroll") for (int m = 0; m < 4; ++m) _Pragma("unroll") for (int n = 0; n < 2; ++n) _Pragma("unroll") for (int k = 0; k < 2; ++k) \
;         acc[ai][bj][m][n] = __builtin_amdgcn_mfma_f32_16x16x32_bf16(Bt[n][k], At[m][k], acc[ai][bj][m][n], 0, 0, 0); __builtin_amdgcn_s_setprio(0); } while (0)
; #define PG8_WAIT_V(n) asm volatile("s_waitcnt vmcnt(" #n ")" ::: "memory")
; #define PG8_WAIT_L(n) asm volatile("s_waitcnt lgkmcnt(" #n ")" ::: "memory")
; template <class Epi, class Sched, bool ALIGN_EPI = false, bool SP2 = false>
; __device__ __forceinline__ void gemm_phase(PG8_LAS unsigned char* lds, const Gemm g, const Sched& S, const Epi& E) {
;     ...
;             const bool last = (t == nt - 2);
;             const char* a1 = cA + (size_t)(t + 1) * kstep;
;             const char* a2 = last ? nA : cA + (size_t)(t + 2) * kstep; const char* b2 = last ? nB : cB + (size_t)(t + 2) * kstep;
;             const char* a3 = a2 + kstep; const char* b3 = b2 + kstep;
;             if (last && has_next) S.a_ready(nxt);
;             if constexpr (SP2) {
;             PG8_LDB(B0, 0, 0); PG8_LDB(B1, 0, 1); PG8_SCHED; PG8_LDA(At, 0, 0); PG8_STAGE(PG8_SA(1, 1), a1 + hstep, voffA);
;             PG8_WAIT_V(8); PG8_WAIT_L(0); PG8_BAR; PG8_MMA(0, 0, At, B0); PG8_MMA(0, 1, At, B1); PG8_BAR; PG8_SCHED;
;             PG8_LDA(At, 0, 1); PG8_STAGE(PG8_SB(0, 0), b2, voffB); PG8_STAGE(PG8_SB(0, 1), b2 + hstep, voffB); PG8_STAGE(PG8_SA(0, 0), a2, voffA);
;             PG8_WAIT_V(8); PG8_WAIT_L(0); PG8_BAR; PG8_MMA(1, 0, At, B0); PG8_MMA(1, 1, At, B1); PG8_BAR; PG8_SCHED;
.LBB0_365:
	s_add_i32 s88, s86, 2
	s_add_u32 s89, s0, 0x80
	s_addc_u32 s87, s1, 0
	s_cmp_eq_u32 s33, s86
	s_cselect_b32 s87, s3, s87
	s_cselect_b32 s86, s2, s89
	v_add_u32_e32 v0, s19, v230
	s_cselect_b32 vcc_hi, s85, s73
	s_cselect_b32 vcc_lo, s84, s72
	s_add_i32 s89, 0, 0x14000
	ds_read_b128 v[120:123], v0
	ds_read_b128 v[124:127], v0 offset:1024
	ds_read_b128 v[128:131], v0 offset:2048
	ds_read_b128 v[132:135], v0 offset:3072
	v_add_u32_e32 v0, s89, v230
	ds_read_b128 v[136:139], v0
	ds_read_b128 v[140:143], v0 offset:1024
	ds_read_b128 v[162:165], v0 offset:2048
	ds_read_b128 v[166:169], v0 offset:3072
	v_lshl_add_u64 v[144:145], s[0:1], 0, v[184:185]
	s_add_i32 m0, s93, 0xc000
	ds_read_b128 v[170:173], v238
	ds_read_b128 v[188:191], v238 offset:1024
	ds_read_b128 v[192:195], v238 offset:2048
	ds_read_b128 v[196:199], v238 offset:3072
	ds_read_b128 v[200:203], v238 offset:4096
	ds_read_b128 v[204:207], v238 offset:5120
	ds_read_b128 v[242:245], v238 offset:6144
	ds_read_b128 v[246:249], v238 offset:7168
	global_load_lds_dwordx4 v[144:145], off
	v_lshl_add_u64 v[144:145], s[0:1], 0, v[186:187]
	s_add_i32 m0, s93, 0xe000
	s_nop 0
	global_load_lds_dwordx4 v[144:145], off
	s_waitcnt vmcnt(8)
	s_waitcnt lgkmcnt(0)
	s_barrier
	s_waitcnt lgkmcnt(0)
	v_mfma_f32_16x16x32_bf16 v[158:161], v[120:123], v[170:173], v[158:161]
	v_mfma_f32_16x16x32_bf16 v[158:161], v[124:127], v[188:191], v[158:161]
	v_mfma_f32_16x16x32_bf16 v[150:153], v[120:123], v[192:195], v[150:153]
	v_mfma_f32_16x16x32_bf16 v[150:153], v[124:127], v[196:199], v[150:153]
	v_mfma_f32_16x16x32_bf16 v[100:103], v[120:123], v[200:203], v[100:103]
	v_mfma_f32_16x16x32_bf16 v[100:103], v[124:127], v[204:207], v[100:103]
	v_mfma_f32_16x16x32_bf16 v[116:119], v[120:123], v[242:245], v[116:119]
	v_mfma_f32_16x16x32_bf16 v[116:119], v[124:127], v[246:249], v[116:119]
	v_mfma_f32_16x16x32_bf16 v[68:71], v[128:131], v[242:245], v[68:71]
	v_mfma_f32_16x16x32_bf16 v[68:71], v[132:135], v[246:249], v[68:71]
	v_mfma_f32_16x16x32_bf16 v[36:39], v[128:131], v[200:203], v[36:39]
	v_mfma_f32_16x16x32_bf16 v[36:39], v[132:135], v[204:207], v[36:39]
	v_mfma_f32_16x16x32_bf16 v[52:55], v[128:131], v[192:195], v[52:55]
	v_mfma_f32_16x16x32_bf16 v[52:55], v[132:135], v[196:199], v[52:55]
	v_mfma_f32_16x16x32_bf16 v[60:63], v[128:131], v[170:173], v[60:63]
	v_mfma_f32_16x16x32_bf16 v[60:63], v[132:135], v[188:191], v[60:63]
	v_mfma_f32_16x16x32_bf16 v[154:157], v[136:139], v[170:173], v[154:157]
	v_mfma_f32_16x16x32_bf16 v[154:157], v[140:143], v[188:191], v[154:157]
	v_mfma_f32_16x16x32_bf16 v[144:147], v[136:139], v[192:195], v[146:149]
	v_mfma_f32_16x16x32_bf16 v[144:147], v[140:143], v[196:199], v[144:147]
	v_mfma_f32_16x16x32_bf16 v[96:99], v[136:139], v[200:203], v[96:99]
	v_mfma_f32_16x16x32_bf16 v[96:99], v[140:143], v[204:207], v[96:99]
	v_mfma_f32_16x16x32_bf16 v[112:115], v[136:139], v[242:245], v[112:115]
	v_mfma_f32_16x16x32_bf16 v[112:115], v[140:143], v[246:249], v[112:115]
	v_mfma_f32_16x16x32_bf16 v[64:67], v[162:165], v[242:245], v[64:67]
	v_mfma_f32_16x16x32_bf16 v[64:67], v[166:169], v[246:249], v[64:67]
	v_mfma_f32_16x16x32_bf16 v[32:35], v[162:165], v[200:203], v[32:35]
	v_mfma_f32_16x16x32_bf16 v[32:35], v[166:169], v[204:207], v[32:35]
	v_mfma_f32_16x16x32_bf16 v[48:51], v[162:165], v[192:195], v[48:51]
	v_mfma_f32_16x16x32_bf16 v[48:51], v[166:169], v[196:199], v[48:51]
	v_mfma_f32_16x16x32_bf16 v[56:59], v[162:165], v[170:173], v[56:59]
	v_mfma_f32_16x16x32_bf16 v[56:59], v[166:169], v[188:191], v[56:59]
	s_barrier
	s_add_i32 s38, s19, s92
	v_lshl_add_u64 v[174:175], vcc, 0, v[176:177]
	s_mov_b32 m0, s38
	ds_read_b128 v[170:173], v238 offset:16384
	ds_read_b128 v[188:191], v238 offset:17408
	ds_read_b128 v[192:195], v238 offset:18432
	ds_read_b128 v[196:199], v238 offset:19456
	ds_read_b128 v[200:203], v238 offset:20480
	ds_read_b128 v[204:207], v238 offset:21504
	ds_read_b128 v[242:245], v238 offset:22528
	ds_read_b128 v[246:249], v238 offset:23552
	global_load_lds_dwordx4 v[174:175], off
	s_add_i32 m0, s38, 0x2000
	v_lshl_add_u64 v[208:209], vcc, 0, v[180:181]
	s_add_u32 vcc_lo, vcc_lo, s48
	s_addc_u32 vcc_hi, vcc_hi, s49
	s_add_i32 s38, s89, s92
	global_load_lds_dwordx4 v[208:209], off
	v_lshl_add_u64 v[216:217], vcc, 0, v[176:177]
	s_mov_b32 m0, s38
	v_lshl_add_u64 v[224:225], vcc, 0, v[180:181]
	global_load_lds_dwordx4 v[216:217], off
	s_add_i32 m0, s38, 0x2000
	v_lshl_add_u64 v[226:227], s[86:87], 0, v[2:3]
	global_load_lds_dwordx4 v[224:225], off
	s_mov_b32 m0, s93
	v_lshl_add_u64 v[228:229], s[86:87], 0, v[178:179]
	global_load_lds_dwordx4 v[226:227], off
	s_mov_b32 m0, s94
	s_nop 0
	global_load_lds_dwordx4 v[228:229], off
	s_waitcnt vmcnt(8)
	s_waitcnt lgkmcnt(0)
	s_barrier
; #define PG8_STAGE(bufoff, gbase, voff) do { _Pragma("unroll") for (int _i = 0; _i < 2; ++_i) \
;         __builtin_amdgcn_global_load_lds((const unsigned*)((const char*)(gbase) + (voff)[_i]), (PG8_LAS unsigned*)(lds + (bufoff) + ldsw + _i * 8192), 16, 0, 0); } while (0)
; #define PG8_LDA(dst, b, h) do { _Pragma("unroll") for (int m = 0; m < 4; ++m) _Pragma("unroll") for (int k = 0; k < 2; ++k) dst[m][k] = *(const PG8_LAS bf16x8*)(lds + PG8_SA(b, h) + aoff + m * 2048 + k * 1024); } while (0)
; #define PG8_LDB(dst, b, h) do { _Pragma("unroll") for (int n = 0; n < 2; ++n) _Pragma("unroll") for (int k = 0; k < 2; ++k) dst[n][k] = *(const PG8_LAS bf16x8*)(lds + PG8_SB(b, h) + boff + n * 2048 + k * 1024); } while (0)
; #define PG8_MMA(ai, bj, At, Bt) do { __builtin_amdgcn_s_setprio(1); _Pragma("unroll") for (int m = 0; m < 4; ++m) _Pragma("unroll") for (int n = 0; n < 2; ++n) _Pragma("unroll") for (int k = 0; k < 2; ++k) \
;         acc[ai][bj][m][n] = __builtin_amdgcn_mfma_f32_16x16x32_bf16(Bt[n][k], At[m][k], acc[ai][bj][m][n], 0, 0, 0); __builtin_amdgcn_s_setprio(0); } while (0)
; #define PG8_WAIT_V(n) asm volatile("s_waitcnt vmcnt(" #n ")" ::: "memory")
; #define PG8_WAIT_L(n) asm volatile("s_waitcnt lgkmcnt(" #n ")" ::: "memory")
; #define PG8_BAR __builtin_amdgcn_s_barrier()
; #define PG8_SCHED __builtin_amdgcn_sched_barrier(0)
; template <class Epi, class Sched, bool ALIGN_EPI = false, bool SP2 = false>
; __device__ __forceinline__ void gemm_phase(PG8_LAS unsigned char* lds, const Gemm g, const Sched& S, const Epi& E) {
;     ...
;             PG8_WAIT_V(8); PG8_WAIT_L(0); PG8_BAR; PG8_MMA(1, 0, At, B0); PG8_MMA(1, 1, At, B1); PG8_BAR; PG8_SCHED;
;             PG8_LDB(B0, 1, 0); PG8_LDB(B1, 1, 1); PG8_SCHED; PG8_LDA(At, 1, 0); PG8_STAGE(PG8_SA(0, 1), a2 + hstep, voffA);
;             PG8_WAIT_V(8); PG8_WAIT_L(0); PG8_BAR; PG8_MMA(0, 0, At, B0); PG8_MMA(0, 1, At, B1); PG8_BAR; PG8_SCHED;
	s_waitcnt lgkmcnt(0)
	v_mfma_f32_16x16x32_bf16 v[92:95], v[120:123], v[170:173], v[92:95]
	v_mfma_f32_16x16x32_bf16 v[92:95], v[124:127], v[188:191], v[92:95]
	v_mfma_f32_16x16x32_bf16 v[84:87], v[120:123], v[192:195], v[84:87]
	v_mfma_f32_16x16x32_bf16 v[84:87], v[124:127], v[196:199], v[84:87]
	v_mfma_f32_16x16x32_bf16 v[76:79], v[120:123], v[200:203], v[76:79]
	v_mfma_f32_16x16x32_bf16 v[76:79], v[124:127], v[204:207], v[76:79]
	v_mfma_f32_16x16x32_bf16 v[108:111], v[120:123], v[242:245], v[108:111]
	v_mfma_f32_16x16x32_bf16 v[108:111], v[124:127], v[246:249], v[108:111]
	v_mfma_f32_16x16x32_bf16 v[44:47], v[128:131], v[242:245], v[44:47]
	v_mfma_f32_16x16x32_bf16 v[44:47], v[132:135], v[246:249], v[44:47]
	v_mfma_f32_16x16x32_bf16 v[12:15], v[128:131], v[200:203], v[12:15]
	v_mfma_f32_16x16x32_bf16 v[12:15], v[132:135], v[204:207], v[12:15]
	v_mfma_f32_16x16x32_bf16 v[20:23], v[128:131], v[192:195], v[20:23]
	v_mfma_f32_16x16x32_bf16 v[20:23], v[132:135], v[196:199], v[20:23]
	v_mfma_f32_16x16x32_bf16 v[28:31], v[128:131], v[170:173], v[28:31]
	v_mfma_f32_16x16x32_bf16 v[28:31], v[132:135], v[188:191], v[28:31]
	v_mfma_f32_16x16x32_bf16 v[88:91], v[136:139], v[170:173], v[88:91]
	v_mfma_f32_16x16x32_bf16 v[88:91], v[140:143], v[188:191], v[88:91]
	v_mfma_f32_16x16x32_bf16 v[80:83], v[136:139], v[192:195], v[80:83]
	v_mfma_f32_16x16x32_bf16 v[80:83], v[140:143], v[196:199], v[80:83]
	v_mfma_f32_16x16x32_bf16 v[72:75], v[136:139], v[200:203], v[72:75]
	v_mfma_f32_16x16x32_bf16 v[72:75], v[140:143], v[204:207], v[72:75]
	v_mfma_f32_16x16x32_bf16 v[104:107], v[136:139], v[242:245], v[104:107]
	v_mfma_f32_16x16x32_bf16 v[104:107], v[140:143], v[246:249], v[104:107]
	v_mfma_f32_16x16x32_bf16 v[40:43], v[162:165], v[242:245], v[40:43]
	v_mfma_f32_16x16x32_bf16 v[40:43], v[166:169], v[246:249], v[40:43]
	v_mfma_f32_16x16x32_bf16 v[8:11], v[162:165], v[200:203], v[8:11]
	v_mfma_f32_16x16x32_bf16 v[8:11], v[166:169], v[204:207], v[8:11]
	v_mfma_f32_16x16x32_bf16 v[16:19], v[162:165], v[192:195], v[16:19]
	v_mfma_f32_16x16x32_bf16 v[16:19], v[166:169], v[196:199], v[16:19]
	v_mfma_f32_16x16x32_bf16 v[24:27], v[162:165], v[170:173], v[24:27]
	v_mfma_f32_16x16x32_bf16 v[24:27], v[166:169], v[188:191], v[24:27]
	s_barrier
	v_add_u32_e32 v0, s91, v230
	s_add_i32 s38, 0, 0x1c000
	ds_read_b128 v[120:123], v0
	ds_read_b128 v[124:127], v0 offset:1024
	ds_read_b128 v[128:131], v0 offset:2048
	ds_read_b128 v[132:135], v0 offset:3072
	v_add_u32_e32 v0, s38, v230
	ds_read_b128 v[136:139], v0
	ds_read_b128 v[140:143], v0 offset:1024
	ds_read_b128 v[162:165], v0 offset:2048
	ds_read_b128 v[166:169], v0 offset:3072
	s_add_u32 s86, s86, s48
	s_addc_u32 s87, s87, s49
	s_mov_b32 m0, s95
	v_lshl_add_u64 v[148:149], s[86:87], 0, v[2:3]
	ds_read_b128 v[170:173], v238 offset:32768
	ds_read_b128 v[188:191], v238 offset:33792
	ds_read_b128 v[192:195], v238 offset:34816
	ds_read_b128 v[196:199], v238 offset:35840
	ds_read_b128 v[200:203], v238 offset:36864
	ds_read_b128 v[204:207], v238 offset:37888
	ds_read_b128 v[242:245], v238 offset:38912
	ds_read_b128 v[246:249], v238 offset:39936
	global_load_lds_dwordx4 v[148:149], off
	v_lshl_add_u64 v[148:149], s[86:87], 0, v[178:179]
	s_mov_b32 m0, s96
	s_nop 0
	global_load_lds_dwordx4 v[148:149], off
	s_waitcnt vmcnt(8)
	s_waitcnt lgkmcnt(0)
	s_barrier
	s_waitcnt lgkmcnt(0)
	v_mfma_f32_16x16x32_bf16 v[158:161], v[120:123], v[170:173], v[158:161]
	v_mfma_f32_16x16x32_bf16 v[158:161], v[124:127], v[188:191], v[158:161]
	v_mfma_f32_16x16x32_bf16 v[148:151], v[120:123], v[192:195], v[150:153]
	v_mfma_f32_16x16x32_bf16 v[150:153], v[124:127], v[196:199], v[148:151]
	v_mfma_f32_16x16x32_bf16 v[100:103], v[120:123], v[200:203], v[100:103]
	v_mfma_f32_16x16x32_bf16 v[100:103], v[124:127], v[204:207], v[100:103]
	v_mfma_f32_16x16x32_bf16 v[116:119], v[120:123], v[242:245], v[116:119]
	v_mfma_f32_16x16x32_bf16 v[116:119], v[124:127], v[246:249], v[116:119]
	v_mfma_f32_16x16x32_bf16 v[68:71], v[128:131], v[242:245], v[68:71]
	v_mfma_f32_16x16x32_bf16 v[68:71], v[132:135], v[246:249], v[68:71]
	v_mfma_f32_16x16x32_bf16 v[36:39], v[128:131], v[200:203], v[36:39]
	v_mfma_f32_16x16x32_bf16 v[36:39], v[132:135], v[204:207], v[36:39]
	v_mfma_f32_16x16x32_bf16 v[52:55], v[128:131], v[192:195], v[52:55]
	v_mfma_f32_16x16x32_bf16 v[52:55], v[132:135], v[196:199], v[52:55]
	v_mfma_f32_16x16x32_bf16 v[60:63], v[128:131], v[170:173], v[60:63]
	v_mfma_f32_16x16x32_bf16 v[60:63], v[132:135], v[188:191], v[60:63]
	v_mfma_f32_16x16x32_bf16 v[154:157], v[136:139], v[170:173], v[154:157]
	v_mfma_f32_16x16x32_bf16 v[154:157], v[140:143], v[188:191], v[154:157]
	v_mfma_f32_16x16x32_bf16 v[144:147], v[136:139], v[192:195], v[144:147]
	v_mfma_f32_16x16x32_bf16 v[146:149], v[140:143], v[196:199], v[144:147]
	v_mfma_f32_16x16x32_bf16 v[96:99], v[136:139], v[200:203], v[96:99]
	v_mfma_f32_16x16x32_bf16 v[96:99], v[140:143], v[204:207], v[96:99]
	v_mfma_f32_16x16x32_bf16 v[112:115], v[136:139], v[242:245], v[112:115]
	v_mfma_f32_16x16x32_bf16 v[112:115], v[140:143], v[246:249], v[112:115]
	v_mfma_f32_16x16x32_bf16 v[64:67], v[162:165], v[242:245], v[64:67]
	v_mfma_f32_16x16x32_bf16 v[64:67], v[166:169], v[246:249], v[64:67]
	v_mfma_f32_16x16x32_bf16 v[32:35], v[162:165], v[200:203], v[32:35]
	v_mfma_f32_16x16x32_bf16 v[32:35], v[166:169], v[204:207], v[32:35]
	v_mfma_f32_16x16x32_bf16 v[48:51], v[162:165], v[192:195], v[48:51]
	v_mfma_f32_16x16x32_bf16 v[48:51], v[166:169], v[196:199], v[48:51]
	v_mfma_f32_16x16x32_bf16 v[56:59], v[162:165], v[170:173], v[56:59]
	v_mfma_f32_16x16x32_bf16 v[56:59], v[166:169], v[188:191], v[56:59]
	s_barrier
; #define PG8_STAGE(bufoff, gbase, voff) do { _Pragma("unroll") for (int _i = 0; _i < 2; ++_i) \
;         __builtin_amdgcn_global_load_lds((const unsigned*)((const char*)(gbase) + (voff)[_i]), (PG8_LAS unsigned*)(lds + (bufoff) + ldsw + _i * 8192), 16, 0, 0); } while (0)
; #define PG8_LDA(dst, b, h) do { _Pragma("unroll") for (int m = 0; m < 4; ++m) _Pragma("unroll") for (int k = 0; k < 2; ++k) dst[m][k] = *(const PG8_LAS bf16x8*)(lds + PG8_SA(b, h) + aoff + m * 2048 + k * 1024); } while (0)
; #define PG8_MMA(ai, bj, At, Bt) do { __builtin_amdgcn_s_setprio(1); _Pragma("unroll") for (int m = 0; m < 4; ++m) _Pragma("unroll") for (int n = 0; n < 2; ++n) _Pragma("unroll") for (int k = 0; k < 2; ++k) \
;         acc[ai][bj][m][n] = __builtin_amdgcn_mfma_f32_16x16x32_bf16(Bt[n][k], At[m][k], acc[ai][bj][m][n], 0, 0, 0); __builtin_amdgcn_s_setprio(0); } while (0)
; #define PG8_WAIT_V(n) asm volatile("s_waitcnt vmcnt(" #n ")" ::: "memory")
; #define PG8_WAIT_L(n) asm volatile("s_waitcnt lgkmcnt(" #n ")" ::: "memory")
; #define PG8_BAR __builtin_amdgcn_s_barrier()
; #define PG8_SCHED __builtin_amdgcn_sched_barrier(0)
; template <class Epi, class Sched, bool ALIGN_EPI = false, bool SP2 = false>
; __device__ __forceinline__ void gemm_phase(PG8_LAS unsigned char* lds, const Gemm g, const Sched& S, const Epi& E) {
;     ...
;         for (int t = 0; t < nt; t += 2) {
;             if constexpr (Epi::KHOOK) { if ((t & 7) == 0 && t != 0) E.khook(acc, t >> 3, wr, fr, lds); }
;             const bool last = (t == nt - 2);
;             const char* a1 = cA + (size_t)(t + 1) * kstep;
;             const char* a2 = last ? nA : cA + (size_t)(t + 2) * kstep; const char* b2 = last ? nB : cB + (size_t)(t + 2) * kstep;
;     ...
;             PG8_LDA(At, 1, 1); PG8_STAGE(PG8_SB(1, 0), b3, voffB); PG8_STAGE(PG8_SB(1, 1), b3 + hstep, voffB); PG8_STAGE(PG8_SA(1, 0), a3, voffA);
;             PG8_WAIT_V(8); PG8_WAIT_L(0); PG8_BAR; PG8_MMA(1, 0, At, B0); PG8_MMA(1, 1, At, B1); PG8_BAR; PG8_SCHED;
	s_add_i32 s39, s91, s92
	v_lshl_add_u64 v[144:145], v[174:175], 0, s[24:25]
	s_mov_b32 m0, s39
	ds_read_b128 v[170:173], v238 offset:49152
	ds_read_b128 v[188:191], v238 offset:50176
	ds_read_b128 v[192:195], v238 offset:51200
	ds_read_b128 v[196:199], v238 offset:52224
	ds_read_b128 v[200:203], v238 offset:53248
	ds_read_b128 v[204:207], v238 offset:54272
	ds_read_b128 v[242:245], v238 offset:55296
	ds_read_b128 v[246:249], v238 offset:56320
	global_load_lds_dwordx4 v[144:145], off
	v_lshl_add_u64 v[144:145], v[208:209], 0, s[24:25]
	s_add_i32 m0, s39, 0x2000
	s_add_i32 s38, s38, s92
	global_load_lds_dwordx4 v[144:145], off
	v_lshl_add_u64 v[144:145], v[216:217], 0, s[24:25]
	s_mov_b32 m0, s38
	s_nop 0
	global_load_lds_dwordx4 v[144:145], off
	v_lshl_add_u64 v[144:145], v[224:225], 0, s[24:25]
	s_add_i32 m0, s38, 0x2000
	s_nop 0
	global_load_lds_dwordx4 v[144:145], off
	v_lshl_add_u64 v[144:145], v[226:227], 0, s[24:25]
	s_mov_b32 m0, s10
	s_nop 0
	global_load_lds_dwordx4 v[144:145], off
	v_lshl_add_u64 v[144:145], v[228:229], 0, s[24:25]
	s_mov_b32 m0, s11
	s_nop 0
	global_load_lds_dwordx4 v[144:145], off
	s_waitcnt vmcnt(8)
	s_waitcnt lgkmcnt(0)
	s_barrier
	s_waitcnt lgkmcnt(0)
	v_mfma_f32_16x16x32_bf16 v[92:95], v[120:123], v[170:173], v[92:95]
	v_mfma_f32_16x16x32_bf16 v[92:95], v[124:127], v[188:191], v[92:95]
	v_mfma_f32_16x16x32_bf16 v[84:87], v[120:123], v[192:195], v[84:87]
	v_mfma_f32_16x16x32_bf16 v[84:87], v[124:127], v[196:199], v[84:87]
	v_mfma_f32_16x16x32_bf16 v[76:79], v[120:123], v[200:203], v[76:79]
	v_mfma_f32_16x16x32_bf16 v[76:79], v[124:127], v[204:207], v[76:79]
	v_mfma_f32_16x16x32_bf16 v[108:111], v[120:123], v[242:245], v[108:111]
	v_mfma_f32_16x16x32_bf16 v[108:111], v[124:127], v[246:249], v[108:111]
	v_mfma_f32_16x16x32_bf16 v[44:47], v[128:131], v[242:245], v[44:47]
	v_mfma_f32_16x16x32_bf16 v[44:47], v[132:135], v[246:249], v[44:47]
	v_mfma_f32_16x16x32_bf16 v[12:15], v[128:131], v[200:203], v[12:15]
	v_mfma_f32_16x16x32_bf16 v[12:15], v[132:135], v[204:207], v[12:15]
	v_mfma_f32_16x16x32_bf16 v[20:23], v[128:131], v[192:195], v[20:23]
	v_mfma_f32_16x16x32_bf16 v[20:23], v[132:135], v[196:199], v[20:23]
	v_mfma_f32_16x16x32_bf16 v[28:31], v[128:131], v[170:173], v[28:31]
	v_mfma_f32_16x16x32_bf16 v[28:31], v[132:135], v[188:191], v[28:31]
	v_mfma_f32_16x16x32_bf16 v[88:91], v[136:139], v[170:173], v[88:91]
	v_mfma_f32_16x16x32_bf16 v[88:91], v[140:143], v[188:191], v[88:91]
	v_mfma_f32_16x16x32_bf16 v[80:83], v[136:139], v[192:195], v[80:83]
	v_mfma_f32_16x16x32_bf16 v[80:83], v[140:143], v[196:199], v[80:83]
	v_mfma_f32_16x16x32_bf16 v[72:75], v[136:139], v[200:203], v[72:75]
	v_mfma_f32_16x16x32_bf16 v[72:75], v[140:143], v[204:207], v[72:75]
	v_mfma_f32_16x16x32_bf16 v[104:107], v[136:139], v[242:245], v[104:107]
	v_mfma_f32_16x16x32_bf16 v[104:107], v[140:143], v[246:249], v[104:107]
	v_mfma_f32_16x16x32_bf16 v[40:43], v[162:165], v[242:245], v[40:43]
	v_mfma_f32_16x16x32_bf16 v[40:43], v[166:169], v[246:249], v[40:43]
	v_mfma_f32_16x16x32_bf16 v[8:11], v[162:165], v[200:203], v[8:11]
	v_mfma_f32_16x16x32_bf16 v[8:11], v[166:169], v[204:207], v[8:11]
	v_mfma_f32_16x16x32_bf16 v[16:19], v[162:165], v[192:195], v[16:19]
	v_mfma_f32_16x16x32_bf16 v[16:19], v[166:169], v[196:199], v[16:19]
	v_mfma_f32_16x16x32_bf16 v[24:27], v[162:165], v[170:173], v[24:27]
	v_mfma_f32_16x16x32_bf16 v[24:27], v[166:169], v[188:191], v[24:27]
	s_barrier
	s_add_u32 s0, s0, 0x100
	s_addc_u32 s1, s1, 0
	s_add_u32 s72, s72, 0x100
	s_addc_u32 s73, s73, 0
	s_cmp_ge_u32 s88, s9
	s_mov_b32 s86, s88
	s_cbranch_scc0 .LBB0_365

; #define PG8_STAGE(bufoff, gbase, voff) do { _Pragma("unroll") for (int _i = 0; _i < 2; ++_i) \
;         __builtin_amdgcn_global_load_lds((const unsigned*)((const char*)(gbase) + (voff)[_i]), (PG8_LAS unsigned*)(lds + (bufoff) + ldsw + _i * 8192), 16, 0, 0); } while (0)
; #define PG8_LDA(dst, b, h) do { _Pragma("unroll") for (int m = 0; m < 4; ++m) _Pragma("unroll") for (int k = 0; k < 2; ++k) dst[m][k] = *(const PG8_LAS bf16x8*)(lds + PG8_SA(b, h) + aoff + m * 2048 + k * 1024); } while (0)
; #define PG8_LDB(dst, b, h) do { _Pragma("unroll") for (int n = 0; n < 2; ++n) _Pragma("unroll") for (int k = 0; k < 2; ++k) dst[n][k] = *(const PG8_LAS bf16x8*)(lds + PG8_SB(b, h) + boff + n * 2048 + k * 1024); } while (0)
; #define PG8_MMA(ai, bj, At, Bt) do { __builtin_amdgcn_s_setprio(1); _Pragma("unroll") for (int m = 0; m < 4; ++m) _Pragma("unroll") for (int n = 0; n < 2; ++n) _Pragma("unroll") for (int k = 0; k < 2; ++k) \
;         acc[ai][bj][m][n] = __builtin_amdgcn_mfma_f32_16x16x32_bf16(Bt[n][k], At[m][k], acc[ai][bj][m][n], 0, 0, 0); __builtin_amdgcn_s_setprio(0); } while (0)
; #define PG8_WAIT_V(n) asm volatile("s_waitcnt vmcnt(" #n ")" ::: "memory")
; #define PG8_WAIT_L(n) asm volatile("s_waitcnt lgkmcnt(" #n ")" ::: "memory")
; template <class Epi, class Sched, bool ALIGN_EPI = false, bool SP2 = false>
; __device__ __forceinline__ void gemm_phase(PG8_LAS unsigned char* lds, const Gemm g, const Sched& S, const Epi& E) {
;     ...
;             const bool last = (t == nt - 2);
;             const char* a1 = cA + (size_t)(t + 1) * kstep;
;             const char* a2 = last ? nA : cA + (size_t)(t + 2) * kstep; const char* b2 = last ? nB : cB + (size_t)(t + 2) * kstep;
;             const char* a3 = a2 + kstep; const char* b3 = b2 + kstep;
;             if (last && has_next) S.a_ready(nxt);
;             if constexpr (SP2) {
;             PG8_LDB(B0, 0, 0); PG8_LDB(B1, 0, 1); PG8_SCHED; PG8_LDA(At, 0, 0); PG8_STAGE(PG8_SA(1, 1), a1 + hstep, voffA);
;             PG8_WAIT_V(8); PG8_WAIT_L(0); PG8_BAR; PG8_MMA(0, 0, At, B0); PG8_MMA(0, 1, At, B1); PG8_BAR; PG8_SCHED;
;             PG8_LDA(At, 0, 1); PG8_STAGE(PG8_SB(0, 0), b2, voffB); PG8_STAGE(PG8_SB(0, 1), b2 + hstep, voffB); PG8_STAGE(PG8_SA(0, 0), a2, voffA);
;             PG8_WAIT_V(8); PG8_WAIT_L(0); PG8_BAR; PG8_MMA(1, 0, At, B0); PG8_MMA(1, 1, At, B1); PG8_BAR; PG8_SCHED;
.LBB0_468:
	s_add_i32 s78, s38, 2
	s_add_u32 s79, s0, 0x80
	s_addc_u32 s39, s1, 0
	s_cmp_eq_u32 s33, s38
	s_cselect_b32 s39, s7, s39
	s_cselect_b32 s38, s6, s79
	s_cselect_b32 s81, s23, s41
	s_cselect_b32 s80, s22, s40
	s_add_i32 s79, 0, 0x14000
	v_add_u32_e32 v148, s19, v162
	v_add_u32_e32 v171, s79, v162
	ds_read_b128 v[136:139], v148
	ds_read_b128 v[140:143], v148 offset:1024
	ds_read_b128 v[144:147], v148 offset:2048
	ds_read_b128 v[148:151], v148 offset:3072
	ds_read_b128 v[172:175], v171
	ds_read_b128 v[176:179], v171 offset:1024
	ds_read_b128 v[184:187], v171 offset:2048
	ds_read_b128 v[188:191], v171 offset:3072
	v_lshl_add_u64 v[180:181], s[0:1], 0, v[158:159]
	s_add_i32 m0, s46, 0xc000
	ds_read_b128 v[192:195], v167
	ds_read_b128 v[196:199], v167 offset:1024
	ds_read_b128 v[200:203], v167 offset:2048
	ds_read_b128 v[204:207], v167 offset:3072
	ds_read_b128 v[230:233], v167 offset:4096
	ds_read_b128 v[234:237], v167 offset:5120
	ds_read_b128 v[238:241], v167 offset:6144
	ds_read_b128 v[242:245], v167 offset:7168
	global_load_lds_dwordx4 v[180:181], off
	v_lshl_add_u64 v[180:181], s[0:1], 0, v[160:161]
	s_add_i32 m0, s46, 0xe000
	s_nop 0
	global_load_lds_dwordx4 v[180:181], off
	s_waitcnt vmcnt(8)
	s_waitcnt lgkmcnt(0)
	s_barrier
	s_waitcnt lgkmcnt(0)
	v_mfma_f32_16x16x32_bf16 v[132:135], v[136:139], v[192:195], v[132:135]
	v_mfma_f32_16x16x32_bf16 v[132:135], v[140:143], v[196:199], v[132:135]
	v_mfma_f32_16x16x32_bf16 v[116:119], v[136:139], v[200:203], v[116:119]
	v_mfma_f32_16x16x32_bf16 v[116:119], v[140:143], v[204:207], v[116:119]
	v_mfma_f32_16x16x32_bf16 v[100:103], v[136:139], v[230:233], v[100:103]
	v_mfma_f32_16x16x32_bf16 v[100:103], v[140:143], v[234:237], v[100:103]
	v_mfma_f32_16x16x32_bf16 v[84:87], v[136:139], v[238:241], v[84:87]
	v_mfma_f32_16x16x32_bf16 v[84:87], v[140:143], v[242:245], v[84:87]
	v_mfma_f32_16x16x32_bf16 v[80:83], v[144:147], v[238:241], v[80:83]
	v_mfma_f32_16x16x32_bf16 v[80:83], v[148:151], v[242:245], v[80:83]
	v_mfma_f32_16x16x32_bf16 v[96:99], v[144:147], v[230:233], v[96:99]
	v_mfma_f32_16x16x32_bf16 v[96:99], v[148:151], v[234:237], v[96:99]
	v_mfma_f32_16x16x32_bf16 v[112:115], v[144:147], v[200:203], v[112:115]
	v_mfma_f32_16x16x32_bf16 v[112:115], v[148:151], v[204:207], v[112:115]
	v_mfma_f32_16x16x32_bf16 v[128:131], v[144:147], v[192:195], v[128:131]
	v_mfma_f32_16x16x32_bf16 v[128:131], v[148:151], v[196:199], v[128:131]
	v_mfma_f32_16x16x32_bf16 v[124:127], v[172:175], v[192:195], v[124:127]
	v_mfma_f32_16x16x32_bf16 v[124:127], v[176:179], v[196:199], v[124:127]
	v_mfma_f32_16x16x32_bf16 v[108:111], v[172:175], v[200:203], v[108:111]
	v_mfma_f32_16x16x32_bf16 v[108:111], v[176:179], v[204:207], v[108:111]
	v_mfma_f32_16x16x32_bf16 v[92:95], v[172:175], v[230:233], v[92:95]
	v_mfma_f32_16x16x32_bf16 v[92:95], v[176:179], v[234:237], v[92:95]
	v_mfma_f32_16x16x32_bf16 v[76:79], v[172:175], v[238:241], v[76:79]
	v_mfma_f32_16x16x32_bf16 v[76:79], v[176:179], v[242:245], v[76:79]
	v_mfma_f32_16x16x32_bf16 v[72:75], v[184:187], v[238:241], v[72:75]
	v_mfma_f32_16x16x32_bf16 v[72:75], v[188:191], v[242:245], v[72:75]
	v_mfma_f32_16x16x32_bf16 v[88:91], v[184:187], v[230:233], v[88:91]
	v_mfma_f32_16x16x32_bf16 v[88:91], v[188:191], v[234:237], v[88:91]
	v_mfma_f32_16x16x32_bf16 v[104:107], v[184:187], v[200:203], v[104:107]
	v_mfma_f32_16x16x32_bf16 v[104:107], v[188:191], v[204:207], v[104:107]
	v_mfma_f32_16x16x32_bf16 v[120:123], v[184:187], v[192:195], v[120:123]
	v_mfma_f32_16x16x32_bf16 v[120:123], v[188:191], v[196:199], v[120:123]
	s_barrier
	s_add_i32 s82, s19, s42
	v_lshl_add_u64 v[180:181], s[80:81], 0, v[154:155]
	s_mov_b32 m0, s82
	ds_read_b128 v[192:195], v167 offset:16384
	ds_read_b128 v[196:199], v167 offset:17408
	ds_read_b128 v[200:203], v167 offset:18432
	ds_read_b128 v[204:207], v167 offset:19456
	ds_read_b128 v[230:233], v167 offset:20480
	ds_read_b128 v[234:237], v167 offset:21504
	ds_read_b128 v[238:241], v167 offset:22528
	ds_read_b128 v[242:245], v167 offset:23552
	global_load_lds_dwordx4 v[180:181], off
	s_add_i32 m0, s82, 0x2000
	v_lshl_add_u64 v[208:209], s[80:81], 0, v[2:3]
	s_add_u32 s80, s80, s48
	s_addc_u32 s81, s81, s49
	s_add_i32 s79, s79, s42
	global_load_lds_dwordx4 v[208:209], off
	v_lshl_add_u64 v[216:217], s[80:81], 0, v[154:155]
	s_mov_b32 m0, s79
	v_lshl_add_u64 v[224:225], s[80:81], 0, v[2:3]
	global_load_lds_dwordx4 v[216:217], off
	s_add_i32 m0, s79, 0x2000
	v_lshl_add_u64 v[226:227], s[38:39], 0, v[156:157]
	global_load_lds_dwordx4 v[224:225], off
	s_mov_b32 m0, s46
	v_lshl_add_u64 v[246:247], s[38:39], 0, v[152:153]
	global_load_lds_dwordx4 v[226:227], off
	s_mov_b32 m0, s47
	s_nop 0
	global_load_lds_dwordx4 v[246:247], off
	s_waitcnt vmcnt(8)
	s_waitcnt lgkmcnt(0)
	s_barrier
; #define PG8_STAGE(bufoff, gbase, voff) do { _Pragma("unroll") for (int _i = 0; _i < 2; ++_i) \
;         __builtin_amdgcn_global_load_lds((const unsigned*)((const char*)(gbase) + (voff)[_i]), (PG8_LAS unsigned*)(lds + (bufoff) + ldsw + _i * 8192), 16, 0, 0); } while (0)
; #define PG8_LDA(dst, b, h) do { _Pragma("unroll") for (int m = 0; m < 4; ++m) _Pragma("unroll") for (int k = 0; k < 2; ++k) dst[m][k] = *(const PG8_LAS bf16x8*)(lds + PG8_SA(b, h) + aoff + m * 2048 + k * 1024); } while (0)
; #define PG8_LDB(dst, b, h) do { _Pragma("unroll") for (int n = 0; n < 2; ++n) _Pragma("unroll") for (int k = 0; k < 2; ++k) dst[n][k] = *(const PG8_LAS bf16x8*)(lds + PG8_SB(b, h) + boff + n * 2048 + k * 1024); } while (0)
; #define PG8_MMA(ai, bj, At, Bt) do { __builtin_amdgcn_s_setprio(1); _Pragma("unroll") for (int m = 0; m < 4; ++m) _Pragma("unroll") for (int n = 0; n < 2; ++n) _Pragma("unroll") for (int k = 0; k < 2; ++k) \
;         acc[ai][bj][m][n] = __builtin_amdgcn_mfma_f32_16x16x32_bf16(Bt[n][k], At[m][k], acc[ai][bj][m][n], 0, 0, 0); __builtin_amdgcn_s_setprio(0); } while (0)
; #define PG8_WAIT_V(n) asm volatile("s_waitcnt vmcnt(" #n ")" ::: "memory")
; #define PG8_WAIT_L(n) asm volatile("s_waitcnt lgkmcnt(" #n ")" ::: "memory")
; #define PG8_BAR __builtin_amdgcn_s_barrier()
; #define PG8_SCHED __builtin_amdgcn_sched_barrier(0)
; template <class Epi, class Sched, bool ALIGN_EPI = false, bool SP2 = false>
; __device__ __forceinline__ void gemm_phase(PG8_LAS unsigned char* lds, const Gemm g, const Sched& S, const Epi& E) {
;     ...
;             PG8_WAIT_V(8); PG8_WAIT_L(0); PG8_BAR; PG8_MMA(1, 0, At, B0); PG8_MMA(1, 1, At, B1); PG8_BAR; PG8_SCHED;
;             PG8_LDB(B0, 1, 0); PG8_LDB(B1, 1, 1); PG8_SCHED; PG8_LDA(At, 1, 0); PG8_STAGE(PG8_SA(0, 1), a2 + hstep, voffA);
;             PG8_WAIT_V(8); PG8_WAIT_L(0); PG8_BAR; PG8_MMA(0, 0, At, B0); PG8_MMA(0, 1, At, B1); PG8_BAR; PG8_SCHED;
	s_waitcnt lgkmcnt(0)
	v_mfma_f32_16x16x32_bf16 v[68:71], v[136:139], v[192:195], v[68:71]
	v_mfma_f32_16x16x32_bf16 v[68:71], v[140:143], v[196:199], v[68:71]
	v_mfma_f32_16x16x32_bf16 v[52:55], v[136:139], v[200:203], v[52:55]
	v_mfma_f32_16x16x32_bf16 v[52:55], v[140:143], v[204:207], v[52:55]
	v_mfma_f32_16x16x32_bf16 v[36:39], v[136:139], v[230:233], v[36:39]
	v_mfma_f32_16x16x32_bf16 v[36:39], v[140:143], v[234:237], v[36:39]
	v_mfma_f32_16x16x32_bf16 v[20:23], v[136:139], v[238:241], v[20:23]
	v_mfma_f32_16x16x32_bf16 v[20:23], v[140:143], v[242:245], v[20:23]
	v_mfma_f32_16x16x32_bf16 v[16:19], v[144:147], v[238:241], v[16:19]
	v_mfma_f32_16x16x32_bf16 v[16:19], v[148:151], v[242:245], v[16:19]
	v_mfma_f32_16x16x32_bf16 v[32:35], v[144:147], v[230:233], v[32:35]
	v_mfma_f32_16x16x32_bf16 v[32:35], v[148:151], v[234:237], v[32:35]
	v_mfma_f32_16x16x32_bf16 v[48:51], v[144:147], v[200:203], v[48:51]
	v_mfma_f32_16x16x32_bf16 v[48:51], v[148:151], v[204:207], v[48:51]
	v_mfma_f32_16x16x32_bf16 v[64:67], v[144:147], v[192:195], v[64:67]
	v_mfma_f32_16x16x32_bf16 v[64:67], v[148:151], v[196:199], v[64:67]
	v_mfma_f32_16x16x32_bf16 v[60:63], v[172:175], v[192:195], v[60:63]
	v_mfma_f32_16x16x32_bf16 v[60:63], v[176:179], v[196:199], v[60:63]
	v_mfma_f32_16x16x32_bf16 v[44:47], v[172:175], v[200:203], v[44:47]
	v_mfma_f32_16x16x32_bf16 v[44:47], v[176:179], v[204:207], v[44:47]
	v_mfma_f32_16x16x32_bf16 v[28:31], v[172:175], v[230:233], v[28:31]
	v_mfma_f32_16x16x32_bf16 v[28:31], v[176:179], v[234:237], v[28:31]
	v_mfma_f32_16x16x32_bf16 v[12:15], v[172:175], v[238:241], v[12:15]
	v_mfma_f32_16x16x32_bf16 v[12:15], v[176:179], v[242:245], v[12:15]
	v_mfma_f32_16x16x32_bf16 v[8:11], v[184:187], v[238:241], v[8:11]
	v_mfma_f32_16x16x32_bf16 v[8:11], v[188:191], v[242:245], v[8:11]
	v_mfma_f32_16x16x32_bf16 v[24:27], v[184:187], v[230:233], v[24:27]
	v_mfma_f32_16x16x32_bf16 v[24:27], v[188:191], v[234:237], v[24:27]
	v_mfma_f32_16x16x32_bf16 v[40:43], v[184:187], v[200:203], v[40:43]
	v_mfma_f32_16x16x32_bf16 v[40:43], v[188:191], v[204:207], v[40:43]
	v_mfma_f32_16x16x32_bf16 v[56:59], v[184:187], v[192:195], v[56:59]
	v_mfma_f32_16x16x32_bf16 v[56:59], v[188:191], v[196:199], v[56:59]
	s_barrier
	s_add_i32 s79, 0, 0x1c000
	v_add_u32_e32 v148, s91, v162
	v_add_u32_e32 v171, s79, v162
	ds_read_b128 v[136:139], v148
	ds_read_b128 v[140:143], v148 offset:1024
	ds_read_b128 v[144:147], v148 offset:2048
	ds_read_b128 v[148:151], v148 offset:3072
	ds_read_b128 v[172:175], v171
	ds_read_b128 v[176:179], v171 offset:1024
	ds_read_b128 v[184:187], v171 offset:2048
	ds_read_b128 v[188:191], v171 offset:3072
	s_add_u32 s38, s38, s48
	s_addc_u32 s39, s39, s49
	s_mov_b32 m0, s52
	v_lshl_add_u64 v[248:249], s[38:39], 0, v[156:157]
	ds_read_b128 v[192:195], v167 offset:32768
	ds_read_b128 v[196:199], v167 offset:33792
	ds_read_b128 v[200:203], v167 offset:34816
	ds_read_b128 v[204:207], v167 offset:35840
	ds_read_b128 v[230:233], v167 offset:36864
	ds_read_b128 v[234:237], v167 offset:37888
	ds_read_b128 v[238:241], v167 offset:38912
	ds_read_b128 v[242:245], v167 offset:39936
	global_load_lds_dwordx4 v[248:249], off
	v_lshl_add_u64 v[248:249], s[38:39], 0, v[152:153]
	s_mov_b32 m0, s53
	s_nop 0
	global_load_lds_dwordx4 v[248:249], off
	s_waitcnt vmcnt(8)
	s_waitcnt lgkmcnt(0)
	s_barrier
	s_waitcnt lgkmcnt(0)
	v_mfma_f32_16x16x32_bf16 v[132:135], v[136:139], v[192:195], v[132:135]
	v_mfma_f32_16x16x32_bf16 v[132:135], v[140:143], v[196:199], v[132:135]
	v_mfma_f32_16x16x32_bf16 v[116:119], v[136:139], v[200:203], v[116:119]
	v_mfma_f32_16x16x32_bf16 v[116:119], v[140:143], v[204:207], v[116:119]
	v_mfma_f32_16x16x32_bf16 v[100:103], v[136:139], v[230:233], v[100:103]
	v_mfma_f32_16x16x32_bf16 v[100:103], v[140:143], v[234:237], v[100:103]
	v_mfma_f32_16x16x32_bf16 v[84:87], v[136:139], v[238:241], v[84:87]
	v_mfma_f32_16x16x32_bf16 v[84:87], v[140:143], v[242:245], v[84:87]
	v_mfma_f32_16x16x32_bf16 v[80:83], v[144:147], v[238:241], v[80:83]
	v_mfma_f32_16x16x32_bf16 v[80:83], v[148:151], v[242:245], v[80:83]
	v_mfma_f32_16x16x32_bf16 v[96:99], v[144:147], v[230:233], v[96:99]
	v_mfma_f32_16x16x32_bf16 v[96:99], v[148:151], v[234:237], v[96:99]
	v_mfma_f32_16x16x32_bf16 v[112:115], v[144:147], v[200:203], v[112:115]
	v_mfma_f32_16x16x32_bf16 v[112:115], v[148:151], v[204:207], v[112:115]
	v_mfma_f32_16x16x32_bf16 v[128:131], v[144:147], v[192:195], v[128:131]
	v_mfma_f32_16x16x32_bf16 v[128:131], v[148:151], v[196:199], v[128:131]
	v_mfma_f32_16x16x32_bf16 v[124:127], v[172:175], v[192:195], v[124:127]
	v_mfma_f32_16x16x32_bf16 v[124:127], v[176:179], v[196:199], v[124:127]
	v_mfma_f32_16x16x32_bf16 v[108:111], v[172:175], v[200:203], v[108:111]
	v_mfma_f32_16x16x32_bf16 v[108:111], v[176:179], v[204:207], v[108:111]
	v_mfma_f32_16x16x32_bf16 v[92:95], v[172:175], v[230:233], v[92:95]
	v_mfma_f32_16x16x32_bf16 v[92:95], v[176:179], v[234:237], v[92:95]
	v_mfma_f32_16x16x32_bf16 v[76:79], v[172:175], v[238:241], v[76:79]
	v_mfma_f32_16x16x32_bf16 v[76:79], v[176:179], v[242:245], v[76:79]
	v_mfma_f32_16x16x32_bf16 v[72:75], v[184:187], v[238:241], v[72:75]
	v_mfma_f32_16x16x32_bf16 v[72:75], v[188:191], v[242:245], v[72:75]
	v_mfma_f32_16x16x32_bf16 v[88:91], v[184:187], v[230:233], v[88:91]
	v_mfma_f32_16x16x32_bf16 v[88:91], v[188:191], v[234:237], v[88:91]
	v_mfma_f32_16x16x32_bf16 v[104:107], v[184:187], v[200:203], v[104:107]
	v_mfma_f32_16x16x32_bf16 v[104:107], v[188:191], v[204:207], v[104:107]
	v_mfma_f32_16x16x32_bf16 v[120:123], v[184:187], v[192:195], v[120:123]
	v_mfma_f32_16x16x32_bf16 v[120:123], v[188:191], v[196:199], v[120:123]
	s_barrier
; #define PG8_STAGE(bufoff, gbase, voff) do { _Pragma("unroll") for (int _i = 0; _i < 2; ++_i) \
;         __builtin_amdgcn_global_load_lds((const unsigned*)((const char*)(gbase) + (voff)[_i]), (PG8_LAS unsigned*)(lds + (bufoff) + ldsw + _i * 8192), 16, 0, 0); } while (0)
; #define PG8_LDA(dst, b, h) do { _Pragma("unroll") for (int m = 0; m < 4; ++m) _Pragma("unroll") for (int k = 0; k < 2; ++k) dst[m][k] = *(const PG8_LAS bf16x8*)(lds + PG8_SA(b, h) + aoff + m * 2048 + k * 1024); } while (0)
; #define PG8_MMA(ai, bj, At, Bt) do { __builtin_amdgcn_s_setprio(1); _Pragma("unroll") for (int m = 0; m < 4; ++m) _Pragma("unroll") for (int n = 0; n < 2; ++n) _Pragma("unroll") for (int k = 0; k < 2; ++k) \
;         acc[ai][bj][m][n] = __builtin_amdgcn_mfma_f32_16x16x32_bf16(Bt[n][k], At[m][k], acc[ai][bj][m][n], 0, 0, 0); __builtin_amdgcn_s_setprio(0); } while (0)
; #define PG8_WAIT_V(n) asm volatile("s_waitcnt vmcnt(" #n ")" ::: "memory")
; #define PG8_WAIT_L(n) asm volatile("s_waitcnt lgkmcnt(" #n ")" ::: "memory")
; #define PG8_BAR __builtin_amdgcn_s_barrier()
; #define PG8_SCHED __builtin_amdgcn_sched_barrier(0)
; template <class Epi, class Sched, bool ALIGN_EPI = false, bool SP2 = false>
; __device__ __forceinline__ void gemm_phase(PG8_LAS unsigned char* lds, const Gemm g, const Sched& S, const Epi& E) {
;     ...
;         for (int t = 0; t < nt; t += 2) {
;             if constexpr (Epi::KHOOK) { if ((t & 7) == 0 && t != 0) E.khook(acc, t >> 3, wr, fr, lds); }
;             const bool last = (t == nt - 2);
;             const char* a1 = cA + (size_t)(t + 1) * kstep;
;             const char* a2 = last ? nA : cA + (size_t)(t + 2) * kstep; const char* b2 = last ? nB : cB + (size_t)(t + 2) * kstep;
;     ...
;             PG8_LDA(At, 1, 1); PG8_STAGE(PG8_SB(1, 0), b3, voffB); PG8_STAGE(PG8_SB(1, 1), b3 + hstep, voffB); PG8_STAGE(PG8_SA(1, 0), a3, voffA);
;             PG8_WAIT_V(8); PG8_WAIT_L(0); PG8_BAR; PG8_MMA(1, 0, At, B0); PG8_MMA(1, 1, At, B1); PG8_BAR; PG8_SCHED;
	s_add_i32 s38, s91, s42
	v_lshl_add_u64 v[180:181], v[180:181], 0, s[24:25]
	s_mov_b32 m0, s38
	ds_read_b128 v[192:195], v167 offset:49152
	ds_read_b128 v[196:199], v167 offset:50176
	ds_read_b128 v[200:203], v167 offset:51200
	ds_read_b128 v[204:207], v167 offset:52224
	ds_read_b128 v[230:233], v167 offset:53248
	ds_read_b128 v[234:237], v167 offset:54272
	ds_read_b128 v[238:241], v167 offset:55296
	ds_read_b128 v[242:245], v167 offset:56320
	global_load_lds_dwordx4 v[180:181], off
	v_lshl_add_u64 v[180:181], v[208:209], 0, s[24:25]
	s_add_i32 m0, s38, 0x2000
	s_add_i32 s38, s79, s42
	global_load_lds_dwordx4 v[180:181], off
	v_lshl_add_u64 v[180:181], v[216:217], 0, s[24:25]
	s_mov_b32 m0, s38
	s_nop 0
	global_load_lds_dwordx4 v[180:181], off
	v_lshl_add_u64 v[180:181], v[224:225], 0, s[24:25]
	s_add_i32 m0, s38, 0x2000
	s_nop 0
	global_load_lds_dwordx4 v[180:181], off
	v_lshl_add_u64 v[180:181], v[226:227], 0, s[24:25]
	s_mov_b32 m0, s72
	s_nop 0
	global_load_lds_dwordx4 v[180:181], off
	v_lshl_add_u64 v[180:181], v[246:247], 0, s[24:25]
	s_mov_b32 m0, s73
	s_nop 0
	global_load_lds_dwordx4 v[180:181], off
	s_waitcnt vmcnt(8)
	s_waitcnt lgkmcnt(0)
	s_barrier
	s_waitcnt lgkmcnt(0)
	v_mfma_f32_16x16x32_bf16 v[68:71], v[136:139], v[192:195], v[68:71]
	v_mfma_f32_16x16x32_bf16 v[68:71], v[140:143], v[196:199], v[68:71]
	v_mfma_f32_16x16x32_bf16 v[52:55], v[136:139], v[200:203], v[52:55]
	v_mfma_f32_16x16x32_bf16 v[52:55], v[140:143], v[204:207], v[52:55]
	v_mfma_f32_16x16x32_bf16 v[36:39], v[136:139], v[230:233], v[36:39]
	v_mfma_f32_16x16x32_bf16 v[36:39], v[140:143], v[234:237], v[36:39]
	v_mfma_f32_16x16x32_bf16 v[20:23], v[136:139], v[238:241], v[20:23]
	v_mfma_f32_16x16x32_bf16 v[20:23], v[140:143], v[242:245], v[20:23]
	v_mfma_f32_16x16x32_bf16 v[16:19], v[144:147], v[238:241], v[16:19]
	v_mfma_f32_16x16x32_bf16 v[16:19], v[148:151], v[242:245], v[16:19]
	v_mfma_f32_16x16x32_bf16 v[32:35], v[144:147], v[230:233], v[32:35]
	v_mfma_f32_16x16x32_bf16 v[32:35], v[148:151], v[234:237], v[32:35]
	v_mfma_f32_16x16x32_bf16 v[48:51], v[144:147], v[200:203], v[48:51]
	v_mfma_f32_16x16x32_bf16 v[48:51], v[148:151], v[204:207], v[48:51]
	v_mfma_f32_16x16x32_bf16 v[64:67], v[144:147], v[192:195], v[64:67]
	v_mfma_f32_16x16x32_bf16 v[64:67], v[148:151], v[196:199], v[64:67]
	v_mfma_f32_16x16x32_bf16 v[60:63], v[172:175], v[192:195], v[60:63]
	v_mfma_f32_16x16x32_bf16 v[60:63], v[176:179], v[196:199], v[60:63]
	v_mfma_f32_16x16x32_bf16 v[44:47], v[172:175], v[200:203], v[44:47]
	v_mfma_f32_16x16x32_bf16 v[44:47], v[176:179], v[204:207], v[44:47]
	v_mfma_f32_16x16x32_bf16 v[28:31], v[172:175], v[230:233], v[28:31]
	v_mfma_f32_16x16x32_bf16 v[28:31], v[176:179], v[234:237], v[28:31]
	v_mfma_f32_16x16x32_bf16 v[12:15], v[172:175], v[238:241], v[12:15]
	v_mfma_f32_16x16x32_bf16 v[12:15], v[176:179], v[242:245], v[12:15]
	v_mfma_f32_16x16x32_bf16 v[8:11], v[184:187], v[238:241], v[8:11]
	v_mfma_f32_16x16x32_bf16 v[8:11], v[188:191], v[242:245], v[8:11]
	v_mfma_f32_16x16x32_bf16 v[24:27], v[184:187], v[230:233], v[24:27]
	v_mfma_f32_16x16x32_bf16 v[24:27], v[188:191], v[234:237], v[24:27]
	v_mfma_f32_16x16x32_bf16 v[40:43], v[184:187], v[200:203], v[40:43]
	v_mfma_f32_16x16x32_bf16 v[40:43], v[188:191], v[204:207], v[40:43]
	v_mfma_f32_16x16x32_bf16 v[56:59], v[184:187], v[192:195], v[56:59]
	v_mfma_f32_16x16x32_bf16 v[56:59], v[188:191], v[196:199], v[56:59]
	s_barrier
	s_add_u32 s0, s0, 0x100
	s_addc_u32 s1, s1, 0
	s_add_u32 s40, s40, 0x100
	s_addc_u32 s41, s41, 0
	s_cmp_ge_u32 s78, s9
	s_mov_b32 s38, s78
	s_cbranch_scc0 .LBB0_468

; #define PG8_STAGE(bufoff, gbase, voff) do { _Pragma("unroll") for (int _i = 0; _i < 2; ++_i) \
;         __builtin_amdgcn_global_load_lds((const unsigned*)((const char*)(gbase) + (voff)[_i]), (PG8_LAS unsigned*)(lds + (bufoff) + ldsw + _i * 8192), 16, 0, 0); } while (0)
; #define PG8_LDA(dst, b, h) do { _Pragma("unroll") for (int m = 0; m < 4; ++m) _Pragma("unroll") for (int k = 0; k < 2; ++k) dst[m][k] = *(const PG8_LAS bf16x8*)(lds + PG8_SA(b, h) + aoff + m * 2048 + k * 1024); } while (0)
; #define PG8_LDB(dst, b, h) do { _Pragma("unroll") for (int n = 0; n < 2; ++n) _Pragma("unroll") for (int k = 0; k < 2; ++k) dst[n][k] = *(const PG8_LAS bf16x8*)(lds + PG8_SB(b, h) + boff + n * 2048 + k * 1024); } while (0)
; #define PG8_MMA(ai, bj, At, Bt) do { __builtin_amdgcn_s_setprio(1); _Pragma("unroll") for (int m = 0; m < 4; ++m) _Pragma("unroll") for (int n = 0; n < 2; ++n) _Pragma("unroll") for (int k = 0; k < 2; ++k) \
;         acc[ai][bj][m][n] = __builtin_amdgcn_mfma_f32_16x16x32_bf16(Bt[n][k], At[m][k], acc[ai][bj][m][n], 0, 0, 0); __builtin_amdgcn_s_setprio(0); } while (0)
; #define PG8_WAIT_V(n) asm volatile("s_waitcnt vmcnt(" #n ")" ::: "memory")
; #define PG8_WAIT_L(n) asm volatile("s_waitcnt lgkmcnt(" #n ")" ::: "memory")
; template <class Epi, class Sched, bool ALIGN_EPI = false, bool SP2 = false>
; __device__ __forceinline__ void gemm_phase(PG8_LAS unsigned char* lds, const Gemm g, const Sched& S, const Epi& E) {
;     ...
;             const bool last = (t == nt - 2);
;             const char* a1 = cA + (size_t)(t + 1) * kstep;
;             const char* a2 = last ? nA : cA + (size_t)(t + 2) * kstep; const char* b2 = last ? nB : cB + (size_t)(t + 2) * kstep;
;             const char* a3 = a2 + kstep; const char* b3 = b2 + kstep;
;             if (last && has_next) S.a_ready(nxt);
;             if constexpr (SP2) {
;             PG8_LDB(B0, 0, 0); PG8_LDB(B1, 0, 1); PG8_SCHED; PG8_LDA(At, 0, 0); PG8_STAGE(PG8_SA(1, 1), a1 + hstep, voffA);
;             PG8_WAIT_V(8); PG8_WAIT_L(0); PG8_BAR; PG8_MMA(0, 0, At, B0); PG8_MMA(0, 1, At, B1); PG8_BAR; PG8_SCHED;
;             PG8_LDA(At, 0, 1); PG8_STAGE(PG8_SB(0, 0), b2, voffB); PG8_STAGE(PG8_SB(0, 1), b2 + hstep, voffB); PG8_STAGE(PG8_SA(0, 0), a2, voffA);
;             PG8_WAIT_V(8); PG8_WAIT_L(0); PG8_BAR; PG8_MMA(1, 0, At, B0); PG8_MMA(1, 1, At, B1); PG8_BAR; PG8_SCHED;
.LBB0_501:
	s_add_i32 s80, s4, 2
	s_add_u32 s81, s0, 0x80
	s_addc_u32 s5, s1, 0
	s_cmp_eq_u32 s33, s4
	s_cselect_b32 s5, s23, s5
	s_cselect_b32 s4, s22, s81
	s_cselect_b32 s83, s41, s43
	s_cselect_b32 s82, s40, s42
	s_add_i32 s81, 0, 0x14000
	v_add_u32_e32 v148, s19, v164
	v_add_u32_e32 v162, s81, v164
	ds_read_b128 v[136:139], v148
	ds_read_b128 v[140:143], v148 offset:1024
	ds_read_b128 v[144:147], v148 offset:2048
	ds_read_b128 v[148:151], v148 offset:3072
	ds_read_b128 v[174:177], v162
	ds_read_b128 v[178:181], v162 offset:1024
	ds_read_b128 v[184:187], v162 offset:2048
	ds_read_b128 v[188:191], v162 offset:3072
	v_lshl_add_u64 v[162:163], s[0:1], 0, v[158:159]
	s_add_i32 m0, s45, 0xc000
	ds_read_b128 v[192:195], v170
	ds_read_b128 v[196:199], v170 offset:1024
	ds_read_b128 v[200:203], v170 offset:2048
	ds_read_b128 v[204:207], v170 offset:3072
	ds_read_b128 v[230:233], v170 offset:4096
	ds_read_b128 v[234:237], v170 offset:5120
	ds_read_b128 v[238:241], v170 offset:6144
	ds_read_b128 v[242:245], v170 offset:7168
	global_load_lds_dwordx4 v[162:163], off
	v_lshl_add_u64 v[162:163], s[0:1], 0, v[160:161]
	s_add_i32 m0, s45, 0xe000
	s_nop 0
	global_load_lds_dwordx4 v[162:163], off
	s_waitcnt vmcnt(8)
	s_waitcnt lgkmcnt(0)
	s_barrier
	s_waitcnt lgkmcnt(0)
	v_mfma_f32_16x16x32_bf16 v[132:135], v[136:139], v[192:195], v[132:135]
	v_mfma_f32_16x16x32_bf16 v[132:135], v[140:143], v[196:199], v[132:135]
	v_mfma_f32_16x16x32_bf16 v[116:119], v[136:139], v[200:203], v[116:119]
	v_mfma_f32_16x16x32_bf16 v[116:119], v[140:143], v[204:207], v[116:119]
	v_mfma_f32_16x16x32_bf16 v[100:103], v[136:139], v[230:233], v[100:103]
	v_mfma_f32_16x16x32_bf16 v[100:103], v[140:143], v[234:237], v[100:103]
	v_mfma_f32_16x16x32_bf16 v[84:87], v[136:139], v[238:241], v[84:87]
	v_mfma_f32_16x16x32_bf16 v[84:87], v[140:143], v[242:245], v[84:87]
	v_mfma_f32_16x16x32_bf16 v[80:83], v[144:147], v[238:241], v[80:83]
	v_mfma_f32_16x16x32_bf16 v[80:83], v[148:151], v[242:245], v[80:83]
	v_mfma_f32_16x16x32_bf16 v[96:99], v[144:147], v[230:233], v[96:99]
	v_mfma_f32_16x16x32_bf16 v[96:99], v[148:151], v[234:237], v[96:99]
	v_mfma_f32_16x16x32_bf16 v[112:115], v[144:147], v[200:203], v[112:115]
	v_mfma_f32_16x16x32_bf16 v[112:115], v[148:151], v[204:207], v[112:115]
	v_mfma_f32_16x16x32_bf16 v[128:131], v[144:147], v[192:195], v[128:131]
	v_mfma_f32_16x16x32_bf16 v[128:131], v[148:151], v[196:199], v[128:131]
	v_mfma_f32_16x16x32_bf16 v[124:127], v[174:177], v[192:195], v[124:127]
	v_mfma_f32_16x16x32_bf16 v[124:127], v[178:181], v[196:199], v[124:127]
	v_mfma_f32_16x16x32_bf16 v[108:111], v[174:177], v[200:203], v[108:111]
	v_mfma_f32_16x16x32_bf16 v[108:111], v[178:181], v[204:207], v[108:111]
	v_mfma_f32_16x16x32_bf16 v[92:95], v[174:177], v[230:233], v[92:95]
	v_mfma_f32_16x16x32_bf16 v[92:95], v[178:181], v[234:237], v[92:95]
	v_mfma_f32_16x16x32_bf16 v[76:79], v[174:177], v[238:241], v[76:79]
	v_mfma_f32_16x16x32_bf16 v[76:79], v[178:181], v[242:245], v[76:79]
	v_mfma_f32_16x16x32_bf16 v[72:75], v[184:187], v[238:241], v[72:75]
	v_mfma_f32_16x16x32_bf16 v[72:75], v[188:191], v[242:245], v[72:75]
	v_mfma_f32_16x16x32_bf16 v[88:91], v[184:187], v[230:233], v[88:91]
	v_mfma_f32_16x16x32_bf16 v[88:91], v[188:191], v[234:237], v[88:91]
	v_mfma_f32_16x16x32_bf16 v[104:107], v[184:187], v[200:203], v[104:107]
	v_mfma_f32_16x16x32_bf16 v[104:107], v[188:191], v[204:207], v[104:107]
	v_mfma_f32_16x16x32_bf16 v[120:123], v[184:187], v[192:195], v[120:123]
	v_mfma_f32_16x16x32_bf16 v[120:123], v[188:191], v[196:199], v[120:123]
	s_barrier
	s_add_i32 s84, s19, s44
	v_lshl_add_u64 v[162:163], s[82:83], 0, v[152:153]
	s_mov_b32 m0, s84
	ds_read_b128 v[192:195], v170 offset:16384
	ds_read_b128 v[196:199], v170 offset:17408
	ds_read_b128 v[200:203], v170 offset:18432
	ds_read_b128 v[204:207], v170 offset:19456
	ds_read_b128 v[230:233], v170 offset:20480
	ds_read_b128 v[234:237], v170 offset:21504
	ds_read_b128 v[238:241], v170 offset:22528
	ds_read_b128 v[242:245], v170 offset:23552
	global_load_lds_dwordx4 v[162:163], off
	s_add_i32 m0, s84, 0x2000
	v_lshl_add_u64 v[208:209], s[82:83], 0, v[156:157]
	s_add_u32 s82, s82, s48
	s_addc_u32 s83, s83, s49
	s_add_i32 s81, s81, s44
	global_load_lds_dwordx4 v[208:209], off
	v_lshl_add_u64 v[246:247], s[82:83], 0, v[152:153]
	s_mov_b32 m0, s81
	v_lshl_add_u64 v[248:249], s[82:83], 0, v[156:157]
	global_load_lds_dwordx4 v[246:247], off
	s_add_i32 m0, s81, 0x2000
	v_lshl_add_u64 v[216:217], s[4:5], 0, v[2:3]
	global_load_lds_dwordx4 v[248:249], off
	s_mov_b32 m0, s45
	v_lshl_add_u64 v[224:225], s[4:5], 0, v[154:155]
	global_load_lds_dwordx4 v[216:217], off
	s_mov_b32 m0, s46
	s_nop 0
	global_load_lds_dwordx4 v[224:225], off
	s_waitcnt vmcnt(8)
	s_waitcnt lgkmcnt(0)
	s_barrier
; #define PG8_STAGE(bufoff, gbase, voff) do { _Pragma("unroll") for (int _i = 0; _i < 2; ++_i) \
;         __builtin_amdgcn_global_load_lds((const unsigned*)((const char*)(gbase) + (voff)[_i]), (PG8_LAS unsigned*)(lds + (bufoff) + ldsw + _i * 8192), 16, 0, 0); } while (0)
; #define PG8_LDA(dst, b, h) do { _Pragma("unroll") for (int m = 0; m < 4; ++m) _Pragma("unroll") for (int k = 0; k < 2; ++k) dst[m][k] = *(const PG8_LAS bf16x8*)(lds + PG8_SA(b, h) + aoff + m * 2048 + k * 1024); } while (0)
; #define PG8_LDB(dst, b, h) do { _Pragma("unroll") for (int n = 0; n < 2; ++n) _Pragma("unroll") for (int k = 0; k < 2; ++k) dst[n][k] = *(const PG8_LAS bf16x8*)(lds + PG8_SB(b, h) + boff + n * 2048 + k * 1024); } while (0)
; #define PG8_MMA(ai, bj, At, Bt) do { __builtin_amdgcn_s_setprio(1); _Pragma("unroll") for (int m = 0; m < 4; ++m) _Pragma("unroll") for (int n = 0; n < 2; ++n) _Pragma("unroll") for (int k = 0; k < 2; ++k) \
;         acc[ai][bj][m][n] = __builtin_amdgcn_mfma_f32_16x16x32_bf16(Bt[n][k], At[m][k], acc[ai][bj][m][n], 0, 0, 0); __builtin_amdgcn_s_setprio(0); } while (0)
; #define PG8_WAIT_V(n) asm volatile("s_waitcnt vmcnt(" #n ")" ::: "memory")
; #define PG8_WAIT_L(n) asm volatile("s_waitcnt lgkmcnt(" #n ")" ::: "memory")
; #define PG8_BAR __builtin_amdgcn_s_barrier()
; #define PG8_SCHED __builtin_amdgcn_sched_barrier(0)
; template <class Epi, class Sched, bool ALIGN_EPI = false, bool SP2 = false>
; __device__ __forceinline__ void gemm_phase(PG8_LAS unsigned char* lds, const Gemm g, const Sched& S, const Epi& E) {
;     ...
;             PG8_WAIT_V(8); PG8_WAIT_L(0); PG8_BAR; PG8_MMA(1, 0, At, B0); PG8_MMA(1, 1, At, B1); PG8_BAR; PG8_SCHED;
;             PG8_LDB(B0, 1, 0); PG8_LDB(B1, 1, 1); PG8_SCHED; PG8_LDA(At, 1, 0); PG8_STAGE(PG8_SA(0, 1), a2 + hstep, voffA);
;             PG8_WAIT_V(8); PG8_WAIT_L(0); PG8_BAR; PG8_MMA(0, 0, At, B0); PG8_MMA(0, 1, At, B1); PG8_BAR; PG8_SCHED;
	s_waitcnt lgkmcnt(0)
	v_mfma_f32_16x16x32_bf16 v[68:71], v[136:139], v[192:195], v[68:71]
	v_mfma_f32_16x16x32_bf16 v[68:71], v[140:143], v[196:199], v[68:71]
	v_mfma_f32_16x16x32_bf16 v[52:55], v[136:139], v[200:203], v[52:55]
	v_mfma_f32_16x16x32_bf16 v[52:55], v[140:143], v[204:207], v[52:55]
	v_mfma_f32_16x16x32_bf16 v[36:39], v[136:139], v[230:233], v[36:39]
	v_mfma_f32_16x16x32_bf16 v[36:39], v[140:143], v[234:237], v[36:39]
	v_mfma_f32_16x16x32_bf16 v[20:23], v[136:139], v[238:241], v[20:23]
	v_mfma_f32_16x16x32_bf16 v[20:23], v[140:143], v[242:245], v[20:23]
	v_mfma_f32_16x16x32_bf16 v[16:19], v[144:147], v[238:241], v[16:19]
	v_mfma_f32_16x16x32_bf16 v[16:19], v[148:151], v[242:245], v[16:19]
	v_mfma_f32_16x16x32_bf16 v[32:35], v[144:147], v[230:233], v[32:35]
	v_mfma_f32_16x16x32_bf16 v[32:35], v[148:151], v[234:237], v[32:35]
	v_mfma_f32_16x16x32_bf16 v[48:51], v[144:147], v[200:203], v[48:51]
	v_mfma_f32_16x16x32_bf16 v[48:51], v[148:151], v[204:207], v[48:51]
	v_mfma_f32_16x16x32_bf16 v[64:67], v[144:147], v[192:195], v[64:67]
	v_mfma_f32_16x16x32_bf16 v[64:67], v[148:151], v[196:199], v[64:67]
	v_mfma_f32_16x16x32_bf16 v[60:63], v[174:177], v[192:195], v[60:63]
	v_mfma_f32_16x16x32_bf16 v[60:63], v[178:181], v[196:199], v[60:63]
	v_mfma_f32_16x16x32_bf16 v[44:47], v[174:177], v[200:203], v[44:47]
	v_mfma_f32_16x16x32_bf16 v[44:47], v[178:181], v[204:207], v[44:47]
	v_mfma_f32_16x16x32_bf16 v[28:31], v[174:177], v[230:233], v[28:31]
	v_mfma_f32_16x16x32_bf16 v[28:31], v[178:181], v[234:237], v[28:31]
	v_mfma_f32_16x16x32_bf16 v[12:15], v[174:177], v[238:241], v[12:15]
	v_mfma_f32_16x16x32_bf16 v[12:15], v[178:181], v[242:245], v[12:15]
	v_mfma_f32_16x16x32_bf16 v[8:11], v[184:187], v[238:241], v[8:11]
	v_mfma_f32_16x16x32_bf16 v[8:11], v[188:191], v[242:245], v[8:11]
	v_mfma_f32_16x16x32_bf16 v[24:27], v[184:187], v[230:233], v[24:27]
	v_mfma_f32_16x16x32_bf16 v[24:27], v[188:191], v[234:237], v[24:27]
	v_mfma_f32_16x16x32_bf16 v[40:43], v[184:187], v[200:203], v[40:43]
	v_mfma_f32_16x16x32_bf16 v[40:43], v[188:191], v[204:207], v[40:43]
	v_mfma_f32_16x16x32_bf16 v[56:59], v[184:187], v[192:195], v[56:59]
	v_mfma_f32_16x16x32_bf16 v[56:59], v[188:191], v[196:199], v[56:59]
	s_barrier
	s_add_i32 s81, 0, 0x1c000
	v_add_u32_e32 v148, s91, v164
	v_add_u32_e32 v173, s81, v164
	ds_read_b128 v[136:139], v148
	ds_read_b128 v[140:143], v148 offset:1024
	ds_read_b128 v[144:147], v148 offset:2048
	ds_read_b128 v[148:151], v148 offset:3072
	ds_read_b128 v[174:177], v173
	ds_read_b128 v[178:181], v173 offset:1024
	ds_read_b128 v[184:187], v173 offset:2048
	ds_read_b128 v[188:191], v173 offset:3072
	s_add_u32 s4, s4, s48
	s_addc_u32 s5, s5, s49
	s_mov_b32 m0, s47
	v_lshl_add_u64 v[226:227], s[4:5], 0, v[2:3]
	ds_read_b128 v[192:195], v170 offset:32768
	ds_read_b128 v[196:199], v170 offset:33792
	ds_read_b128 v[200:203], v170 offset:34816
	ds_read_b128 v[204:207], v170 offset:35840
	ds_read_b128 v[230:233], v170 offset:36864
	ds_read_b128 v[234:237], v170 offset:37888
	ds_read_b128 v[238:241], v170 offset:38912
	ds_read_b128 v[242:245], v170 offset:39936
	global_load_lds_dwordx4 v[226:227], off
	v_lshl_add_u64 v[226:227], s[4:5], 0, v[154:155]
	s_mov_b32 m0, s52
	s_nop 0
	global_load_lds_dwordx4 v[226:227], off
	s_waitcnt vmcnt(8)
	s_waitcnt lgkmcnt(0)
	s_barrier
	s_waitcnt lgkmcnt(0)
	v_mfma_f32_16x16x32_bf16 v[132:135], v[136:139], v[192:195], v[132:135]
	v_mfma_f32_16x16x32_bf16 v[132:135], v[140:143], v[196:199], v[132:135]
	v_mfma_f32_16x16x32_bf16 v[116:119], v[136:139], v[200:203], v[116:119]
	v_mfma_f32_16x16x32_bf16 v[116:119], v[140:143], v[204:207], v[116:119]
	v_mfma_f32_16x16x32_bf16 v[100:103], v[136:139], v[230:233], v[100:103]
	v_mfma_f32_16x16x32_bf16 v[100:103], v[140:143], v[234:237], v[100:103]
	v_mfma_f32_16x16x32_bf16 v[84:87], v[136:139], v[238:241], v[84:87]
	v_mfma_f32_16x16x32_bf16 v[84:87], v[140:143], v[242:245], v[84:87]
	v_mfma_f32_16x16x32_bf16 v[80:83], v[144:147], v[238:241], v[80:83]
	v_mfma_f32_16x16x32_bf16 v[80:83], v[148:151], v[242:245], v[80:83]
	v_mfma_f32_16x16x32_bf16 v[96:99], v[144:147], v[230:233], v[96:99]
	v_mfma_f32_16x16x32_bf16 v[96:99], v[148:151], v[234:237], v[96:99]
	v_mfma_f32_16x16x32_bf16 v[112:115], v[144:147], v[200:203], v[112:115]
	v_mfma_f32_16x16x32_bf16 v[112:115], v[148:151], v[204:207], v[112:115]
	v_mfma_f32_16x16x32_bf16 v[128:131], v[144:147], v[192:195], v[128:131]
	v_mfma_f32_16x16x32_bf16 v[128:131], v[148:151], v[196:199], v[128:131]
	v_mfma_f32_16x16x32_bf16 v[124:127], v[174:177], v[192:195], v[124:127]
	v_mfma_f32_16x16x32_bf16 v[124:127], v[178:181], v[196:199], v[124:127]
	v_mfma_f32_16x16x32_bf16 v[108:111], v[174:177], v[200:203], v[108:111]
	v_mfma_f32_16x16x32_bf16 v[108:111], v[178:181], v[204:207], v[108:111]
	v_mfma_f32_16x16x32_bf16 v[92:95], v[174:177], v[230:233], v[92:95]
	v_mfma_f32_16x16x32_bf16 v[92:95], v[178:181], v[234:237], v[92:95]
	v_mfma_f32_16x16x32_bf16 v[76:79], v[174:177], v[238:241], v[76:79]
	v_mfma_f32_16x16x32_bf16 v[76:79], v[178:181], v[242:245], v[76:79]
	v_mfma_f32_16x16x32_bf16 v[72:75], v[184:187], v[238:241], v[72:75]
	v_mfma_f32_16x16x32_bf16 v[72:75], v[188:191], v[242:245], v[72:75]
	v_mfma_f32_16x16x32_bf16 v[88:91], v[184:187], v[230:233], v[88:91]
	v_mfma_f32_16x16x32_bf16 v[88:91], v[188:191], v[234:237], v[88:91]
	v_mfma_f32_16x16x32_bf16 v[104:107], v[184:187], v[200:203], v[104:107]
	v_mfma_f32_16x16x32_bf16 v[104:107], v[188:191], v[204:207], v[104:107]
	v_mfma_f32_16x16x32_bf16 v[120:123], v[184:187], v[192:195], v[120:123]
	v_mfma_f32_16x16x32_bf16 v[120:123], v[188:191], v[196:199], v[120:123]
	s_barrier
; #define PG8_STAGE(bufoff, gbase, voff) do { _Pragma("unroll") for (int _i = 0; _i < 2; ++_i) \
;         __builtin_amdgcn_global_load_lds((const unsigned*)((const char*)(gbase) + (voff)[_i]), (PG8_LAS unsigned*)(lds + (bufoff) + ldsw + _i * 8192), 16, 0, 0); } while (0)
; #define PG8_LDA(dst, b, h) do { _Pragma("unroll") for (int m = 0; m < 4; ++m) _Pragma("unroll") for (int k = 0; k < 2; ++k) dst[m][k] = *(const PG8_LAS bf16x8*)(lds + PG8_SA(b, h) + aoff + m * 2048 + k * 1024); } while (0)
; #define PG8_MMA(ai, bj, At, Bt) do { __builtin_amdgcn_s_setprio(1); _Pragma("unroll") for (int m = 0; m < 4; ++m) _Pragma("unroll") for (int n = 0; n < 2; ++n) _Pragma("unroll") for (int k = 0; k < 2; ++k) \
;         acc[ai][bj][m][n] = __builtin_amdgcn_mfma_f32_16x16x32_bf16(Bt[n][k], At[m][k], acc[ai][bj][m][n], 0, 0, 0); __builtin_amdgcn_s_setprio(0); } while (0)
; #define PG8_WAIT_V(n) asm volatile("s_waitcnt vmcnt(" #n ")" ::: "memory")
; #define PG8_WAIT_L(n) asm volatile("s_waitcnt lgkmcnt(" #n ")" ::: "memory")
; #define PG8_BAR __builtin_amdgcn_s_barrier()
; #define PG8_SCHED __builtin_amdgcn_sched_barrier(0)
; template <class Epi, class Sched, bool ALIGN_EPI = false, bool SP2 = false>
; __device__ __forceinline__ void gemm_phase(PG8_LAS unsigned char* lds, const Gemm g, const Sched& S, const Epi& E) {
;     ...
;         for (int t = 0; t < nt; t += 2) {
;             if constexpr (Epi::KHOOK) { if ((t & 7) == 0 && t != 0) E.khook(acc, t >> 3, wr, fr, lds); }
;             const bool last = (t == nt - 2);
;             const char* a1 = cA + (size_t)(t + 1) * kstep;
;             const char* a2 = last ? nA : cA + (size_t)(t + 2) * kstep; const char* b2 = last ? nB : cB + (size_t)(t + 2) * kstep;
;     ...
;             PG8_LDA(At, 1, 1); PG8_STAGE(PG8_SB(1, 0), b3, voffB); PG8_STAGE(PG8_SB(1, 1), b3 + hstep, voffB); PG8_STAGE(PG8_SA(1, 0), a3, voffA);
;             PG8_WAIT_V(8); PG8_WAIT_L(0); PG8_BAR; PG8_MMA(1, 0, At, B0); PG8_MMA(1, 1, At, B1); PG8_BAR; PG8_SCHED;
	s_add_i32 s4, s91, s44
	v_lshl_add_u64 v[162:163], v[162:163], 0, s[24:25]
	s_mov_b32 m0, s4
	ds_read_b128 v[192:195], v170 offset:49152
	ds_read_b128 v[196:199], v170 offset:50176
	ds_read_b128 v[200:203], v170 offset:51200
	ds_read_b128 v[204:207], v170 offset:52224
	ds_read_b128 v[230:233], v170 offset:53248
	ds_read_b128 v[234:237], v170 offset:54272
	ds_read_b128 v[238:241], v170 offset:55296
	ds_read_b128 v[242:245], v170 offset:56320
	global_load_lds_dwordx4 v[162:163], off
	v_lshl_add_u64 v[162:163], v[208:209], 0, s[24:25]
	s_add_i32 m0, s4, 0x2000
	s_add_i32 s4, s81, s44
	global_load_lds_dwordx4 v[162:163], off
	v_lshl_add_u64 v[162:163], v[246:247], 0, s[24:25]
	s_mov_b32 m0, s4
	s_nop 0
	global_load_lds_dwordx4 v[162:163], off
	v_lshl_add_u64 v[162:163], v[248:249], 0, s[24:25]
	s_add_i32 m0, s4, 0x2000
	s_nop 0
	global_load_lds_dwordx4 v[162:163], off
	v_lshl_add_u64 v[162:163], v[216:217], 0, s[24:25]
	s_mov_b32 m0, s53
	s_nop 0
	global_load_lds_dwordx4 v[162:163], off
	v_lshl_add_u64 v[162:163], v[224:225], 0, s[24:25]
	s_mov_b32 m0, s72
	s_nop 0
	global_load_lds_dwordx4 v[162:163], off
	s_waitcnt vmcnt(8)
	s_waitcnt lgkmcnt(0)
	s_barrier
	s_waitcnt lgkmcnt(0)
	v_mfma_f32_16x16x32_bf16 v[68:71], v[136:139], v[192:195], v[68:71]
	v_mfma_f32_16x16x32_bf16 v[68:71], v[140:143], v[196:199], v[68:71]
	v_mfma_f32_16x16x32_bf16 v[52:55], v[136:139], v[200:203], v[52:55]
	v_mfma_f32_16x16x32_bf16 v[52:55], v[140:143], v[204:207], v[52:55]
	v_mfma_f32_16x16x32_bf16 v[36:39], v[136:139], v[230:233], v[36:39]
	v_mfma_f32_16x16x32_bf16 v[36:39], v[140:143], v[234:237], v[36:39]
	v_mfma_f32_16x16x32_bf16 v[20:23], v[136:139], v[238:241], v[20:23]
	v_mfma_f32_16x16x32_bf16 v[20:23], v[140:143], v[242:245], v[20:23]
	v_mfma_f32_16x16x32_bf16 v[16:19], v[144:147], v[238:241], v[16:19]
	v_mfma_f32_16x16x32_bf16 v[16:19], v[148:151], v[242:245], v[16:19]
	v_mfma_f32_16x16x32_bf16 v[32:35], v[144:147], v[230:233], v[32:35]
	v_mfma_f32_16x16x32_bf16 v[32:35], v[148:151], v[234:237], v[32:35]
	v_mfma_f32_16x16x32_bf16 v[48:51], v[144:147], v[200:203], v[48:51]
	v_mfma_f32_16x16x32_bf16 v[48:51], v[148:151], v[204:207], v[48:51]
	v_mfma_f32_16x16x32_bf16 v[64:67], v[144:147], v[192:195], v[64:67]
	v_mfma_f32_16x16x32_bf16 v[64:67], v[148:151], v[196:199], v[64:67]
	v_mfma_f32_16x16x32_bf16 v[60:63], v[174:177], v[192:195], v[60:63]
	v_mfma_f32_16x16x32_bf16 v[60:63], v[178:181], v[196:199], v[60:63]
	v_mfma_f32_16x16x32_bf16 v[44:47], v[174:177], v[200:203], v[44:47]
	v_mfma_f32_16x16x32_bf16 v[44:47], v[178:181], v[204:207], v[44:47]
	v_mfma_f32_16x16x32_bf16 v[28:31], v[174:177], v[230:233], v[28:31]
	v_mfma_f32_16x16x32_bf16 v[28:31], v[178:181], v[234:237], v[28:31]
	v_mfma_f32_16x16x32_bf16 v[12:15], v[174:177], v[238:241], v[12:15]
	v_mfma_f32_16x16x32_bf16 v[12:15], v[178:181], v[242:245], v[12:15]
	v_mfma_f32_16x16x32_bf16 v[8:11], v[184:187], v[238:241], v[8:11]
	v_mfma_f32_16x16x32_bf16 v[8:11], v[188:191], v[242:245], v[8:11]
	v_mfma_f32_16x16x32_bf16 v[24:27], v[184:187], v[230:233], v[24:27]
	v_mfma_f32_16x16x32_bf16 v[24:27], v[188:191], v[234:237], v[24:27]
	v_mfma_f32_16x16x32_bf16 v[40:43], v[184:187], v[200:203], v[40:43]
	v_mfma_f32_16x16x32_bf16 v[40:43], v[188:191], v[204:207], v[40:43]
	v_mfma_f32_16x16x32_bf16 v[56:59], v[184:187], v[192:195], v[56:59]
	v_mfma_f32_16x16x32_bf16 v[56:59], v[188:191], v[196:199], v[56:59]
	s_barrier
	s_add_u32 s0, s0, 0x100
	s_addc_u32 s1, s1, 0
	s_add_u32 s42, s42, 0x100
	s_addc_u32 s43, s43, 0
	s_cmp_ge_u32 s80, s9
	s_mov_b32 s4, s80
	s_cbranch_scc0 .LBB0_501
